# v017 + s_nop padding so every MFMA run of 16+ starts 8-byte aligned
# speedup vs baseline: 1.0000x; 1.0000x over previous
.LBB0_152:
	s_add_i32 s35, s14, 2
	s_add_u32 s15, s12, 0x80
	s_addc_u32 s36, s13, 0
	s_cmp_lg_u32 s34, s14
	s_cselect_b32 s37, s36, 0
	s_cselect_b32 s36, s15, 0
	s_add_u32 s14, s8, s36
	s_addc_u32 s15, s9, s37
	s_add_i32 s38, 0, 0x10000
	s_add_u32 s36, s0, s36
	v_add_u32_e32 v143, s38, v141
	s_addc_u32 s37, s1, s37
	s_add_i32 s39, 0, 0x14000
	ds_read_b128 v[144:147], v143
	ds_read_b128 v[148:151], v143 offset:1024
	ds_read_b128 v[152:155], v143 offset:2048
	ds_read_b128 v[168:171], v143 offset:3072
	v_add_u32_e32 v143, s39, v141
	ds_read_b128 v[172:175], v143
	ds_read_b128 v[176:179], v143 offset:1024
	ds_read_b128 v[180:183], v143 offset:2048
	ds_read_b128 v[184:187], v143 offset:3072
	v_lshl_add_u64 v[156:157], v[136:137], 0, s[12:13]
	s_add_i32 m0, s24, 0xc000
	ds_read_b128 v[188:191], v142
	ds_read_b128 v[192:195], v142 offset:1024
	ds_read_b128 v[196:199], v142 offset:2048
	ds_read_b128 v[200:203], v142 offset:3072
	ds_read_b128 v[204:207], v142 offset:4096
	ds_read_b128 v[216:219], v142 offset:5120
	ds_read_b128 v[220:223], v142 offset:6144
	ds_read_b128 v[224:227], v142 offset:7168
	global_load_lds_dwordx4 v[156:157], off
	v_lshl_add_u64 v[156:157], v[138:139], 0, s[12:13]
	s_add_i32 m0, s24, 0xe000
	s_nop 0
	global_load_lds_dwordx4 v[156:157], off
	s_waitcnt vmcnt(8)
	s_waitcnt lgkmcnt(0)
	s_barrier
	s_nop 0
	s_setprio 1
	s_waitcnt lgkmcnt(0)
	v_mfma_f32_16x16x32_bf16 v[126:129], v[144:147], v[188:191], v[126:129]
	v_mfma_f32_16x16x32_bf16 v[122:125], v[152:155], v[188:191], v[122:125]
	v_mfma_f32_16x16x32_bf16 v[110:113], v[144:147], v[196:199], v[110:113]
	v_mfma_f32_16x16x32_bf16 v[106:109], v[152:155], v[196:199], v[106:109]
	v_mfma_f32_16x16x32_bf16 v[94:97], v[144:147], v[204:207], v[94:97]
	v_mfma_f32_16x16x32_bf16 v[90:93], v[152:155], v[204:207], v[90:93]
	v_mfma_f32_16x16x32_bf16 v[78:81], v[144:147], v[220:223], v[78:81]
	v_mfma_f32_16x16x32_bf16 v[74:77], v[152:155], v[220:223], v[74:77]
	v_mfma_f32_16x16x32_bf16 v[126:129], v[148:151], v[192:195], v[126:129]
	v_mfma_f32_16x16x32_bf16 v[122:125], v[168:171], v[192:195], v[122:125]
	v_mfma_f32_16x16x32_bf16 v[110:113], v[148:151], v[200:203], v[110:113]
	v_mfma_f32_16x16x32_bf16 v[106:109], v[168:171], v[200:203], v[106:109]
	v_mfma_f32_16x16x32_bf16 v[94:97], v[148:151], v[216:219], v[94:97]
	v_mfma_f32_16x16x32_bf16 v[90:93], v[168:171], v[216:219], v[90:93]
	v_mfma_f32_16x16x32_bf16 v[78:81], v[148:151], v[224:227], v[78:81]
	v_mfma_f32_16x16x32_bf16 v[74:77], v[168:171], v[224:227], v[74:77]
	s_setprio 0
	s_setprio 1
	v_mfma_f32_16x16x32_bf16 v[118:121], v[172:175], v[188:191], v[118:121]
	v_mfma_f32_16x16x32_bf16 v[114:117], v[180:183], v[188:191], v[114:117]
	v_mfma_f32_16x16x32_bf16 v[102:105], v[172:175], v[196:199], v[102:105]
	v_mfma_f32_16x16x32_bf16 v[98:101], v[180:183], v[196:199], v[98:101]
	v_mfma_f32_16x16x32_bf16 v[86:89], v[172:175], v[204:207], v[86:89]
	v_mfma_f32_16x16x32_bf16 v[82:85], v[180:183], v[204:207], v[82:85]
	v_mfma_f32_16x16x32_bf16 v[70:73], v[172:175], v[220:223], v[70:73]
	v_mfma_f32_16x16x32_bf16 v[66:69], v[180:183], v[220:223], v[66:69]
	v_mfma_f32_16x16x32_bf16 v[118:121], v[176:179], v[192:195], v[118:121]
	v_mfma_f32_16x16x32_bf16 v[114:117], v[184:187], v[192:195], v[114:117]
	v_mfma_f32_16x16x32_bf16 v[102:105], v[176:179], v[200:203], v[102:105]
	v_mfma_f32_16x16x32_bf16 v[98:101], v[184:187], v[200:203], v[98:101]
	v_mfma_f32_16x16x32_bf16 v[86:89], v[176:179], v[216:219], v[86:89]
	v_mfma_f32_16x16x32_bf16 v[82:85], v[184:187], v[216:219], v[82:85]
	v_mfma_f32_16x16x32_bf16 v[70:73], v[176:179], v[224:227], v[70:73]
	v_mfma_f32_16x16x32_bf16 v[66:69], v[184:187], v[224:227], v[66:69]
	s_setprio 0
	s_barrier
	s_add_i32 s38, s38, s23
	v_lshl_add_u64 v[156:157], s[36:37], 0, v[158:159]
	s_mov_b32 m0, s38
	ds_read_b128 v[188:191], v142 offset:16384
	ds_read_b128 v[192:195], v142 offset:17408
	ds_read_b128 v[196:199], v142 offset:18432
	ds_read_b128 v[200:203], v142 offset:19456
	ds_read_b128 v[204:207], v142 offset:20480
	ds_read_b128 v[216:219], v142 offset:21504
	ds_read_b128 v[220:223], v142 offset:22528
	ds_read_b128 v[224:227], v142 offset:23552
	global_load_lds_dwordx4 v[156:157], off
	s_add_i32 m0, s38, 0x2000
	v_lshl_add_u64 v[228:229], s[36:37], 0, v[134:135]
	s_add_u32 s36, s36, s22
	s_addc_u32 s37, s37, 0
	s_add_i32 s38, s39, s23
	global_load_lds_dwordx4 v[228:229], off
	v_lshl_add_u64 v[230:231], s[36:37], 0, v[158:159]
	s_mov_b32 m0, s38
	v_lshl_add_u64 v[232:233], s[36:37], 0, v[134:135]
	global_load_lds_dwordx4 v[230:231], off
	s_add_i32 m0, s38, 0x2000
	v_lshl_add_u64 v[234:235], s[14:15], 0, v[130:131]
	global_load_lds_dwordx4 v[232:233], off
	s_mov_b32 m0, s24
	v_lshl_add_u64 v[236:237], s[14:15], 0, v[132:133]
	global_load_lds_dwordx4 v[234:235], off
	s_mov_b32 m0, s25
	s_nop 0
	global_load_lds_dwordx4 v[236:237], off
	s_waitcnt vmcnt(8)
	s_waitcnt lgkmcnt(0)
	s_barrier
	s_setprio 1
	s_waitcnt lgkmcnt(0)
	v_mfma_f32_16x16x32_bf16 v[62:65], v[144:147], v[188:191], v[62:65]
	v_mfma_f32_16x16x32_bf16 v[58:61], v[152:155], v[188:191], v[58:61]
	v_mfma_f32_16x16x32_bf16 v[46:49], v[144:147], v[196:199], v[46:49]
	v_mfma_f32_16x16x32_bf16 v[42:45], v[152:155], v[196:199], v[42:45]
	v_mfma_f32_16x16x32_bf16 v[30:33], v[144:147], v[204:207], v[30:33]
	v_mfma_f32_16x16x32_bf16 v[26:29], v[152:155], v[204:207], v[26:29]
	v_mfma_f32_16x16x32_bf16 v[14:17], v[144:147], v[220:223], v[14:17]
	v_mfma_f32_16x16x32_bf16 v[10:13], v[152:155], v[220:223], v[10:13]
	v_mfma_f32_16x16x32_bf16 v[62:65], v[148:151], v[192:195], v[62:65]
	v_mfma_f32_16x16x32_bf16 v[58:61], v[168:171], v[192:195], v[58:61]
	v_mfma_f32_16x16x32_bf16 v[46:49], v[148:151], v[200:203], v[46:49]
	v_mfma_f32_16x16x32_bf16 v[42:45], v[168:171], v[200:203], v[42:45]
	v_mfma_f32_16x16x32_bf16 v[30:33], v[148:151], v[216:219], v[30:33]
	v_mfma_f32_16x16x32_bf16 v[26:29], v[168:171], v[216:219], v[26:29]
	v_mfma_f32_16x16x32_bf16 v[14:17], v[148:151], v[224:227], v[14:17]
	v_mfma_f32_16x16x32_bf16 v[10:13], v[168:171], v[224:227], v[10:13]
	s_setprio 0
	s_setprio 1
	v_mfma_f32_16x16x32_bf16 v[54:57], v[172:175], v[188:191], v[54:57]
	v_mfma_f32_16x16x32_bf16 v[50:53], v[180:183], v[188:191], v[50:53]
	v_mfma_f32_16x16x32_bf16 v[38:41], v[172:175], v[196:199], v[38:41]
	v_mfma_f32_16x16x32_bf16 v[34:37], v[180:183], v[196:199], v[34:37]
	v_mfma_f32_16x16x32_bf16 v[22:25], v[172:175], v[204:207], v[22:25]
	v_mfma_f32_16x16x32_bf16 v[18:21], v[180:183], v[204:207], v[18:21]
	v_mfma_f32_16x16x32_bf16 v[6:9], v[172:175], v[220:223], v[6:9]
	v_mfma_f32_16x16x32_bf16 v[2:5], v[180:183], v[220:223], v[2:5]
	v_mfma_f32_16x16x32_bf16 v[54:57], v[176:179], v[192:195], v[54:57]
	v_mfma_f32_16x16x32_bf16 v[50:53], v[184:187], v[192:195], v[50:53]
	v_mfma_f32_16x16x32_bf16 v[38:41], v[176:179], v[200:203], v[38:41]
	v_mfma_f32_16x16x32_bf16 v[34:37], v[184:187], v[200:203], v[34:37]
	v_mfma_f32_16x16x32_bf16 v[22:25], v[176:179], v[216:219], v[22:25]
	v_mfma_f32_16x16x32_bf16 v[18:21], v[184:187], v[216:219], v[18:21]
	v_mfma_f32_16x16x32_bf16 v[6:9], v[176:179], v[224:227], v[6:9]
	v_mfma_f32_16x16x32_bf16 v[2:5], v[184:187], v[224:227], v[2:5]
	s_setprio 0
	s_barrier
	s_add_i32 s36, 0, 0x18000
	v_add_u32_e32 v143, s36, v141
	s_add_i32 s37, 0, 0x1c000
	ds_read_b128 v[144:147], v143
	ds_read_b128 v[148:151], v143 offset:1024
	ds_read_b128 v[152:155], v143 offset:2048
	ds_read_b128 v[168:171], v143 offset:3072
	v_add_u32_e32 v143, s37, v141
	ds_read_b128 v[172:175], v143
	ds_read_b128 v[176:179], v143 offset:1024
	ds_read_b128 v[180:183], v143 offset:2048
	ds_read_b128 v[184:187], v143 offset:3072
	s_add_u32 s14, s14, s22
	s_addc_u32 s15, s15, 0
	s_mov_b32 m0, s26
	v_lshl_add_u64 v[238:239], s[14:15], 0, v[130:131]
	ds_read_b128 v[188:191], v142 offset:32768
	ds_read_b128 v[192:195], v142 offset:33792
	ds_read_b128 v[196:199], v142 offset:34816
	ds_read_b128 v[200:203], v142 offset:35840
	ds_read_b128 v[204:207], v142 offset:36864
	ds_read_b128 v[216:219], v142 offset:37888
	ds_read_b128 v[220:223], v142 offset:38912
	ds_read_b128 v[224:227], v142 offset:39936
	global_load_lds_dwordx4 v[238:239], off
	v_lshl_add_u64 v[238:239], s[14:15], 0, v[132:133]
	s_mov_b32 m0, s27
	s_nop 0
	global_load_lds_dwordx4 v[238:239], off
	s_waitcnt vmcnt(8)
	s_waitcnt lgkmcnt(0)
	s_barrier
	s_setprio 1
	s_waitcnt lgkmcnt(0)
	v_mfma_f32_16x16x32_bf16 v[126:129], v[144:147], v[188:191], v[126:129]
	v_mfma_f32_16x16x32_bf16 v[122:125], v[152:155], v[188:191], v[122:125]
	v_mfma_f32_16x16x32_bf16 v[110:113], v[144:147], v[196:199], v[110:113]
	v_mfma_f32_16x16x32_bf16 v[106:109], v[152:155], v[196:199], v[106:109]
	v_mfma_f32_16x16x32_bf16 v[94:97], v[144:147], v[204:207], v[94:97]
	v_mfma_f32_16x16x32_bf16 v[90:93], v[152:155], v[204:207], v[90:93]
	v_mfma_f32_16x16x32_bf16 v[78:81], v[144:147], v[220:223], v[78:81]
	v_mfma_f32_16x16x32_bf16 v[74:77], v[152:155], v[220:223], v[74:77]
	v_mfma_f32_16x16x32_bf16 v[126:129], v[148:151], v[192:195], v[126:129]
	v_mfma_f32_16x16x32_bf16 v[122:125], v[168:171], v[192:195], v[122:125]
	v_mfma_f32_16x16x32_bf16 v[110:113], v[148:151], v[200:203], v[110:113]
	v_mfma_f32_16x16x32_bf16 v[106:109], v[168:171], v[200:203], v[106:109]
	v_mfma_f32_16x16x32_bf16 v[94:97], v[148:151], v[216:219], v[94:97]
	v_mfma_f32_16x16x32_bf16 v[90:93], v[168:171], v[216:219], v[90:93]
	v_mfma_f32_16x16x32_bf16 v[78:81], v[148:151], v[224:227], v[78:81]
	v_mfma_f32_16x16x32_bf16 v[74:77], v[168:171], v[224:227], v[74:77]
	s_setprio 0
	s_setprio 1
	v_mfma_f32_16x16x32_bf16 v[118:121], v[172:175], v[188:191], v[118:121]
	v_mfma_f32_16x16x32_bf16 v[114:117], v[180:183], v[188:191], v[114:117]
	v_mfma_f32_16x16x32_bf16 v[102:105], v[172:175], v[196:199], v[102:105]
	v_mfma_f32_16x16x32_bf16 v[98:101], v[180:183], v[196:199], v[98:101]
	v_mfma_f32_16x16x32_bf16 v[86:89], v[172:175], v[204:207], v[86:89]
	v_mfma_f32_16x16x32_bf16 v[82:85], v[180:183], v[204:207], v[82:85]
	v_mfma_f32_16x16x32_bf16 v[70:73], v[172:175], v[220:223], v[70:73]
	v_mfma_f32_16x16x32_bf16 v[66:69], v[180:183], v[220:223], v[66:69]
	v_mfma_f32_16x16x32_bf16 v[118:121], v[176:179], v[192:195], v[118:121]
	v_mfma_f32_16x16x32_bf16 v[114:117], v[184:187], v[192:195], v[114:117]
	v_mfma_f32_16x16x32_bf16 v[102:105], v[176:179], v[200:203], v[102:105]
	v_mfma_f32_16x16x32_bf16 v[98:101], v[184:187], v[200:203], v[98:101]
	v_mfma_f32_16x16x32_bf16 v[86:89], v[176:179], v[216:219], v[86:89]
	v_mfma_f32_16x16x32_bf16 v[82:85], v[184:187], v[216:219], v[82:85]
	v_mfma_f32_16x16x32_bf16 v[70:73], v[176:179], v[224:227], v[70:73]
	v_mfma_f32_16x16x32_bf16 v[66:69], v[184:187], v[224:227], v[66:69]
	s_setprio 0
	s_barrier
	s_add_i32 s14, s36, s23
	v_lshl_add_u64 v[156:157], v[156:157], 0, s[56:57]
	s_mov_b32 m0, s14
	ds_read_b128 v[188:191], v142 offset:49152
	ds_read_b128 v[192:195], v142 offset:50176
	ds_read_b128 v[196:199], v142 offset:51200
	ds_read_b128 v[200:203], v142 offset:52224
	ds_read_b128 v[204:207], v142 offset:53248
	ds_read_b128 v[216:219], v142 offset:54272
	ds_read_b128 v[220:223], v142 offset:55296
	ds_read_b128 v[224:227], v142 offset:56320
	global_load_lds_dwordx4 v[156:157], off
	v_lshl_add_u64 v[156:157], v[228:229], 0, s[56:57]
	s_add_i32 m0, s14, 0x2000
	s_add_i32 s14, s37, s23
	global_load_lds_dwordx4 v[156:157], off
	v_lshl_add_u64 v[156:157], v[230:231], 0, s[56:57]
	s_mov_b32 m0, s14
	s_nop 0
	global_load_lds_dwordx4 v[156:157], off
	v_lshl_add_u64 v[156:157], v[232:233], 0, s[56:57]
	s_add_i32 m0, s14, 0x2000
	s_nop 0
	global_load_lds_dwordx4 v[156:157], off
	v_lshl_add_u64 v[156:157], v[234:235], 0, s[56:57]
	s_mov_b32 m0, s30
	s_nop 0
	global_load_lds_dwordx4 v[156:157], off
	v_lshl_add_u64 v[156:157], v[236:237], 0, s[56:57]
	s_mov_b32 m0, s31
	s_nop 0
	global_load_lds_dwordx4 v[156:157], off
	s_waitcnt vmcnt(8)
	s_waitcnt lgkmcnt(0)
	s_barrier
	s_nop 0
	s_setprio 1
	s_waitcnt lgkmcnt(0)
	v_mfma_f32_16x16x32_bf16 v[62:65], v[144:147], v[188:191], v[62:65]
	v_mfma_f32_16x16x32_bf16 v[58:61], v[152:155], v[188:191], v[58:61]
	v_mfma_f32_16x16x32_bf16 v[46:49], v[144:147], v[196:199], v[46:49]
	v_mfma_f32_16x16x32_bf16 v[42:45], v[152:155], v[196:199], v[42:45]
	v_mfma_f32_16x16x32_bf16 v[30:33], v[144:147], v[204:207], v[30:33]
	v_mfma_f32_16x16x32_bf16 v[26:29], v[152:155], v[204:207], v[26:29]
	v_mfma_f32_16x16x32_bf16 v[14:17], v[144:147], v[220:223], v[14:17]
	v_mfma_f32_16x16x32_bf16 v[10:13], v[152:155], v[220:223], v[10:13]
	v_mfma_f32_16x16x32_bf16 v[62:65], v[148:151], v[192:195], v[62:65]
	v_mfma_f32_16x16x32_bf16 v[58:61], v[168:171], v[192:195], v[58:61]
	v_mfma_f32_16x16x32_bf16 v[46:49], v[148:151], v[200:203], v[46:49]
	v_mfma_f32_16x16x32_bf16 v[42:45], v[168:171], v[200:203], v[42:45]
	v_mfma_f32_16x16x32_bf16 v[30:33], v[148:151], v[216:219], v[30:33]
	v_mfma_f32_16x16x32_bf16 v[26:29], v[168:171], v[216:219], v[26:29]
	v_mfma_f32_16x16x32_bf16 v[14:17], v[148:151], v[224:227], v[14:17]
	v_mfma_f32_16x16x32_bf16 v[10:13], v[168:171], v[224:227], v[10:13]
	s_setprio 0
	s_setprio 1
	v_mfma_f32_16x16x32_bf16 v[54:57], v[172:175], v[188:191], v[54:57]
	v_mfma_f32_16x16x32_bf16 v[50:53], v[180:183], v[188:191], v[50:53]
	v_mfma_f32_16x16x32_bf16 v[38:41], v[172:175], v[196:199], v[38:41]
	v_mfma_f32_16x16x32_bf16 v[34:37], v[180:183], v[196:199], v[34:37]
	v_mfma_f32_16x16x32_bf16 v[22:25], v[172:175], v[204:207], v[22:25]
	v_mfma_f32_16x16x32_bf16 v[18:21], v[180:183], v[204:207], v[18:21]
	v_mfma_f32_16x16x32_bf16 v[6:9], v[172:175], v[220:223], v[6:9]
	v_mfma_f32_16x16x32_bf16 v[2:5], v[180:183], v[220:223], v[2:5]
	v_mfma_f32_16x16x32_bf16 v[54:57], v[176:179], v[192:195], v[54:57]
	v_mfma_f32_16x16x32_bf16 v[50:53], v[184:187], v[192:195], v[50:53]
	v_mfma_f32_16x16x32_bf16 v[38:41], v[176:179], v[200:203], v[38:41]
	v_mfma_f32_16x16x32_bf16 v[34:37], v[184:187], v[200:203], v[34:37]
	v_mfma_f32_16x16x32_bf16 v[22:25], v[176:179], v[216:219], v[22:25]
	v_mfma_f32_16x16x32_bf16 v[18:21], v[184:187], v[216:219], v[18:21]
	v_mfma_f32_16x16x32_bf16 v[6:9], v[176:179], v[224:227], v[6:9]
	v_mfma_f32_16x16x32_bf16 v[2:5], v[184:187], v[224:227], v[2:5]
	s_setprio 0
	s_barrier
	s_add_u32 s12, s12, 0x100
	s_addc_u32 s13, s13, 0
	s_cmp_ge_u32 s35, s29
	s_mov_b32 s14, s35
	s_cbranch_scc0 .LBB0_152
	s_cmpk_lt_u32 s10, 0x100
	s_cbranch_scc0 .LBB0_155
	s_barrier

.LBB0_179:
	s_add_u32 s14, s0, 0xfff80080
	s_addc_u32 s15, s1, -1
	s_add_i32 s31, 0, 0x10000
	s_cmp_eq_u32 s30, 28
	s_cselect_b32 s37, s9, s15
	s_cselect_b32 s36, s26, s14
	v_add_u32_e32 v144, s31, v146
	s_cselect_b32 s15, s13, s29
	s_cselect_b32 s14, s27, s28
	s_add_i32 s44, 0, 0x14000
	ds_read_b128 v[140:143], v144
	ds_read_b128 v[150:153], v144 offset:1024
	ds_read_b128 v[154:157], v144 offset:2048
	ds_read_b128 v[168:171], v144 offset:3072
	v_add_u32_e32 v144, s44, v146
	ds_read_b128 v[172:175], v144
	ds_read_b128 v[176:179], v144 offset:1024
	ds_read_b128 v[180:183], v144 offset:2048
	ds_read_b128 v[184:187], v144 offset:3072
	v_lshl_add_u64 v[144:145], s[0:1], 0, v[136:137]
	s_add_i32 m0, s73, 0xc000
	ds_read_b128 v[188:191], v148
	ds_read_b128 v[192:195], v148 offset:1024
	ds_read_b128 v[196:199], v148 offset:2048
	ds_read_b128 v[200:203], v148 offset:3072
	ds_read_b128 v[204:207], v148 offset:4096
	ds_read_b128 v[216:219], v148 offset:5120
	ds_read_b128 v[220:223], v148 offset:6144
	ds_read_b128 v[224:227], v148 offset:7168
	global_load_lds_dwordx4 v[144:145], off
	v_lshl_add_u64 v[144:145], s[0:1], 0, v[138:139]
	s_add_i32 m0, s73, 0xe000
	s_nop 0
	global_load_lds_dwordx4 v[144:145], off
	s_waitcnt vmcnt(8)
	s_waitcnt lgkmcnt(0)
	s_barrier
	s_setprio 1
	s_waitcnt lgkmcnt(0)
	v_mfma_f32_16x16x32_bf16 v[126:129], v[140:143], v[188:191], v[126:129]
	v_mfma_f32_16x16x32_bf16 v[118:121], v[154:157], v[188:191], v[118:121]
	v_mfma_f32_16x16x32_bf16 v[106:109], v[140:143], v[196:199], v[106:109]
	v_mfma_f32_16x16x32_bf16 v[98:101], v[154:157], v[196:199], v[98:101]
	v_mfma_f32_16x16x32_bf16 v[90:93], v[140:143], v[204:207], v[90:93]
	v_mfma_f32_16x16x32_bf16 v[82:85], v[154:157], v[204:207], v[82:85]
	v_mfma_f32_16x16x32_bf16 v[74:77], v[140:143], v[220:223], v[74:77]
	v_mfma_f32_16x16x32_bf16 v[66:69], v[154:157], v[220:223], v[66:69]
	v_mfma_f32_16x16x32_bf16 v[126:129], v[150:153], v[192:195], v[126:129]
	v_mfma_f32_16x16x32_bf16 v[118:121], v[168:171], v[192:195], v[118:121]
	v_mfma_f32_16x16x32_bf16 v[106:109], v[150:153], v[200:203], v[106:109]
	v_mfma_f32_16x16x32_bf16 v[98:101], v[168:171], v[200:203], v[98:101]
	v_mfma_f32_16x16x32_bf16 v[90:93], v[150:153], v[216:219], v[90:93]
	v_mfma_f32_16x16x32_bf16 v[82:85], v[168:171], v[216:219], v[82:85]
	v_mfma_f32_16x16x32_bf16 v[74:77], v[150:153], v[224:227], v[74:77]
	v_mfma_f32_16x16x32_bf16 v[66:69], v[168:171], v[224:227], v[66:69]
	s_setprio 0
	s_setprio 1
	v_mfma_f32_16x16x32_bf16 v[122:125], v[172:175], v[188:191], v[122:125]
	v_mfma_f32_16x16x32_bf16 v[114:117], v[180:183], v[188:191], v[114:117]
	v_mfma_f32_16x16x32_bf16 v[110:113], v[172:175], v[196:199], v[110:113]
	v_mfma_f32_16x16x32_bf16 v[102:105], v[180:183], v[196:199], v[102:105]
	v_mfma_f32_16x16x32_bf16 v[94:97], v[172:175], v[204:207], v[94:97]
	v_mfma_f32_16x16x32_bf16 v[86:89], v[180:183], v[204:207], v[86:89]
	v_mfma_f32_16x16x32_bf16 v[78:81], v[172:175], v[220:223], v[78:81]
	v_mfma_f32_16x16x32_bf16 v[70:73], v[180:183], v[220:223], v[70:73]
	v_mfma_f32_16x16x32_bf16 v[122:125], v[176:179], v[192:195], v[122:125]
	v_mfma_f32_16x16x32_bf16 v[114:117], v[184:187], v[192:195], v[114:117]
	v_mfma_f32_16x16x32_bf16 v[110:113], v[176:179], v[200:203], v[110:113]
	v_mfma_f32_16x16x32_bf16 v[102:105], v[184:187], v[200:203], v[102:105]
	v_mfma_f32_16x16x32_bf16 v[94:97], v[176:179], v[216:219], v[94:97]
	v_mfma_f32_16x16x32_bf16 v[86:89], v[184:187], v[216:219], v[86:89]
	v_mfma_f32_16x16x32_bf16 v[78:81], v[176:179], v[224:227], v[78:81]
	v_mfma_f32_16x16x32_bf16 v[70:73], v[184:187], v[224:227], v[70:73]
	s_setprio 0
	s_barrier
	s_add_i32 s31, s31, s72
	v_lshl_add_u64 v[144:145], s[14:15], 0, v[158:159]
	s_mov_b32 m0, s31
	ds_read_b128 v[188:191], v148 offset:16384
	ds_read_b128 v[192:195], v148 offset:17408
	ds_read_b128 v[196:199], v148 offset:18432
	ds_read_b128 v[200:203], v148 offset:19456
	ds_read_b128 v[204:207], v148 offset:20480
	ds_read_b128 v[216:219], v148 offset:21504
	ds_read_b128 v[220:223], v148 offset:22528
	ds_read_b128 v[224:227], v148 offset:23552
	global_load_lds_dwordx4 v[144:145], off
	s_add_i32 m0, s31, 0x2000
	s_add_u32 s34, s14, 0x80000
	v_lshl_add_u64 v[228:229], s[14:15], 0, v[134:135]
	s_addc_u32 s35, s15, 0
	s_add_i32 s31, s44, s72
	global_load_lds_dwordx4 v[228:229], off
	v_lshl_add_u64 v[230:231], s[34:35], 0, v[158:159]
	s_mov_b32 m0, s31
	v_lshl_add_u64 v[232:233], s[36:37], 0, v[132:133]
	global_load_lds_dwordx4 v[230:231], off
	v_lshl_add_u64 v[230:231], s[34:35], 0, v[134:135]
	s_add_i32 m0, s31, 0x2000
	s_nop 0
	global_load_lds_dwordx4 v[230:231], off
	v_lshl_add_u64 v[230:231], s[36:37], 0, v[130:131]
	s_mov_b32 m0, s73
	s_nop 0
	global_load_lds_dwordx4 v[230:231], off
	s_mov_b32 m0, s74
	s_nop 0
	global_load_lds_dwordx4 v[232:233], off
	s_waitcnt vmcnt(8)
	s_waitcnt lgkmcnt(0)
	s_barrier
	s_nop 0
	s_setprio 1
	s_waitcnt lgkmcnt(0)
	v_mfma_f32_16x16x32_bf16 v[58:61], v[140:143], v[188:191], v[58:61]
	v_mfma_f32_16x16x32_bf16 v[50:53], v[154:157], v[188:191], v[50:53]
	v_mfma_f32_16x16x32_bf16 v[42:45], v[140:143], v[196:199], v[42:45]
	v_mfma_f32_16x16x32_bf16 v[34:37], v[154:157], v[196:199], v[34:37]
	v_mfma_f32_16x16x32_bf16 v[26:29], v[140:143], v[204:207], v[26:29]
	v_mfma_f32_16x16x32_bf16 v[18:21], v[154:157], v[204:207], v[18:21]
	v_mfma_f32_16x16x32_bf16 v[10:13], v[140:143], v[220:223], v[10:13]
	v_mfma_f32_16x16x32_bf16 v[2:5], v[154:157], v[220:223], v[2:5]
	v_mfma_f32_16x16x32_bf16 v[58:61], v[150:153], v[192:195], v[58:61]
	v_mfma_f32_16x16x32_bf16 v[50:53], v[168:171], v[192:195], v[50:53]
	v_mfma_f32_16x16x32_bf16 v[42:45], v[150:153], v[200:203], v[42:45]
	v_mfma_f32_16x16x32_bf16 v[34:37], v[168:171], v[200:203], v[34:37]
	v_mfma_f32_16x16x32_bf16 v[26:29], v[150:153], v[216:219], v[26:29]
	v_mfma_f32_16x16x32_bf16 v[18:21], v[168:171], v[216:219], v[18:21]
	v_mfma_f32_16x16x32_bf16 v[10:13], v[150:153], v[224:227], v[10:13]
	v_mfma_f32_16x16x32_bf16 v[2:5], v[168:171], v[224:227], v[2:5]
	s_setprio 0
	s_setprio 1
	v_mfma_f32_16x16x32_bf16 v[62:65], v[172:175], v[188:191], v[62:65]
	v_mfma_f32_16x16x32_bf16 v[54:57], v[180:183], v[188:191], v[54:57]
	v_mfma_f32_16x16x32_bf16 v[46:49], v[172:175], v[196:199], v[46:49]
	v_mfma_f32_16x16x32_bf16 v[38:41], v[180:183], v[196:199], v[38:41]
	v_mfma_f32_16x16x32_bf16 v[30:33], v[172:175], v[204:207], v[30:33]
	v_mfma_f32_16x16x32_bf16 v[22:25], v[180:183], v[204:207], v[22:25]
	v_mfma_f32_16x16x32_bf16 v[14:17], v[172:175], v[220:223], v[14:17]
	v_mfma_f32_16x16x32_bf16 v[6:9], v[180:183], v[220:223], v[6:9]
	v_mfma_f32_16x16x32_bf16 v[62:65], v[176:179], v[192:195], v[62:65]
	v_mfma_f32_16x16x32_bf16 v[54:57], v[184:187], v[192:195], v[54:57]
	v_mfma_f32_16x16x32_bf16 v[46:49], v[176:179], v[200:203], v[46:49]
	v_mfma_f32_16x16x32_bf16 v[38:41], v[184:187], v[200:203], v[38:41]
	v_mfma_f32_16x16x32_bf16 v[30:33], v[176:179], v[216:219], v[30:33]
	v_mfma_f32_16x16x32_bf16 v[22:25], v[184:187], v[216:219], v[22:25]
	v_mfma_f32_16x16x32_bf16 v[14:17], v[176:179], v[224:227], v[14:17]
	v_mfma_f32_16x16x32_bf16 v[6:9], v[184:187], v[224:227], v[6:9]
	s_setprio 0
	s_barrier
	s_add_i32 s31, 0, 0x18000
	v_add_u32_e32 v149, s31, v146
	s_add_i32 s44, 0, 0x1c000
	ds_read_b128 v[140:143], v149
	ds_read_b128 v[150:153], v149 offset:1024
	ds_read_b128 v[154:157], v149 offset:2048
	ds_read_b128 v[168:171], v149 offset:3072
	v_add_u32_e32 v149, s44, v146
	ds_read_b128 v[172:175], v149
	ds_read_b128 v[176:179], v149 offset:1024
	ds_read_b128 v[180:183], v149 offset:2048
	ds_read_b128 v[184:187], v149 offset:3072
	s_add_u32 s34, s36, 0x80000
	s_addc_u32 s35, s37, 0
	s_mov_b32 m0, s75
	v_lshl_add_u64 v[234:235], s[34:35], 0, v[130:131]
	ds_read_b128 v[188:191], v148 offset:32768
	ds_read_b128 v[192:195], v148 offset:33792
	ds_read_b128 v[196:199], v148 offset:34816
	ds_read_b128 v[200:203], v148 offset:35840
	ds_read_b128 v[204:207], v148 offset:36864
	ds_read_b128 v[216:219], v148 offset:37888
	ds_read_b128 v[220:223], v148 offset:38912
	ds_read_b128 v[224:227], v148 offset:39936
	global_load_lds_dwordx4 v[234:235], off
	v_lshl_add_u64 v[234:235], s[34:35], 0, v[132:133]
	s_mov_b32 m0, s92
	s_nop 0
	global_load_lds_dwordx4 v[234:235], off
	s_waitcnt vmcnt(8)
	s_waitcnt lgkmcnt(0)
	s_barrier
	s_nop 0
	s_setprio 1
	s_waitcnt lgkmcnt(0)
	v_mfma_f32_16x16x32_bf16 v[126:129], v[140:143], v[188:191], v[126:129]
	v_mfma_f32_16x16x32_bf16 v[118:121], v[154:157], v[188:191], v[118:121]
	v_mfma_f32_16x16x32_bf16 v[106:109], v[140:143], v[196:199], v[106:109]
	v_mfma_f32_16x16x32_bf16 v[98:101], v[154:157], v[196:199], v[98:101]
	v_mfma_f32_16x16x32_bf16 v[90:93], v[140:143], v[204:207], v[90:93]
	v_mfma_f32_16x16x32_bf16 v[82:85], v[154:157], v[204:207], v[82:85]
	v_mfma_f32_16x16x32_bf16 v[74:77], v[140:143], v[220:223], v[74:77]
	v_mfma_f32_16x16x32_bf16 v[66:69], v[154:157], v[220:223], v[66:69]
	v_mfma_f32_16x16x32_bf16 v[126:129], v[150:153], v[192:195], v[126:129]
	v_mfma_f32_16x16x32_bf16 v[118:121], v[168:171], v[192:195], v[118:121]
	v_mfma_f32_16x16x32_bf16 v[106:109], v[150:153], v[200:203], v[106:109]
	v_mfma_f32_16x16x32_bf16 v[98:101], v[168:171], v[200:203], v[98:101]
	v_mfma_f32_16x16x32_bf16 v[90:93], v[150:153], v[216:219], v[90:93]
	v_mfma_f32_16x16x32_bf16 v[82:85], v[168:171], v[216:219], v[82:85]
	v_mfma_f32_16x16x32_bf16 v[74:77], v[150:153], v[224:227], v[74:77]
	v_mfma_f32_16x16x32_bf16 v[66:69], v[168:171], v[224:227], v[66:69]
	s_setprio 0
	s_setprio 1
	v_mfma_f32_16x16x32_bf16 v[122:125], v[172:175], v[188:191], v[122:125]
	v_mfma_f32_16x16x32_bf16 v[114:117], v[180:183], v[188:191], v[114:117]
	v_mfma_f32_16x16x32_bf16 v[110:113], v[172:175], v[196:199], v[110:113]
	v_mfma_f32_16x16x32_bf16 v[102:105], v[180:183], v[196:199], v[102:105]
	v_mfma_f32_16x16x32_bf16 v[94:97], v[172:175], v[204:207], v[94:97]
	v_mfma_f32_16x16x32_bf16 v[86:89], v[180:183], v[204:207], v[86:89]
	v_mfma_f32_16x16x32_bf16 v[78:81], v[172:175], v[220:223], v[78:81]
	v_mfma_f32_16x16x32_bf16 v[70:73], v[180:183], v[220:223], v[70:73]
	v_mfma_f32_16x16x32_bf16 v[122:125], v[176:179], v[192:195], v[122:125]
	v_mfma_f32_16x16x32_bf16 v[114:117], v[184:187], v[192:195], v[114:117]
	v_mfma_f32_16x16x32_bf16 v[110:113], v[176:179], v[200:203], v[110:113]
	v_mfma_f32_16x16x32_bf16 v[102:105], v[184:187], v[200:203], v[102:105]
	v_mfma_f32_16x16x32_bf16 v[94:97], v[176:179], v[216:219], v[94:97]
	v_mfma_f32_16x16x32_bf16 v[86:89], v[184:187], v[216:219], v[86:89]
	v_mfma_f32_16x16x32_bf16 v[78:81], v[176:179], v[224:227], v[78:81]
	v_mfma_f32_16x16x32_bf16 v[70:73], v[184:187], v[224:227], v[70:73]
	s_setprio 0
	s_barrier
	s_add_i32 s31, s31, s72
	v_lshl_add_u64 v[144:145], v[144:145], 0, s[56:57]
	s_mov_b32 m0, s31
	ds_read_b128 v[188:191], v148 offset:49152
	ds_read_b128 v[192:195], v148 offset:50176
	ds_read_b128 v[196:199], v148 offset:51200
	ds_read_b128 v[200:203], v148 offset:52224
	ds_read_b128 v[204:207], v148 offset:53248
	ds_read_b128 v[216:219], v148 offset:54272
	ds_read_b128 v[220:223], v148 offset:55296
	ds_read_b128 v[224:227], v148 offset:56320
	global_load_lds_dwordx4 v[144:145], off
	s_add_i32 m0, s31, 0x2000
	s_add_u32 s14, s14, 0x80080
	v_lshl_add_u64 v[144:145], v[228:229], 0, s[56:57]
	s_addc_u32 s15, s15, 0
	s_add_i32 s31, s44, s72
	global_load_lds_dwordx4 v[144:145], off
	v_lshl_add_u64 v[144:145], s[14:15], 0, v[158:159]
	s_mov_b32 m0, s31
	s_nop 0
	global_load_lds_dwordx4 v[144:145], off
	v_lshl_add_u64 v[144:145], s[14:15], 0, v[134:135]
	s_add_i32 m0, s31, 0x2000
	s_nop 0
	global_load_lds_dwordx4 v[144:145], off
	v_lshl_add_u64 v[144:145], v[230:231], 0, s[56:57]
	s_mov_b32 m0, s93
	s_nop 0
	global_load_lds_dwordx4 v[144:145], off
	v_lshl_add_u64 v[144:145], v[232:233], 0, s[56:57]
	s_mov_b32 m0, s97
	s_nop 0
	global_load_lds_dwordx4 v[144:145], off
	s_waitcnt vmcnt(8)
	s_waitcnt lgkmcnt(0)
	s_barrier
	s_setprio 1
	s_waitcnt lgkmcnt(0)
	v_mfma_f32_16x16x32_bf16 v[58:61], v[140:143], v[188:191], v[58:61]
	v_mfma_f32_16x16x32_bf16 v[50:53], v[154:157], v[188:191], v[50:53]
	v_mfma_f32_16x16x32_bf16 v[42:45], v[140:143], v[196:199], v[42:45]
	v_mfma_f32_16x16x32_bf16 v[34:37], v[154:157], v[196:199], v[34:37]
	v_mfma_f32_16x16x32_bf16 v[26:29], v[140:143], v[204:207], v[26:29]
	v_mfma_f32_16x16x32_bf16 v[18:21], v[154:157], v[204:207], v[18:21]
	v_mfma_f32_16x16x32_bf16 v[10:13], v[140:143], v[220:223], v[10:13]
	v_mfma_f32_16x16x32_bf16 v[2:5], v[154:157], v[220:223], v[2:5]
	v_mfma_f32_16x16x32_bf16 v[58:61], v[150:153], v[192:195], v[58:61]
	v_mfma_f32_16x16x32_bf16 v[50:53], v[168:171], v[192:195], v[50:53]
	v_mfma_f32_16x16x32_bf16 v[42:45], v[150:153], v[200:203], v[42:45]
	v_mfma_f32_16x16x32_bf16 v[34:37], v[168:171], v[200:203], v[34:37]
	v_mfma_f32_16x16x32_bf16 v[26:29], v[150:153], v[216:219], v[26:29]
	v_mfma_f32_16x16x32_bf16 v[18:21], v[168:171], v[216:219], v[18:21]
	v_mfma_f32_16x16x32_bf16 v[10:13], v[150:153], v[224:227], v[10:13]
	v_mfma_f32_16x16x32_bf16 v[2:5], v[168:171], v[224:227], v[2:5]
	s_setprio 0
	s_setprio 1
	v_mfma_f32_16x16x32_bf16 v[62:65], v[172:175], v[188:191], v[62:65]
	v_mfma_f32_16x16x32_bf16 v[54:57], v[180:183], v[188:191], v[54:57]
	v_mfma_f32_16x16x32_bf16 v[46:49], v[172:175], v[196:199], v[46:49]
	v_mfma_f32_16x16x32_bf16 v[38:41], v[180:183], v[196:199], v[38:41]
	v_mfma_f32_16x16x32_bf16 v[30:33], v[172:175], v[204:207], v[30:33]
	v_mfma_f32_16x16x32_bf16 v[22:25], v[180:183], v[204:207], v[22:25]
	v_mfma_f32_16x16x32_bf16 v[14:17], v[172:175], v[220:223], v[14:17]
	v_mfma_f32_16x16x32_bf16 v[6:9], v[180:183], v[220:223], v[6:9]
	v_mfma_f32_16x16x32_bf16 v[62:65], v[176:179], v[192:195], v[62:65]
	v_mfma_f32_16x16x32_bf16 v[54:57], v[184:187], v[192:195], v[54:57]
	v_mfma_f32_16x16x32_bf16 v[46:49], v[176:179], v[200:203], v[46:49]
	v_mfma_f32_16x16x32_bf16 v[38:41], v[184:187], v[200:203], v[38:41]
	v_mfma_f32_16x16x32_bf16 v[30:33], v[176:179], v[216:219], v[30:33]
	v_mfma_f32_16x16x32_bf16 v[22:25], v[184:187], v[216:219], v[22:25]
	v_mfma_f32_16x16x32_bf16 v[14:17], v[176:179], v[224:227], v[14:17]
	v_mfma_f32_16x16x32_bf16 v[6:9], v[184:187], v[224:227], v[6:9]
	s_setprio 0
	s_barrier
	s_add_i32 s30, s30, 2
	s_add_u32 s0, s0, 0x100
	s_addc_u32 s1, s1, 0
	s_add_u32 s28, s28, 0x100
	s_addc_u32 s29, s29, 0
	s_cmp_gt_u32 s30, 29
	s_cbranch_scc0 .LBB0_179
	s_and_b64 vcc, exec, s[66:67]
	s_cbranch_vccz .LBB0_182
	s_barrier

.Lsp_LBB0269_plup:
	s_or_b32 s54, s35, 1
	s_lshl_b64 s[16:17], s[54:55], 7
	s_add_i32 s54, s35, 2
	s_lshl_b64 s[44:45], s[54:55], 7
	s_add_u32 s46, s66, s44
	s_addc_u32 s47, s67, s45
	s_and_b64 vcc, s[14:15], exec
	s_cselect_b32 vcc_hi, s29, s47
	s_cselect_b32 vcc_lo, s65, s46
	s_add_u32 s44, s70, s44
	s_addc_u32 s45, s71, s45
	s_and_b64 s[14:15], s[14:15], exec
	s_cselect_b32 s15, s51, s45
	s_cselect_b32 s14, s30, s44
	s_add_i32 s44, 0, 0x10000
	v_add_u32_e32 v143, s44, v140
	s_add_i32 s45, 0, 0x14000
	ds_read_b128 v[136:139], v143
	ds_read_b128 v[144:147], v143 offset:1024
	ds_read_b128 v[148:151], v143 offset:2048
	ds_read_b128 v[152:155], v143 offset:3072
	v_add_u32_e32 v143, s45, v140
	ds_read_b128 v[168:171], v143
	ds_read_b128 v[172:175], v143 offset:1024
	ds_read_b128 v[176:179], v143 offset:2048
	ds_read_b128 v[180:183], v143 offset:3072
	s_add_u32 s16, s31, s16
	s_addc_u32 s17, s34, s17
	v_lshl_add_u64 v[156:157], s[16:17], 0, v[130:131]
	s_add_i32 m0, s73, 0xc000
	ds_read_b128 v[184:187], v142
	ds_read_b128 v[188:191], v142 offset:1024
	ds_read_b128 v[192:195], v142 offset:2048
	ds_read_b128 v[196:199], v142 offset:3072
	ds_read_b128 v[200:203], v142 offset:4096
	ds_read_b128 v[204:207], v142 offset:5120
	ds_read_b128 v[216:219], v142 offset:6144
	ds_read_b128 v[220:223], v142 offset:7168
	global_load_lds_dwordx4 v[156:157], off
	v_lshl_add_u64 v[156:157], s[16:17], 0, v[132:133]
	s_add_i32 m0, s73, 0xe000
	s_nop 0
	global_load_lds_dwordx4 v[156:157], off
	s_waitcnt vmcnt(8)
	s_waitcnt lgkmcnt(0)
	s_barrier
	s_waitcnt lgkmcnt(0)
	v_mfma_f32_16x16x32_bf16 v[122:125], v[136:139], v[184:187], 0
	v_mfma_f32_16x16x32_bf16 v[122:125], v[144:147], v[188:191], v[122:125]
	v_mfma_f32_16x16x32_bf16 v[114:117], v[148:151], v[184:187], 0
	v_mfma_f32_16x16x32_bf16 v[114:117], v[152:155], v[188:191], v[114:117]
	v_mfma_f32_16x16x32_bf16 v[106:109], v[136:139], v[192:195], 0
	v_mfma_f32_16x16x32_bf16 v[106:109], v[144:147], v[196:199], v[106:109]
	v_mfma_f32_16x16x32_bf16 v[102:105], v[148:151], v[192:195], 0
	v_mfma_f32_16x16x32_bf16 v[102:105], v[152:155], v[196:199], v[102:105]
	v_mfma_f32_16x16x32_bf16 v[90:93], v[136:139], v[200:203], 0
	v_mfma_f32_16x16x32_bf16 v[90:93], v[144:147], v[204:207], v[90:93]
	v_mfma_f32_16x16x32_bf16 v[86:89], v[148:151], v[200:203], 0
	v_mfma_f32_16x16x32_bf16 v[86:89], v[152:155], v[204:207], v[86:89]
	v_mfma_f32_16x16x32_bf16 v[74:77], v[136:139], v[216:219], 0
	v_mfma_f32_16x16x32_bf16 v[74:77], v[144:147], v[220:223], v[74:77]
	v_mfma_f32_16x16x32_bf16 v[70:73], v[148:151], v[216:219], 0
	v_mfma_f32_16x16x32_bf16 v[70:73], v[152:155], v[220:223], v[70:73]
	v_mfma_f32_16x16x32_bf16 v[126:129], v[168:171], v[184:187], 0
	v_mfma_f32_16x16x32_bf16 v[126:129], v[172:175], v[188:191], v[126:129]
	v_mfma_f32_16x16x32_bf16 v[118:121], v[176:179], v[184:187], 0
	v_mfma_f32_16x16x32_bf16 v[118:121], v[180:183], v[188:191], v[118:121]
	v_mfma_f32_16x16x32_bf16 v[110:113], v[168:171], v[192:195], 0
	v_mfma_f32_16x16x32_bf16 v[110:113], v[172:175], v[196:199], v[110:113]
	v_mfma_f32_16x16x32_bf16 v[98:101], v[176:179], v[192:195], 0
	v_mfma_f32_16x16x32_bf16 v[98:101], v[180:183], v[196:199], v[98:101]
	v_mfma_f32_16x16x32_bf16 v[94:97], v[168:171], v[200:203], 0
	v_mfma_f32_16x16x32_bf16 v[94:97], v[172:175], v[204:207], v[94:97]
	v_mfma_f32_16x16x32_bf16 v[82:85], v[176:179], v[200:203], 0
	v_mfma_f32_16x16x32_bf16 v[82:85], v[180:183], v[204:207], v[82:85]
	v_mfma_f32_16x16x32_bf16 v[78:81], v[168:171], v[216:219], 0
	v_mfma_f32_16x16x32_bf16 v[78:81], v[172:175], v[220:223], v[78:81]
	v_mfma_f32_16x16x32_bf16 v[66:69], v[176:179], v[216:219], 0
	v_mfma_f32_16x16x32_bf16 v[66:69], v[180:183], v[220:223], v[66:69]
	s_barrier
	s_add_i32 s16, s44, s61
	v_lshl_add_u64 v[156:157], s[14:15], 0, v[158:159]
	s_mov_b32 m0, s16
	ds_read_b128 v[184:187], v142 offset:16384
	ds_read_b128 v[188:191], v142 offset:17408
	ds_read_b128 v[192:195], v142 offset:18432
	ds_read_b128 v[196:199], v142 offset:19456
	ds_read_b128 v[200:203], v142 offset:20480
	ds_read_b128 v[204:207], v142 offset:21504
	ds_read_b128 v[216:219], v142 offset:22528
	ds_read_b128 v[220:223], v142 offset:23552
	global_load_lds_dwordx4 v[156:157], off
	s_add_i32 m0, s16, 0x2000
	s_add_u32 s16, s14, 0x80000
	v_lshl_add_u64 v[224:225], s[14:15], 0, v[134:135]
	s_addc_u32 s17, s15, 0
	s_add_i32 s44, s45, s61
	global_load_lds_dwordx4 v[224:225], off
	v_lshl_add_u64 v[226:227], s[16:17], 0, v[158:159]
	s_mov_b32 m0, s44
	v_lshl_add_u64 v[228:229], vcc, 0, v[132:133]
	global_load_lds_dwordx4 v[226:227], off
	v_lshl_add_u64 v[226:227], s[16:17], 0, v[134:135]
	s_add_i32 m0, s44, 0x2000
	s_nop 0
	global_load_lds_dwordx4 v[226:227], off
	v_lshl_add_u64 v[226:227], vcc, 0, v[130:131]
	s_mov_b32 m0, s73
	s_nop 0
	global_load_lds_dwordx4 v[226:227], off
	s_mov_b32 m0, s75
	s_nop 0
	global_load_lds_dwordx4 v[228:229], off
	s_waitcnt vmcnt(8)
	s_waitcnt lgkmcnt(0)
	s_barrier
	s_nop 0
	s_waitcnt lgkmcnt(0)
	v_mfma_f32_16x16x32_bf16 v[58:61], v[136:139], v[184:187], 0
	v_mfma_f32_16x16x32_bf16 v[58:61], v[144:147], v[188:191], v[58:61]
	v_mfma_f32_16x16x32_bf16 v[54:57], v[148:151], v[184:187], 0
	v_mfma_f32_16x16x32_bf16 v[54:57], v[152:155], v[188:191], v[54:57]
	v_mfma_f32_16x16x32_bf16 v[42:45], v[136:139], v[192:195], 0
	v_mfma_f32_16x16x32_bf16 v[42:45], v[144:147], v[196:199], v[42:45]
	v_mfma_f32_16x16x32_bf16 v[38:41], v[148:151], v[192:195], 0
	v_mfma_f32_16x16x32_bf16 v[38:41], v[152:155], v[196:199], v[38:41]
	v_mfma_f32_16x16x32_bf16 v[26:29], v[136:139], v[200:203], 0
	v_mfma_f32_16x16x32_bf16 v[26:29], v[144:147], v[204:207], v[26:29]
	v_mfma_f32_16x16x32_bf16 v[22:25], v[148:151], v[200:203], 0
	v_mfma_f32_16x16x32_bf16 v[22:25], v[152:155], v[204:207], v[22:25]
	v_mfma_f32_16x16x32_bf16 v[10:13], v[136:139], v[216:219], 0
	v_mfma_f32_16x16x32_bf16 v[10:13], v[144:147], v[220:223], v[10:13]
	v_mfma_f32_16x16x32_bf16 v[2:5], v[148:151], v[216:219], 0
	v_mfma_f32_16x16x32_bf16 v[2:5], v[152:155], v[220:223], v[2:5]
	v_mfma_f32_16x16x32_bf16 v[62:65], v[168:171], v[184:187], 0
	v_mfma_f32_16x16x32_bf16 v[62:65], v[172:175], v[188:191], v[62:65]
	v_mfma_f32_16x16x32_bf16 v[50:53], v[176:179], v[184:187], 0
	v_mfma_f32_16x16x32_bf16 v[50:53], v[180:183], v[188:191], v[50:53]
	v_mfma_f32_16x16x32_bf16 v[46:49], v[168:171], v[192:195], 0
	v_mfma_f32_16x16x32_bf16 v[46:49], v[172:175], v[196:199], v[46:49]
	v_mfma_f32_16x16x32_bf16 v[34:37], v[176:179], v[192:195], 0
	v_mfma_f32_16x16x32_bf16 v[34:37], v[180:183], v[196:199], v[34:37]
	v_mfma_f32_16x16x32_bf16 v[30:33], v[168:171], v[200:203], 0
	v_mfma_f32_16x16x32_bf16 v[30:33], v[172:175], v[204:207], v[30:33]
	v_mfma_f32_16x16x32_bf16 v[18:21], v[176:179], v[200:203], 0
	v_mfma_f32_16x16x32_bf16 v[18:21], v[180:183], v[204:207], v[18:21]
	v_mfma_f32_16x16x32_bf16 v[14:17], v[168:171], v[216:219], 0
	v_mfma_f32_16x16x32_bf16 v[14:17], v[172:175], v[220:223], v[14:17]
	v_mfma_f32_16x16x32_bf16 v[6:9], v[176:179], v[216:219], 0
	v_mfma_f32_16x16x32_bf16 v[6:9], v[180:183], v[220:223], v[6:9]
	s_barrier
	s_add_i32 s44, 0, 0x18000
	v_add_u32_e32 v143, s44, v140
	s_add_i32 s45, 0, 0x1c000
	ds_read_b128 v[136:139], v143
	ds_read_b128 v[144:147], v143 offset:1024
	ds_read_b128 v[148:151], v143 offset:2048
	ds_read_b128 v[152:155], v143 offset:3072
	v_add_u32_e32 v143, s45, v140
	ds_read_b128 v[168:171], v143
	ds_read_b128 v[172:175], v143 offset:1024
	ds_read_b128 v[176:179], v143 offset:2048
	ds_read_b128 v[180:183], v143 offset:3072
	s_add_u32 s16, vcc_lo, 0x80000
	s_addc_u32 s17, vcc_hi, 0
	s_mov_b32 m0, s24
	v_lshl_add_u64 v[230:231], s[16:17], 0, v[130:131]
	ds_read_b128 v[184:187], v142 offset:32768
	ds_read_b128 v[188:191], v142 offset:33792
	ds_read_b128 v[192:195], v142 offset:34816
	ds_read_b128 v[196:199], v142 offset:35840
	ds_read_b128 v[200:203], v142 offset:36864
	ds_read_b128 v[204:207], v142 offset:37888
	ds_read_b128 v[216:219], v142 offset:38912
	ds_read_b128 v[220:223], v142 offset:39936
	global_load_lds_dwordx4 v[230:231], off
	v_lshl_add_u64 v[230:231], s[16:17], 0, v[132:133]
	s_mov_b32 m0, s25
	s_nop 0
	global_load_lds_dwordx4 v[230:231], off
	s_waitcnt vmcnt(8)
	s_waitcnt lgkmcnt(0)
	s_barrier
	s_nop 0
	s_waitcnt lgkmcnt(0)
	v_mfma_f32_16x16x32_bf16 v[122:125], v[136:139], v[184:187], v[122:125]
	v_mfma_f32_16x16x32_bf16 v[122:125], v[144:147], v[188:191], v[122:125]
	v_mfma_f32_16x16x32_bf16 v[114:117], v[148:151], v[184:187], v[114:117]
	v_mfma_f32_16x16x32_bf16 v[114:117], v[152:155], v[188:191], v[114:117]
	v_mfma_f32_16x16x32_bf16 v[106:109], v[136:139], v[192:195], v[106:109]
	v_mfma_f32_16x16x32_bf16 v[106:109], v[144:147], v[196:199], v[106:109]
	v_mfma_f32_16x16x32_bf16 v[102:105], v[148:151], v[192:195], v[102:105]
	v_mfma_f32_16x16x32_bf16 v[102:105], v[152:155], v[196:199], v[102:105]
	v_mfma_f32_16x16x32_bf16 v[90:93], v[136:139], v[200:203], v[90:93]
	v_mfma_f32_16x16x32_bf16 v[90:93], v[144:147], v[204:207], v[90:93]
	v_mfma_f32_16x16x32_bf16 v[86:89], v[148:151], v[200:203], v[86:89]
	v_mfma_f32_16x16x32_bf16 v[86:89], v[152:155], v[204:207], v[86:89]
	v_mfma_f32_16x16x32_bf16 v[74:77], v[136:139], v[216:219], v[74:77]
	v_mfma_f32_16x16x32_bf16 v[74:77], v[144:147], v[220:223], v[74:77]
	v_mfma_f32_16x16x32_bf16 v[70:73], v[148:151], v[216:219], v[70:73]
	v_mfma_f32_16x16x32_bf16 v[70:73], v[152:155], v[220:223], v[70:73]
	v_mfma_f32_16x16x32_bf16 v[126:129], v[168:171], v[184:187], v[126:129]
	v_mfma_f32_16x16x32_bf16 v[126:129], v[172:175], v[188:191], v[126:129]
	v_mfma_f32_16x16x32_bf16 v[118:121], v[176:179], v[184:187], v[118:121]
	v_mfma_f32_16x16x32_bf16 v[118:121], v[180:183], v[188:191], v[118:121]
	v_mfma_f32_16x16x32_bf16 v[110:113], v[168:171], v[192:195], v[110:113]
	v_mfma_f32_16x16x32_bf16 v[110:113], v[172:175], v[196:199], v[110:113]
	v_mfma_f32_16x16x32_bf16 v[98:101], v[176:179], v[192:195], v[98:101]
	v_mfma_f32_16x16x32_bf16 v[98:101], v[180:183], v[196:199], v[98:101]
	v_mfma_f32_16x16x32_bf16 v[94:97], v[168:171], v[200:203], v[94:97]
	v_mfma_f32_16x16x32_bf16 v[94:97], v[172:175], v[204:207], v[94:97]
	v_mfma_f32_16x16x32_bf16 v[82:85], v[176:179], v[200:203], v[82:85]
	v_mfma_f32_16x16x32_bf16 v[82:85], v[180:183], v[204:207], v[82:85]
	v_mfma_f32_16x16x32_bf16 v[78:81], v[168:171], v[216:219], v[78:81]
	v_mfma_f32_16x16x32_bf16 v[78:81], v[172:175], v[220:223], v[78:81]
	v_mfma_f32_16x16x32_bf16 v[66:69], v[176:179], v[216:219], v[66:69]
	v_mfma_f32_16x16x32_bf16 v[66:69], v[180:183], v[220:223], v[66:69]
	s_barrier
	s_add_i32 s16, s44, s61
	v_lshl_add_u64 v[156:157], v[156:157], 0, s[56:57]
	s_mov_b32 m0, s16
	ds_read_b128 v[184:187], v142 offset:49152
	ds_read_b128 v[188:191], v142 offset:50176
	ds_read_b128 v[192:195], v142 offset:51200
	ds_read_b128 v[196:199], v142 offset:52224
	ds_read_b128 v[200:203], v142 offset:53248
	ds_read_b128 v[204:207], v142 offset:54272
	ds_read_b128 v[216:219], v142 offset:55296
	ds_read_b128 v[220:223], v142 offset:56320
	global_load_lds_dwordx4 v[156:157], off
	s_add_i32 m0, s16, 0x2000
	s_add_u32 s14, s14, 0x80080
	v_lshl_add_u64 v[156:157], v[224:225], 0, s[56:57]
	s_addc_u32 s15, s15, 0
	s_add_i32 s16, s45, s61
	global_load_lds_dwordx4 v[156:157], off
	v_lshl_add_u64 v[156:157], s[14:15], 0, v[158:159]
	s_mov_b32 m0, s16
	s_nop 0
	global_load_lds_dwordx4 v[156:157], off
	v_lshl_add_u64 v[156:157], s[14:15], 0, v[134:135]
	s_add_i32 m0, s16, 0x2000
	s_nop 0
	global_load_lds_dwordx4 v[156:157], off
	v_lshl_add_u64 v[156:157], v[226:227], 0, s[56:57]
	s_mov_b32 m0, s26
	s_nop 0
	global_load_lds_dwordx4 v[156:157], off
	v_lshl_add_u64 v[156:157], v[228:229], 0, s[56:57]
	s_mov_b32 m0, s27
	s_nop 0
	global_load_lds_dwordx4 v[156:157], off
	s_waitcnt vmcnt(8)
	s_waitcnt lgkmcnt(0)
	s_barrier
	s_waitcnt lgkmcnt(0)
	v_mfma_f32_16x16x32_bf16 v[58:61], v[136:139], v[184:187], v[58:61]
	v_mfma_f32_16x16x32_bf16 v[58:61], v[144:147], v[188:191], v[58:61]
	v_mfma_f32_16x16x32_bf16 v[54:57], v[148:151], v[184:187], v[54:57]
	v_mfma_f32_16x16x32_bf16 v[54:57], v[152:155], v[188:191], v[54:57]
	v_mfma_f32_16x16x32_bf16 v[42:45], v[136:139], v[192:195], v[42:45]
	v_mfma_f32_16x16x32_bf16 v[42:45], v[144:147], v[196:199], v[42:45]
	v_mfma_f32_16x16x32_bf16 v[38:41], v[148:151], v[192:195], v[38:41]
	v_mfma_f32_16x16x32_bf16 v[38:41], v[152:155], v[196:199], v[38:41]
	v_mfma_f32_16x16x32_bf16 v[26:29], v[136:139], v[200:203], v[26:29]
	v_mfma_f32_16x16x32_bf16 v[26:29], v[144:147], v[204:207], v[26:29]
	v_mfma_f32_16x16x32_bf16 v[22:25], v[148:151], v[200:203], v[22:25]
	v_mfma_f32_16x16x32_bf16 v[22:25], v[152:155], v[204:207], v[22:25]
	v_mfma_f32_16x16x32_bf16 v[10:13], v[136:139], v[216:219], v[10:13]
	v_mfma_f32_16x16x32_bf16 v[10:13], v[144:147], v[220:223], v[10:13]
	v_mfma_f32_16x16x32_bf16 v[2:5], v[148:151], v[216:219], v[2:5]
	v_mfma_f32_16x16x32_bf16 v[2:5], v[152:155], v[220:223], v[2:5]
	v_mfma_f32_16x16x32_bf16 v[62:65], v[168:171], v[184:187], v[62:65]
	v_mfma_f32_16x16x32_bf16 v[62:65], v[172:175], v[188:191], v[62:65]
	v_mfma_f32_16x16x32_bf16 v[50:53], v[176:179], v[184:187], v[50:53]
	v_mfma_f32_16x16x32_bf16 v[50:53], v[180:183], v[188:191], v[50:53]
	v_mfma_f32_16x16x32_bf16 v[46:49], v[168:171], v[192:195], v[46:49]
	v_mfma_f32_16x16x32_bf16 v[46:49], v[172:175], v[196:199], v[46:49]
	v_mfma_f32_16x16x32_bf16 v[34:37], v[176:179], v[192:195], v[34:37]
	v_mfma_f32_16x16x32_bf16 v[34:37], v[180:183], v[196:199], v[34:37]
	v_mfma_f32_16x16x32_bf16 v[30:33], v[168:171], v[200:203], v[30:33]
	v_mfma_f32_16x16x32_bf16 v[30:33], v[172:175], v[204:207], v[30:33]
	v_mfma_f32_16x16x32_bf16 v[18:21], v[176:179], v[200:203], v[18:21]
	v_mfma_f32_16x16x32_bf16 v[18:21], v[180:183], v[204:207], v[18:21]
	v_mfma_f32_16x16x32_bf16 v[14:17], v[168:171], v[216:219], v[14:17]
	v_mfma_f32_16x16x32_bf16 v[14:17], v[172:175], v[220:223], v[14:17]
	v_mfma_f32_16x16x32_bf16 v[6:9], v[176:179], v[216:219], v[6:9]
	v_mfma_f32_16x16x32_bf16 v[6:9], v[180:183], v[220:223], v[6:9]
	s_barrier
	s_cmp_gt_u32 s35, 29
	s_mov_b32 s35, s54
	s_cbranch_scc1 .LBB0_279
	s_branch .LBB0_270

.Lsp_LBB0269:
	v_add_u32_e32 v143, 0x10000, v140
	ds_read_b128 v[136:139], v143
	ds_read_b128 v[144:147], v143 offset:1024
	ds_read_b128 v[148:151], v143 offset:2048
	ds_read_b128 v[152:155], v143 offset:3072
	v_add_u32_e32 v143, 0x14000, v140
	ds_read_b128 v[168:171], v143
	ds_read_b128 v[172:175], v143 offset:1024
	ds_read_b128 v[176:179], v143 offset:2048
	ds_read_b128 v[180:183], v143 offset:3072
	ds_read_b128 v[184:187], v142
	ds_read_b128 v[188:191], v142 offset:1024
	ds_read_b128 v[192:195], v142 offset:2048
	ds_read_b128 v[196:199], v142 offset:3072
	ds_read_b128 v[200:203], v142 offset:4096
	ds_read_b128 v[204:207], v142 offset:5120
	ds_read_b128 v[216:219], v142 offset:6144
	ds_read_b128 v[220:223], v142 offset:7168
	s_or_b32 s54, s35, 1
	s_lshl_b64 s[16:17], s[54:55], 7
	s_add_i32 s54, s35, 2
	s_lshl_b64 s[44:45], s[54:55], 7
	s_add_u32 s46, s66, s44
	s_addc_u32 s47, s67, s45
	s_and_b64 vcc, s[14:15], exec
	s_cselect_b32 vcc_hi, s29, s47
	s_cselect_b32 vcc_lo, s65, s46
	s_add_u32 s44, s70, s44
	s_addc_u32 s45, s71, s45
	s_and_b64 s[14:15], s[14:15], exec
	s_cselect_b32 s15, s51, s45
	s_cselect_b32 s14, s30, s44
	s_add_i32 s44, 0, 0x10000
	s_add_i32 s45, 0, 0x14000
	s_add_i32 m0, s73, 0xc000
	s_add_u32 s16, s31, s16
	s_addc_u32 s17, s34, s17
	global_load_lds_dwordx4 v130, s[16:17]
	s_add_i32 m0, s73, 0xe000
	s_nop 0
	global_load_lds_dwordx4 v132, s[16:17]
	s_waitcnt vmcnt(8)
	s_waitcnt lgkmcnt(0)
	s_barrier
	s_waitcnt lgkmcnt(0)
	v_mfma_f32_16x16x32_bf16 v[122:125], v[136:139], v[184:187], v[122:125]
	v_mfma_f32_16x16x32_bf16 v[122:125], v[144:147], v[188:191], v[122:125]
	v_mfma_f32_16x16x32_bf16 v[114:117], v[148:151], v[184:187], v[114:117]
	v_mfma_f32_16x16x32_bf16 v[114:117], v[152:155], v[188:191], v[114:117]
	v_mfma_f32_16x16x32_bf16 v[106:109], v[136:139], v[192:195], v[106:109]
	v_mfma_f32_16x16x32_bf16 v[106:109], v[144:147], v[196:199], v[106:109]
	v_mfma_f32_16x16x32_bf16 v[102:105], v[148:151], v[192:195], v[102:105]
	v_mfma_f32_16x16x32_bf16 v[102:105], v[152:155], v[196:199], v[102:105]
	v_mfma_f32_16x16x32_bf16 v[90:93], v[136:139], v[200:203], v[90:93]
	v_mfma_f32_16x16x32_bf16 v[90:93], v[144:147], v[204:207], v[90:93]
	v_mfma_f32_16x16x32_bf16 v[86:89], v[148:151], v[200:203], v[86:89]
	v_mfma_f32_16x16x32_bf16 v[86:89], v[152:155], v[204:207], v[86:89]
	v_mfma_f32_16x16x32_bf16 v[74:77], v[136:139], v[216:219], v[74:77]
	v_mfma_f32_16x16x32_bf16 v[74:77], v[144:147], v[220:223], v[74:77]
	v_mfma_f32_16x16x32_bf16 v[70:73], v[148:151], v[216:219], v[70:73]
	v_mfma_f32_16x16x32_bf16 v[70:73], v[152:155], v[220:223], v[70:73]
	v_mfma_f32_16x16x32_bf16 v[126:129], v[168:171], v[184:187], v[126:129]
	v_mfma_f32_16x16x32_bf16 v[126:129], v[172:175], v[188:191], v[126:129]
	v_mfma_f32_16x16x32_bf16 v[118:121], v[176:179], v[184:187], v[118:121]
	v_mfma_f32_16x16x32_bf16 v[118:121], v[180:183], v[188:191], v[118:121]
	v_mfma_f32_16x16x32_bf16 v[110:113], v[168:171], v[192:195], v[110:113]
	v_mfma_f32_16x16x32_bf16 v[110:113], v[172:175], v[196:199], v[110:113]
	v_mfma_f32_16x16x32_bf16 v[98:101], v[176:179], v[192:195], v[98:101]
	v_mfma_f32_16x16x32_bf16 v[98:101], v[180:183], v[196:199], v[98:101]
	v_mfma_f32_16x16x32_bf16 v[94:97], v[168:171], v[200:203], v[94:97]
	v_mfma_f32_16x16x32_bf16 v[94:97], v[172:175], v[204:207], v[94:97]
	v_mfma_f32_16x16x32_bf16 v[82:85], v[176:179], v[200:203], v[82:85]
	v_mfma_f32_16x16x32_bf16 v[82:85], v[180:183], v[204:207], v[82:85]
	v_mfma_f32_16x16x32_bf16 v[78:81], v[168:171], v[216:219], v[78:81]
	v_mfma_f32_16x16x32_bf16 v[78:81], v[172:175], v[220:223], v[78:81]
	v_mfma_f32_16x16x32_bf16 v[66:69], v[176:179], v[216:219], v[66:69]
	v_mfma_f32_16x16x32_bf16 v[66:69], v[180:183], v[220:223], v[66:69]
	s_barrier
	s_add_i32 s16, s44, s61
	s_mov_b32 m0, s16
	ds_read_b128 v[184:187], v142 offset:16384
	ds_read_b128 v[188:191], v142 offset:17408
	ds_read_b128 v[192:195], v142 offset:18432
	ds_read_b128 v[196:199], v142 offset:19456
	ds_read_b128 v[200:203], v142 offset:20480
	ds_read_b128 v[204:207], v142 offset:21504
	ds_read_b128 v[216:219], v142 offset:22528
	ds_read_b128 v[220:223], v142 offset:23552
	global_load_lds_dwordx4 v158, s[14:15]
	s_add_i32 m0, s16, 0x2000
	s_nop 0
	global_load_lds_dwordx4 v134, s[14:15]
	s_add_u32 s16, s14, 0x80000
	s_addc_u32 s17, s15, 0
	s_add_i32 s44, s45, s61
	s_mov_b32 m0, s44
	s_nop 0
	global_load_lds_dwordx4 v158, s[16:17]
	s_add_i32 m0, s44, 0x2000
	s_nop 0
	global_load_lds_dwordx4 v134, s[16:17]
	s_mov_b32 m0, s73
	s_nop 0
	global_load_lds_dwordx4 v130, vcc
	s_mov_b32 m0, s75
	s_nop 0
	global_load_lds_dwordx4 v132, vcc
	s_waitcnt vmcnt(8)
	s_waitcnt lgkmcnt(0)
	s_barrier
	s_nop 0
	s_waitcnt lgkmcnt(0)
	v_mfma_f32_16x16x32_bf16 v[58:61], v[136:139], v[184:187], v[58:61]
	v_mfma_f32_16x16x32_bf16 v[58:61], v[144:147], v[188:191], v[58:61]
	v_mfma_f32_16x16x32_bf16 v[54:57], v[148:151], v[184:187], v[54:57]
	v_mfma_f32_16x16x32_bf16 v[54:57], v[152:155], v[188:191], v[54:57]
	v_mfma_f32_16x16x32_bf16 v[42:45], v[136:139], v[192:195], v[42:45]
	v_mfma_f32_16x16x32_bf16 v[42:45], v[144:147], v[196:199], v[42:45]
	v_mfma_f32_16x16x32_bf16 v[38:41], v[148:151], v[192:195], v[38:41]
	v_mfma_f32_16x16x32_bf16 v[38:41], v[152:155], v[196:199], v[38:41]
	v_mfma_f32_16x16x32_bf16 v[26:29], v[136:139], v[200:203], v[26:29]
	v_mfma_f32_16x16x32_bf16 v[26:29], v[144:147], v[204:207], v[26:29]
	v_mfma_f32_16x16x32_bf16 v[22:25], v[148:151], v[200:203], v[22:25]
	v_mfma_f32_16x16x32_bf16 v[22:25], v[152:155], v[204:207], v[22:25]
	v_mfma_f32_16x16x32_bf16 v[10:13], v[136:139], v[216:219], v[10:13]
	v_mfma_f32_16x16x32_bf16 v[10:13], v[144:147], v[220:223], v[10:13]
	v_mfma_f32_16x16x32_bf16 v[2:5], v[148:151], v[216:219], v[2:5]
	v_mfma_f32_16x16x32_bf16 v[2:5], v[152:155], v[220:223], v[2:5]
	v_mfma_f32_16x16x32_bf16 v[62:65], v[168:171], v[184:187], v[62:65]
	v_mfma_f32_16x16x32_bf16 v[62:65], v[172:175], v[188:191], v[62:65]
	v_mfma_f32_16x16x32_bf16 v[50:53], v[176:179], v[184:187], v[50:53]
	v_mfma_f32_16x16x32_bf16 v[50:53], v[180:183], v[188:191], v[50:53]
	v_mfma_f32_16x16x32_bf16 v[46:49], v[168:171], v[192:195], v[46:49]
	v_mfma_f32_16x16x32_bf16 v[46:49], v[172:175], v[196:199], v[46:49]
	v_mfma_f32_16x16x32_bf16 v[34:37], v[176:179], v[192:195], v[34:37]
	v_mfma_f32_16x16x32_bf16 v[34:37], v[180:183], v[196:199], v[34:37]
	v_mfma_f32_16x16x32_bf16 v[30:33], v[168:171], v[200:203], v[30:33]
	v_mfma_f32_16x16x32_bf16 v[30:33], v[172:175], v[204:207], v[30:33]
	v_mfma_f32_16x16x32_bf16 v[18:21], v[176:179], v[200:203], v[18:21]
	v_mfma_f32_16x16x32_bf16 v[18:21], v[180:183], v[204:207], v[18:21]
	v_mfma_f32_16x16x32_bf16 v[14:17], v[168:171], v[216:219], v[14:17]
	v_mfma_f32_16x16x32_bf16 v[14:17], v[172:175], v[220:223], v[14:17]
	v_mfma_f32_16x16x32_bf16 v[6:9], v[176:179], v[216:219], v[6:9]
	v_mfma_f32_16x16x32_bf16 v[6:9], v[180:183], v[220:223], v[6:9]
	s_barrier
	s_add_i32 s44, 0, 0x18000
	s_add_i32 s45, 0, 0x1c000
	s_add_u32 s16, vcc_lo, 0x80000
	s_addc_u32 s17, vcc_hi, 0
	s_mov_b32 m0, s24
	v_add_u32_e32 v143, s44, v140
	ds_read_b128 v[136:139], v143
	ds_read_b128 v[144:147], v143 offset:1024
	ds_read_b128 v[148:151], v143 offset:2048
	ds_read_b128 v[152:155], v143 offset:3072
	v_add_u32_e32 v143, s45, v140
	ds_read_b128 v[168:171], v143
	ds_read_b128 v[172:175], v143 offset:1024
	ds_read_b128 v[176:179], v143 offset:2048
	ds_read_b128 v[180:183], v143 offset:3072
	ds_read_b128 v[184:187], v142 offset:32768
	ds_read_b128 v[188:191], v142 offset:33792
	ds_read_b128 v[192:195], v142 offset:34816
	ds_read_b128 v[196:199], v142 offset:35840
	ds_read_b128 v[200:203], v142 offset:36864
	ds_read_b128 v[204:207], v142 offset:37888
	ds_read_b128 v[216:219], v142 offset:38912
	ds_read_b128 v[220:223], v142 offset:39936
	global_load_lds_dwordx4 v130, s[16:17]
	s_mov_b32 m0, s25
	s_nop 0
	global_load_lds_dwordx4 v132, s[16:17]
	s_waitcnt vmcnt(8)
	s_waitcnt lgkmcnt(0)
	s_barrier
	s_nop 0
	s_waitcnt lgkmcnt(0)
	v_mfma_f32_16x16x32_bf16 v[122:125], v[136:139], v[184:187], v[122:125]
	v_mfma_f32_16x16x32_bf16 v[122:125], v[144:147], v[188:191], v[122:125]
	v_mfma_f32_16x16x32_bf16 v[114:117], v[148:151], v[184:187], v[114:117]
	v_mfma_f32_16x16x32_bf16 v[114:117], v[152:155], v[188:191], v[114:117]
	v_mfma_f32_16x16x32_bf16 v[106:109], v[136:139], v[192:195], v[106:109]
	v_mfma_f32_16x16x32_bf16 v[106:109], v[144:147], v[196:199], v[106:109]
	v_mfma_f32_16x16x32_bf16 v[102:105], v[148:151], v[192:195], v[102:105]
	v_mfma_f32_16x16x32_bf16 v[102:105], v[152:155], v[196:199], v[102:105]
	v_mfma_f32_16x16x32_bf16 v[90:93], v[136:139], v[200:203], v[90:93]
	v_mfma_f32_16x16x32_bf16 v[90:93], v[144:147], v[204:207], v[90:93]
	v_mfma_f32_16x16x32_bf16 v[86:89], v[148:151], v[200:203], v[86:89]
	v_mfma_f32_16x16x32_bf16 v[86:89], v[152:155], v[204:207], v[86:89]
	v_mfma_f32_16x16x32_bf16 v[74:77], v[136:139], v[216:219], v[74:77]
	v_mfma_f32_16x16x32_bf16 v[74:77], v[144:147], v[220:223], v[74:77]
	v_mfma_f32_16x16x32_bf16 v[70:73], v[148:151], v[216:219], v[70:73]
	v_mfma_f32_16x16x32_bf16 v[70:73], v[152:155], v[220:223], v[70:73]
	v_mfma_f32_16x16x32_bf16 v[126:129], v[168:171], v[184:187], v[126:129]
	v_mfma_f32_16x16x32_bf16 v[126:129], v[172:175], v[188:191], v[126:129]
	v_mfma_f32_16x16x32_bf16 v[118:121], v[176:179], v[184:187], v[118:121]
	v_mfma_f32_16x16x32_bf16 v[118:121], v[180:183], v[188:191], v[118:121]
	v_mfma_f32_16x16x32_bf16 v[110:113], v[168:171], v[192:195], v[110:113]
	v_mfma_f32_16x16x32_bf16 v[110:113], v[172:175], v[196:199], v[110:113]
	v_mfma_f32_16x16x32_bf16 v[98:101], v[176:179], v[192:195], v[98:101]
	v_mfma_f32_16x16x32_bf16 v[98:101], v[180:183], v[196:199], v[98:101]
	v_mfma_f32_16x16x32_bf16 v[94:97], v[168:171], v[200:203], v[94:97]
	v_mfma_f32_16x16x32_bf16 v[94:97], v[172:175], v[204:207], v[94:97]
	v_mfma_f32_16x16x32_bf16 v[82:85], v[176:179], v[200:203], v[82:85]
	v_mfma_f32_16x16x32_bf16 v[82:85], v[180:183], v[204:207], v[82:85]
	v_mfma_f32_16x16x32_bf16 v[78:81], v[168:171], v[216:219], v[78:81]
	v_mfma_f32_16x16x32_bf16 v[78:81], v[172:175], v[220:223], v[78:81]
	v_mfma_f32_16x16x32_bf16 v[66:69], v[176:179], v[216:219], v[66:69]
	v_mfma_f32_16x16x32_bf16 v[66:69], v[180:183], v[220:223], v[66:69]
	s_barrier
	s_add_i32 s16, s44, s61
	s_mov_b32 m0, s16
	s_add_u32 s14, s14, 0x80
	s_addc_u32 s15, s15, 0
	s_add_u32 vcc_lo, vcc_lo, 0x80
	s_addc_u32 vcc_hi, vcc_hi, 0
	ds_read_b128 v[184:187], v142 offset:49152
	ds_read_b128 v[188:191], v142 offset:50176
	ds_read_b128 v[192:195], v142 offset:51200
	ds_read_b128 v[196:199], v142 offset:52224
	ds_read_b128 v[200:203], v142 offset:53248
	ds_read_b128 v[204:207], v142 offset:54272
	ds_read_b128 v[216:219], v142 offset:55296
	ds_read_b128 v[220:223], v142 offset:56320
	global_load_lds_dwordx4 v158, s[14:15]
	s_add_i32 m0, s16, 0x2000
	s_nop 0
	global_load_lds_dwordx4 v134, s[14:15]
	s_add_u32 s14, s14, 0x80000
	s_addc_u32 s15, s15, 0
	s_add_i32 s16, s45, s61
	s_mov_b32 m0, s16
	s_nop 0
	global_load_lds_dwordx4 v158, s[14:15]
	s_add_i32 m0, s16, 0x2000
	s_nop 0
	global_load_lds_dwordx4 v134, s[14:15]
	s_mov_b32 m0, s26
	s_nop 0
	global_load_lds_dwordx4 v130, vcc
	s_mov_b32 m0, s27
	s_nop 0
	global_load_lds_dwordx4 v132, vcc
	s_waitcnt vmcnt(8)
	s_waitcnt lgkmcnt(0)
	s_barrier
	s_nop 0
	s_waitcnt lgkmcnt(0)
	v_mfma_f32_16x16x32_bf16 v[58:61], v[136:139], v[184:187], v[58:61]
	v_mfma_f32_16x16x32_bf16 v[58:61], v[144:147], v[188:191], v[58:61]
	v_mfma_f32_16x16x32_bf16 v[54:57], v[148:151], v[184:187], v[54:57]
	v_mfma_f32_16x16x32_bf16 v[54:57], v[152:155], v[188:191], v[54:57]
	v_mfma_f32_16x16x32_bf16 v[42:45], v[136:139], v[192:195], v[42:45]
	v_mfma_f32_16x16x32_bf16 v[42:45], v[144:147], v[196:199], v[42:45]
	v_mfma_f32_16x16x32_bf16 v[38:41], v[148:151], v[192:195], v[38:41]
	v_mfma_f32_16x16x32_bf16 v[38:41], v[152:155], v[196:199], v[38:41]
	v_mfma_f32_16x16x32_bf16 v[26:29], v[136:139], v[200:203], v[26:29]
	v_mfma_f32_16x16x32_bf16 v[26:29], v[144:147], v[204:207], v[26:29]
	v_mfma_f32_16x16x32_bf16 v[22:25], v[148:151], v[200:203], v[22:25]
	v_mfma_f32_16x16x32_bf16 v[22:25], v[152:155], v[204:207], v[22:25]
	v_mfma_f32_16x16x32_bf16 v[10:13], v[136:139], v[216:219], v[10:13]
	v_mfma_f32_16x16x32_bf16 v[10:13], v[144:147], v[220:223], v[10:13]
	v_mfma_f32_16x16x32_bf16 v[2:5], v[148:151], v[216:219], v[2:5]
	v_mfma_f32_16x16x32_bf16 v[2:5], v[152:155], v[220:223], v[2:5]
	v_mfma_f32_16x16x32_bf16 v[62:65], v[168:171], v[184:187], v[62:65]
	v_mfma_f32_16x16x32_bf16 v[62:65], v[172:175], v[188:191], v[62:65]
	v_mfma_f32_16x16x32_bf16 v[50:53], v[176:179], v[184:187], v[50:53]
	v_mfma_f32_16x16x32_bf16 v[50:53], v[180:183], v[188:191], v[50:53]
	v_mfma_f32_16x16x32_bf16 v[46:49], v[168:171], v[192:195], v[46:49]
	v_mfma_f32_16x16x32_bf16 v[46:49], v[172:175], v[196:199], v[46:49]
	v_mfma_f32_16x16x32_bf16 v[34:37], v[176:179], v[192:195], v[34:37]
	v_mfma_f32_16x16x32_bf16 v[34:37], v[180:183], v[196:199], v[34:37]
	v_mfma_f32_16x16x32_bf16 v[30:33], v[168:171], v[200:203], v[30:33]
	v_mfma_f32_16x16x32_bf16 v[30:33], v[172:175], v[204:207], v[30:33]
	v_mfma_f32_16x16x32_bf16 v[18:21], v[176:179], v[200:203], v[18:21]
	v_mfma_f32_16x16x32_bf16 v[18:21], v[180:183], v[204:207], v[18:21]
	v_mfma_f32_16x16x32_bf16 v[14:17], v[168:171], v[216:219], v[14:17]
	v_mfma_f32_16x16x32_bf16 v[14:17], v[172:175], v[220:223], v[14:17]
	v_mfma_f32_16x16x32_bf16 v[6:9], v[176:179], v[216:219], v[6:9]
	v_mfma_f32_16x16x32_bf16 v[6:9], v[180:183], v[220:223], v[6:9]
	s_barrier
	s_cmp_gt_u32 s35, 29
	s_mov_b32 s35, s54
	s_cbranch_scc1 .LBB0_279

.Lsp_LBB0353_plp353:
	s_add_u32 s36, s0, 0x100
	s_addc_u32 s37, s1, 0
	s_add_i32 s27, 0, 0x10000
	s_cmpk_eq_i32 s26, 0x52
	s_cselect_b32 s69, s65, s37
	s_cselect_b32 s68, s64, s36
	v_add_u32_e32 v144, s27, v146
	s_cselect_b32 s15, s67, s25
	s_cselect_b32 s14, s66, s24
	s_add_i32 s28, 0, 0x14000
	ds_read_b128 v[140:143], v144
	ds_read_b128 v[150:153], v144 offset:1024
	ds_read_b128 v[154:157], v144 offset:2048
	ds_read_b128 v[168:171], v144 offset:3072
	v_add_u32_e32 v144, s28, v146
	ds_read_b128 v[172:175], v144
	ds_read_b128 v[176:179], v144 offset:1024
	ds_read_b128 v[180:183], v144 offset:2048
	ds_read_b128 v[184:187], v144 offset:3072
	v_lshl_add_u64 v[144:145], s[0:1], 0, v[136:137]
	s_add_i32 m0, s59, 0xc000
	ds_read_b128 v[188:191], v148
	ds_read_b128 v[192:195], v148 offset:1024
	ds_read_b128 v[196:199], v148 offset:2048
	ds_read_b128 v[200:203], v148 offset:3072
	ds_read_b128 v[204:207], v148 offset:4096
	ds_read_b128 v[216:219], v148 offset:5120
	ds_read_b128 v[220:223], v148 offset:6144
	ds_read_b128 v[224:227], v148 offset:7168
	global_load_lds_dwordx4 v[144:145], off
	v_lshl_add_u64 v[144:145], s[0:1], 0, v[138:139]
	s_add_i32 m0, s59, 0xe000
	s_nop 0
	global_load_lds_dwordx4 v[144:145], off
	s_waitcnt vmcnt(8)
	s_waitcnt lgkmcnt(0)
	s_barrier
	s_nop 0
	s_waitcnt lgkmcnt(0)
	v_mfma_f32_16x16x32_bf16 v[126:129], v[140:143], v[188:191], 0
	v_mfma_f32_16x16x32_bf16 v[126:129], v[150:153], v[192:195], v[126:129]
	v_mfma_f32_16x16x32_bf16 v[122:125], v[154:157], v[188:191], 0
	v_mfma_f32_16x16x32_bf16 v[122:125], v[168:171], v[192:195], v[122:125]
	v_mfma_f32_16x16x32_bf16 v[110:113], v[140:143], v[196:199], 0
	v_mfma_f32_16x16x32_bf16 v[110:113], v[150:153], v[200:203], v[110:113]
	v_mfma_f32_16x16x32_bf16 v[106:109], v[154:157], v[196:199], 0
	v_mfma_f32_16x16x32_bf16 v[106:109], v[168:171], v[200:203], v[106:109]
	v_mfma_f32_16x16x32_bf16 v[94:97], v[140:143], v[204:207], 0
	v_mfma_f32_16x16x32_bf16 v[94:97], v[150:153], v[216:219], v[94:97]
	v_mfma_f32_16x16x32_bf16 v[90:93], v[154:157], v[204:207], 0
	v_mfma_f32_16x16x32_bf16 v[90:93], v[168:171], v[216:219], v[90:93]
	v_mfma_f32_16x16x32_bf16 v[78:81], v[140:143], v[220:223], 0
	v_mfma_f32_16x16x32_bf16 v[78:81], v[150:153], v[224:227], v[78:81]
	v_mfma_f32_16x16x32_bf16 v[74:77], v[154:157], v[220:223], 0
	v_mfma_f32_16x16x32_bf16 v[74:77], v[168:171], v[224:227], v[74:77]
	v_mfma_f32_16x16x32_bf16 v[118:121], v[172:175], v[188:191], 0
	v_mfma_f32_16x16x32_bf16 v[118:121], v[176:179], v[192:195], v[118:121]
	v_mfma_f32_16x16x32_bf16 v[114:117], v[180:183], v[188:191], 0
	v_mfma_f32_16x16x32_bf16 v[114:117], v[184:187], v[192:195], v[114:117]
	v_mfma_f32_16x16x32_bf16 v[102:105], v[172:175], v[196:199], 0
	v_mfma_f32_16x16x32_bf16 v[102:105], v[176:179], v[200:203], v[102:105]
	v_mfma_f32_16x16x32_bf16 v[98:101], v[180:183], v[196:199], 0
	v_mfma_f32_16x16x32_bf16 v[98:101], v[184:187], v[200:203], v[98:101]
	v_mfma_f32_16x16x32_bf16 v[86:89], v[172:175], v[204:207], 0
	v_mfma_f32_16x16x32_bf16 v[86:89], v[176:179], v[216:219], v[86:89]
	v_mfma_f32_16x16x32_bf16 v[82:85], v[180:183], v[204:207], 0
	v_mfma_f32_16x16x32_bf16 v[82:85], v[184:187], v[216:219], v[82:85]
	v_mfma_f32_16x16x32_bf16 v[70:73], v[172:175], v[220:223], 0
	v_mfma_f32_16x16x32_bf16 v[70:73], v[176:179], v[224:227], v[70:73]
	v_mfma_f32_16x16x32_bf16 v[66:69], v[180:183], v[220:223], 0
	v_mfma_f32_16x16x32_bf16 v[66:69], v[184:187], v[224:227], v[66:69]
	s_barrier
	s_add_i32 s0, s27, s58
	v_lshl_add_u64 v[144:145], s[14:15], 0, v[158:159]
	s_mov_b32 m0, s0
	ds_read_b128 v[188:191], v148 offset:16384
	ds_read_b128 v[192:195], v148 offset:17408
	ds_read_b128 v[196:199], v148 offset:18432
	ds_read_b128 v[200:203], v148 offset:19456
	ds_read_b128 v[204:207], v148 offset:20480
	ds_read_b128 v[216:219], v148 offset:21504
	ds_read_b128 v[220:223], v148 offset:22528
	ds_read_b128 v[224:227], v148 offset:23552
	global_load_lds_dwordx4 v[144:145], off
	s_add_i32 m0, s0, 0x2000
	s_add_u32 s0, s14, 0x158000
	v_lshl_add_u64 v[228:229], s[14:15], 0, v[134:135]
	s_addc_u32 s1, s15, 0
	s_add_i32 s27, s28, s58
	global_load_lds_dwordx4 v[228:229], off
	v_lshl_add_u64 v[230:231], s[0:1], 0, v[158:159]
	s_mov_b32 m0, s27
	v_lshl_add_u64 v[232:233], s[68:69], 0, v[132:133]
	global_load_lds_dwordx4 v[230:231], off
	v_lshl_add_u64 v[230:231], s[0:1], 0, v[134:135]
	s_add_i32 m0, s27, 0x2000
	s_nop 0
	global_load_lds_dwordx4 v[230:231], off
	v_lshl_add_u64 v[230:231], s[68:69], 0, v[130:131]
	s_mov_b32 m0, s59
	s_nop 0
	global_load_lds_dwordx4 v[230:231], off
	s_mov_b32 m0, s70
	s_nop 0
	global_load_lds_dwordx4 v[232:233], off
	s_waitcnt vmcnt(8)
	s_waitcnt lgkmcnt(0)
	s_barrier
	s_nop 0
	s_waitcnt lgkmcnt(0)
	v_mfma_f32_16x16x32_bf16 v[62:65], v[140:143], v[188:191], 0
	v_mfma_f32_16x16x32_bf16 v[62:65], v[150:153], v[192:195], v[62:65]
	v_mfma_f32_16x16x32_bf16 v[58:61], v[154:157], v[188:191], 0
	v_mfma_f32_16x16x32_bf16 v[58:61], v[168:171], v[192:195], v[58:61]
	v_mfma_f32_16x16x32_bf16 v[46:49], v[140:143], v[196:199], 0
	v_mfma_f32_16x16x32_bf16 v[46:49], v[150:153], v[200:203], v[46:49]
	v_mfma_f32_16x16x32_bf16 v[42:45], v[154:157], v[196:199], 0
	v_mfma_f32_16x16x32_bf16 v[42:45], v[168:171], v[200:203], v[42:45]
	v_mfma_f32_16x16x32_bf16 v[30:33], v[140:143], v[204:207], 0
	v_mfma_f32_16x16x32_bf16 v[30:33], v[150:153], v[216:219], v[30:33]
	v_mfma_f32_16x16x32_bf16 v[26:29], v[154:157], v[204:207], 0
	v_mfma_f32_16x16x32_bf16 v[26:29], v[168:171], v[216:219], v[26:29]
	v_mfma_f32_16x16x32_bf16 v[14:17], v[140:143], v[220:223], 0
	v_mfma_f32_16x16x32_bf16 v[14:17], v[150:153], v[224:227], v[14:17]
	v_mfma_f32_16x16x32_bf16 v[10:13], v[154:157], v[220:223], 0
	v_mfma_f32_16x16x32_bf16 v[10:13], v[168:171], v[224:227], v[10:13]
	v_mfma_f32_16x16x32_bf16 v[54:57], v[172:175], v[188:191], 0
	v_mfma_f32_16x16x32_bf16 v[54:57], v[176:179], v[192:195], v[54:57]
	v_mfma_f32_16x16x32_bf16 v[50:53], v[180:183], v[188:191], 0
	v_mfma_f32_16x16x32_bf16 v[50:53], v[184:187], v[192:195], v[50:53]
	v_mfma_f32_16x16x32_bf16 v[38:41], v[172:175], v[196:199], 0
	v_mfma_f32_16x16x32_bf16 v[38:41], v[176:179], v[200:203], v[38:41]
	v_mfma_f32_16x16x32_bf16 v[34:37], v[180:183], v[196:199], 0
	v_mfma_f32_16x16x32_bf16 v[34:37], v[184:187], v[200:203], v[34:37]
	v_mfma_f32_16x16x32_bf16 v[22:25], v[172:175], v[204:207], 0
	v_mfma_f32_16x16x32_bf16 v[22:25], v[176:179], v[216:219], v[22:25]
	v_mfma_f32_16x16x32_bf16 v[18:21], v[180:183], v[204:207], 0
	v_mfma_f32_16x16x32_bf16 v[18:21], v[184:187], v[216:219], v[18:21]
	v_mfma_f32_16x16x32_bf16 v[6:9], v[172:175], v[220:223], 0
	v_mfma_f32_16x16x32_bf16 v[6:9], v[176:179], v[224:227], v[6:9]
	v_mfma_f32_16x16x32_bf16 v[2:5], v[180:183], v[220:223], 0
	v_mfma_f32_16x16x32_bf16 v[2:5], v[184:187], v[224:227], v[2:5]
	s_barrier
	s_add_i32 s27, 0, 0x18000
	v_add_u32_e32 v149, s27, v146
	s_add_i32 s28, 0, 0x1c000
	ds_read_b128 v[140:143], v149
	ds_read_b128 v[150:153], v149 offset:1024
	ds_read_b128 v[154:157], v149 offset:2048
	ds_read_b128 v[168:171], v149 offset:3072
	v_add_u32_e32 v149, s28, v146
	ds_read_b128 v[172:175], v149
	ds_read_b128 v[176:179], v149 offset:1024
	ds_read_b128 v[180:183], v149 offset:2048
	ds_read_b128 v[184:187], v149 offset:3072
	s_add_u32 s0, s68, 0x158000
	s_addc_u32 s1, s69, 0
	s_mov_b32 m0, s71
	v_lshl_add_u64 v[234:235], s[0:1], 0, v[130:131]
	ds_read_b128 v[188:191], v148 offset:32768
	ds_read_b128 v[192:195], v148 offset:33792
	ds_read_b128 v[196:199], v148 offset:34816
	ds_read_b128 v[200:203], v148 offset:35840
	ds_read_b128 v[204:207], v148 offset:36864
	ds_read_b128 v[216:219], v148 offset:37888
	ds_read_b128 v[220:223], v148 offset:38912
	ds_read_b128 v[224:227], v148 offset:39936
	global_load_lds_dwordx4 v[234:235], off
	v_lshl_add_u64 v[234:235], s[0:1], 0, v[132:133]
	s_mov_b32 m0, s72
	s_nop 0
	global_load_lds_dwordx4 v[234:235], off
	s_waitcnt vmcnt(8)
	s_waitcnt lgkmcnt(0)
	s_barrier
	s_nop 0
	s_waitcnt lgkmcnt(0)
	v_mfma_f32_16x16x32_bf16 v[126:129], v[140:143], v[188:191], v[126:129]
	v_mfma_f32_16x16x32_bf16 v[126:129], v[150:153], v[192:195], v[126:129]
	v_mfma_f32_16x16x32_bf16 v[122:125], v[154:157], v[188:191], v[122:125]
	v_mfma_f32_16x16x32_bf16 v[122:125], v[168:171], v[192:195], v[122:125]
	v_mfma_f32_16x16x32_bf16 v[110:113], v[140:143], v[196:199], v[110:113]
	v_mfma_f32_16x16x32_bf16 v[110:113], v[150:153], v[200:203], v[110:113]
	v_mfma_f32_16x16x32_bf16 v[106:109], v[154:157], v[196:199], v[106:109]
	v_mfma_f32_16x16x32_bf16 v[106:109], v[168:171], v[200:203], v[106:109]
	v_mfma_f32_16x16x32_bf16 v[94:97], v[140:143], v[204:207], v[94:97]
	v_mfma_f32_16x16x32_bf16 v[94:97], v[150:153], v[216:219], v[94:97]
	v_mfma_f32_16x16x32_bf16 v[90:93], v[154:157], v[204:207], v[90:93]
	v_mfma_f32_16x16x32_bf16 v[90:93], v[168:171], v[216:219], v[90:93]
	v_mfma_f32_16x16x32_bf16 v[78:81], v[140:143], v[220:223], v[78:81]
	v_mfma_f32_16x16x32_bf16 v[78:81], v[150:153], v[224:227], v[78:81]
	v_mfma_f32_16x16x32_bf16 v[74:77], v[154:157], v[220:223], v[74:77]
	v_mfma_f32_16x16x32_bf16 v[74:77], v[168:171], v[224:227], v[74:77]
	v_mfma_f32_16x16x32_bf16 v[118:121], v[172:175], v[188:191], v[118:121]
	v_mfma_f32_16x16x32_bf16 v[118:121], v[176:179], v[192:195], v[118:121]
	v_mfma_f32_16x16x32_bf16 v[114:117], v[180:183], v[188:191], v[114:117]
	v_mfma_f32_16x16x32_bf16 v[114:117], v[184:187], v[192:195], v[114:117]
	v_mfma_f32_16x16x32_bf16 v[102:105], v[172:175], v[196:199], v[102:105]
	v_mfma_f32_16x16x32_bf16 v[102:105], v[176:179], v[200:203], v[102:105]
	v_mfma_f32_16x16x32_bf16 v[98:101], v[180:183], v[196:199], v[98:101]
	v_mfma_f32_16x16x32_bf16 v[98:101], v[184:187], v[200:203], v[98:101]
	v_mfma_f32_16x16x32_bf16 v[86:89], v[172:175], v[204:207], v[86:89]
	v_mfma_f32_16x16x32_bf16 v[86:89], v[176:179], v[216:219], v[86:89]
	v_mfma_f32_16x16x32_bf16 v[82:85], v[180:183], v[204:207], v[82:85]
	v_mfma_f32_16x16x32_bf16 v[82:85], v[184:187], v[216:219], v[82:85]
	v_mfma_f32_16x16x32_bf16 v[70:73], v[172:175], v[220:223], v[70:73]
	v_mfma_f32_16x16x32_bf16 v[70:73], v[176:179], v[224:227], v[70:73]
	v_mfma_f32_16x16x32_bf16 v[66:69], v[180:183], v[220:223], v[66:69]
	v_mfma_f32_16x16x32_bf16 v[66:69], v[184:187], v[224:227], v[66:69]
	s_barrier
	s_add_i32 s0, s27, s58
	v_lshl_add_u64 v[144:145], v[144:145], 0, s[56:57]
	s_mov_b32 m0, s0
	ds_read_b128 v[188:191], v148 offset:49152
	ds_read_b128 v[192:195], v148 offset:50176
	ds_read_b128 v[196:199], v148 offset:51200
	ds_read_b128 v[200:203], v148 offset:52224
	ds_read_b128 v[204:207], v148 offset:53248
	ds_read_b128 v[216:219], v148 offset:54272
	ds_read_b128 v[220:223], v148 offset:55296
	ds_read_b128 v[224:227], v148 offset:56320
	global_load_lds_dwordx4 v[144:145], off
	s_add_i32 m0, s0, 0x2000
	s_add_u32 s0, s14, 0x158080
	v_lshl_add_u64 v[144:145], v[228:229], 0, s[56:57]
	s_addc_u32 s1, s15, 0
	s_add_i32 s14, s28, s58
	global_load_lds_dwordx4 v[144:145], off
	v_lshl_add_u64 v[144:145], s[0:1], 0, v[158:159]
	s_mov_b32 m0, s14
	s_nop 0
	global_load_lds_dwordx4 v[144:145], off
	v_lshl_add_u64 v[144:145], s[0:1], 0, v[134:135]
	s_add_i32 m0, s14, 0x2000
	s_nop 0
	global_load_lds_dwordx4 v[144:145], off
	v_lshl_add_u64 v[144:145], v[230:231], 0, s[56:57]
	s_mov_b32 m0, s73
	s_nop 0
	global_load_lds_dwordx4 v[144:145], off
	v_lshl_add_u64 v[144:145], v[232:233], 0, s[56:57]
	s_mov_b32 m0, s74
	s_nop 0
	global_load_lds_dwordx4 v[144:145], off
	s_waitcnt vmcnt(8)
	s_waitcnt lgkmcnt(0)
	s_barrier
	s_waitcnt lgkmcnt(0)
	v_mfma_f32_16x16x32_bf16 v[62:65], v[140:143], v[188:191], v[62:65]
	v_mfma_f32_16x16x32_bf16 v[62:65], v[150:153], v[192:195], v[62:65]
	v_mfma_f32_16x16x32_bf16 v[58:61], v[154:157], v[188:191], v[58:61]
	v_mfma_f32_16x16x32_bf16 v[58:61], v[168:171], v[192:195], v[58:61]
	v_mfma_f32_16x16x32_bf16 v[46:49], v[140:143], v[196:199], v[46:49]
	v_mfma_f32_16x16x32_bf16 v[46:49], v[150:153], v[200:203], v[46:49]
	v_mfma_f32_16x16x32_bf16 v[42:45], v[154:157], v[196:199], v[42:45]
	v_mfma_f32_16x16x32_bf16 v[42:45], v[168:171], v[200:203], v[42:45]
	v_mfma_f32_16x16x32_bf16 v[30:33], v[140:143], v[204:207], v[30:33]
	v_mfma_f32_16x16x32_bf16 v[30:33], v[150:153], v[216:219], v[30:33]
	v_mfma_f32_16x16x32_bf16 v[26:29], v[154:157], v[204:207], v[26:29]
	v_mfma_f32_16x16x32_bf16 v[26:29], v[168:171], v[216:219], v[26:29]
	v_mfma_f32_16x16x32_bf16 v[14:17], v[140:143], v[220:223], v[14:17]
	v_mfma_f32_16x16x32_bf16 v[14:17], v[150:153], v[224:227], v[14:17]
	v_mfma_f32_16x16x32_bf16 v[10:13], v[154:157], v[220:223], v[10:13]
	v_mfma_f32_16x16x32_bf16 v[10:13], v[168:171], v[224:227], v[10:13]
	v_mfma_f32_16x16x32_bf16 v[54:57], v[172:175], v[188:191], v[54:57]
	v_mfma_f32_16x16x32_bf16 v[54:57], v[176:179], v[192:195], v[54:57]
	v_mfma_f32_16x16x32_bf16 v[50:53], v[180:183], v[188:191], v[50:53]
	v_mfma_f32_16x16x32_bf16 v[50:53], v[184:187], v[192:195], v[50:53]
	v_mfma_f32_16x16x32_bf16 v[38:41], v[172:175], v[196:199], v[38:41]
	v_mfma_f32_16x16x32_bf16 v[38:41], v[176:179], v[200:203], v[38:41]
	v_mfma_f32_16x16x32_bf16 v[34:37], v[180:183], v[196:199], v[34:37]
	v_mfma_f32_16x16x32_bf16 v[34:37], v[184:187], v[200:203], v[34:37]
	v_mfma_f32_16x16x32_bf16 v[22:25], v[172:175], v[204:207], v[22:25]
	v_mfma_f32_16x16x32_bf16 v[22:25], v[176:179], v[216:219], v[22:25]
	v_mfma_f32_16x16x32_bf16 v[18:21], v[180:183], v[204:207], v[18:21]
	v_mfma_f32_16x16x32_bf16 v[18:21], v[184:187], v[216:219], v[18:21]
	v_mfma_f32_16x16x32_bf16 v[6:9], v[172:175], v[220:223], v[6:9]
	v_mfma_f32_16x16x32_bf16 v[6:9], v[176:179], v[224:227], v[6:9]
	v_mfma_f32_16x16x32_bf16 v[2:5], v[180:183], v[220:223], v[2:5]
	v_mfma_f32_16x16x32_bf16 v[2:5], v[184:187], v[224:227], v[2:5]
	s_barrier
	s_add_i32 s26, s26, 2
	s_add_u32 s24, s24, 0x100
	s_addc_u32 s25, s25, 0
	s_cmpk_gt_u32 s26, 0x53
	s_mov_b64 s[0:1], s[36:37]

.Lsp_LBB0353:
	s_add_u32 s36, s0, 0x100
	s_addc_u32 s37, s1, 0
	s_add_i32 s27, 0, 0x10000
	s_cmpk_eq_i32 s26, 0x52
	s_cselect_b32 s69, s65, s37
	s_cselect_b32 s68, s64, s36
	v_add_u32_e32 v144, s27, v146
	s_cselect_b32 s15, s67, s25
	s_cselect_b32 s14, s66, s24
	s_add_i32 s28, 0, 0x14000
	ds_read_b128 v[140:143], v144
	ds_read_b128 v[150:153], v144 offset:1024
	ds_read_b128 v[154:157], v144 offset:2048
	ds_read_b128 v[168:171], v144 offset:3072
	v_add_u32_e32 v144, s28, v146
	ds_read_b128 v[172:175], v144
	ds_read_b128 v[176:179], v144 offset:1024
	ds_read_b128 v[180:183], v144 offset:2048
	ds_read_b128 v[184:187], v144 offset:3072
	s_add_i32 m0, s59, 0xc000
	ds_read_b128 v[188:191], v148
	ds_read_b128 v[192:195], v148 offset:1024
	ds_read_b128 v[196:199], v148 offset:2048
	ds_read_b128 v[200:203], v148 offset:3072
	ds_read_b128 v[204:207], v148 offset:4096
	ds_read_b128 v[216:219], v148 offset:5120
	ds_read_b128 v[220:223], v148 offset:6144
	ds_read_b128 v[224:227], v148 offset:7168
	global_load_lds_dwordx4 v136, s[0:1]
	s_add_i32 m0, s59, 0xe000
	s_nop 0
	global_load_lds_dwordx4 v138, s[0:1]
	s_waitcnt vmcnt(8)
	s_waitcnt lgkmcnt(0)
	s_barrier
	s_nop 0
	s_waitcnt lgkmcnt(0)
	v_mfma_f32_16x16x32_bf16 v[126:129], v[140:143], v[188:191], v[126:129]
	v_mfma_f32_16x16x32_bf16 v[126:129], v[150:153], v[192:195], v[126:129]
	v_mfma_f32_16x16x32_bf16 v[122:125], v[154:157], v[188:191], v[122:125]
	v_mfma_f32_16x16x32_bf16 v[122:125], v[168:171], v[192:195], v[122:125]
	v_mfma_f32_16x16x32_bf16 v[110:113], v[140:143], v[196:199], v[110:113]
	v_mfma_f32_16x16x32_bf16 v[110:113], v[150:153], v[200:203], v[110:113]
	v_mfma_f32_16x16x32_bf16 v[106:109], v[154:157], v[196:199], v[106:109]
	v_mfma_f32_16x16x32_bf16 v[106:109], v[168:171], v[200:203], v[106:109]
	v_mfma_f32_16x16x32_bf16 v[94:97], v[140:143], v[204:207], v[94:97]
	v_mfma_f32_16x16x32_bf16 v[94:97], v[150:153], v[216:219], v[94:97]
	v_mfma_f32_16x16x32_bf16 v[90:93], v[154:157], v[204:207], v[90:93]
	v_mfma_f32_16x16x32_bf16 v[90:93], v[168:171], v[216:219], v[90:93]
	v_mfma_f32_16x16x32_bf16 v[78:81], v[140:143], v[220:223], v[78:81]
	v_mfma_f32_16x16x32_bf16 v[78:81], v[150:153], v[224:227], v[78:81]
	v_mfma_f32_16x16x32_bf16 v[74:77], v[154:157], v[220:223], v[74:77]
	v_mfma_f32_16x16x32_bf16 v[74:77], v[168:171], v[224:227], v[74:77]
	v_mfma_f32_16x16x32_bf16 v[118:121], v[172:175], v[188:191], v[118:121]
	v_mfma_f32_16x16x32_bf16 v[118:121], v[176:179], v[192:195], v[118:121]
	v_mfma_f32_16x16x32_bf16 v[114:117], v[180:183], v[188:191], v[114:117]
	v_mfma_f32_16x16x32_bf16 v[114:117], v[184:187], v[192:195], v[114:117]
	v_mfma_f32_16x16x32_bf16 v[102:105], v[172:175], v[196:199], v[102:105]
	v_mfma_f32_16x16x32_bf16 v[102:105], v[176:179], v[200:203], v[102:105]
	v_mfma_f32_16x16x32_bf16 v[98:101], v[180:183], v[196:199], v[98:101]
	v_mfma_f32_16x16x32_bf16 v[98:101], v[184:187], v[200:203], v[98:101]
	v_mfma_f32_16x16x32_bf16 v[86:89], v[172:175], v[204:207], v[86:89]
	v_mfma_f32_16x16x32_bf16 v[86:89], v[176:179], v[216:219], v[86:89]
	v_mfma_f32_16x16x32_bf16 v[82:85], v[180:183], v[204:207], v[82:85]
	v_mfma_f32_16x16x32_bf16 v[82:85], v[184:187], v[216:219], v[82:85]
	v_mfma_f32_16x16x32_bf16 v[70:73], v[172:175], v[220:223], v[70:73]
	v_mfma_f32_16x16x32_bf16 v[70:73], v[176:179], v[224:227], v[70:73]
	v_mfma_f32_16x16x32_bf16 v[66:69], v[180:183], v[220:223], v[66:69]
	v_mfma_f32_16x16x32_bf16 v[66:69], v[184:187], v[224:227], v[66:69]
	s_barrier
	s_add_i32 s0, s27, s58
	s_mov_b32 m0, s0
	ds_read_b128 v[188:191], v148 offset:16384
	ds_read_b128 v[192:195], v148 offset:17408
	ds_read_b128 v[196:199], v148 offset:18432
	ds_read_b128 v[200:203], v148 offset:19456
	ds_read_b128 v[204:207], v148 offset:20480
	ds_read_b128 v[216:219], v148 offset:21504
	ds_read_b128 v[220:223], v148 offset:22528
	ds_read_b128 v[224:227], v148 offset:23552
	global_load_lds_dwordx4 v158, s[14:15]
	s_add_i32 m0, s0, 0x2000
	s_add_u32 s0, s14, 0x158000
	s_addc_u32 s1, s15, 0
	s_add_i32 s27, s28, s58
	global_load_lds_dwordx4 v134, s[14:15]
	s_mov_b32 m0, s27
	s_nop 0
	global_load_lds_dwordx4 v158, s[0:1]
	s_add_i32 m0, s27, 0x2000
	s_nop 0
	global_load_lds_dwordx4 v134, s[0:1]
	s_mov_b32 m0, s59
	s_nop 0
	global_load_lds_dwordx4 v130, s[68:69]
	s_mov_b32 m0, s70
	s_nop 0
	global_load_lds_dwordx4 v132, s[68:69]
	s_waitcnt vmcnt(8)
	s_waitcnt lgkmcnt(0)
	s_barrier
	s_waitcnt lgkmcnt(0)
	v_mfma_f32_16x16x32_bf16 v[62:65], v[140:143], v[188:191], v[62:65]
	v_mfma_f32_16x16x32_bf16 v[62:65], v[150:153], v[192:195], v[62:65]
	v_mfma_f32_16x16x32_bf16 v[58:61], v[154:157], v[188:191], v[58:61]
	v_mfma_f32_16x16x32_bf16 v[58:61], v[168:171], v[192:195], v[58:61]
	v_mfma_f32_16x16x32_bf16 v[46:49], v[140:143], v[196:199], v[46:49]
	v_mfma_f32_16x16x32_bf16 v[46:49], v[150:153], v[200:203], v[46:49]
	v_mfma_f32_16x16x32_bf16 v[42:45], v[154:157], v[196:199], v[42:45]
	v_mfma_f32_16x16x32_bf16 v[42:45], v[168:171], v[200:203], v[42:45]
	v_mfma_f32_16x16x32_bf16 v[30:33], v[140:143], v[204:207], v[30:33]
	v_mfma_f32_16x16x32_bf16 v[30:33], v[150:153], v[216:219], v[30:33]
	v_mfma_f32_16x16x32_bf16 v[26:29], v[154:157], v[204:207], v[26:29]
	v_mfma_f32_16x16x32_bf16 v[26:29], v[168:171], v[216:219], v[26:29]
	v_mfma_f32_16x16x32_bf16 v[14:17], v[140:143], v[220:223], v[14:17]
	v_mfma_f32_16x16x32_bf16 v[14:17], v[150:153], v[224:227], v[14:17]
	v_mfma_f32_16x16x32_bf16 v[10:13], v[154:157], v[220:223], v[10:13]
	v_mfma_f32_16x16x32_bf16 v[10:13], v[168:171], v[224:227], v[10:13]
	v_mfma_f32_16x16x32_bf16 v[54:57], v[172:175], v[188:191], v[54:57]
	v_mfma_f32_16x16x32_bf16 v[54:57], v[176:179], v[192:195], v[54:57]
	v_mfma_f32_16x16x32_bf16 v[50:53], v[180:183], v[188:191], v[50:53]
	v_mfma_f32_16x16x32_bf16 v[50:53], v[184:187], v[192:195], v[50:53]
	v_mfma_f32_16x16x32_bf16 v[38:41], v[172:175], v[196:199], v[38:41]
	v_mfma_f32_16x16x32_bf16 v[38:41], v[176:179], v[200:203], v[38:41]
	v_mfma_f32_16x16x32_bf16 v[34:37], v[180:183], v[196:199], v[34:37]
	v_mfma_f32_16x16x32_bf16 v[34:37], v[184:187], v[200:203], v[34:37]
	v_mfma_f32_16x16x32_bf16 v[22:25], v[172:175], v[204:207], v[22:25]
	v_mfma_f32_16x16x32_bf16 v[22:25], v[176:179], v[216:219], v[22:25]
	v_mfma_f32_16x16x32_bf16 v[18:21], v[180:183], v[204:207], v[18:21]
	v_mfma_f32_16x16x32_bf16 v[18:21], v[184:187], v[216:219], v[18:21]
	v_mfma_f32_16x16x32_bf16 v[6:9], v[172:175], v[220:223], v[6:9]
	v_mfma_f32_16x16x32_bf16 v[6:9], v[176:179], v[224:227], v[6:9]
	v_mfma_f32_16x16x32_bf16 v[2:5], v[180:183], v[220:223], v[2:5]
	v_mfma_f32_16x16x32_bf16 v[2:5], v[184:187], v[224:227], v[2:5]
	s_barrier
	s_add_i32 s27, 0, 0x18000
	v_add_u32_e32 v149, s27, v146
	s_add_i32 s28, 0, 0x1c000
	ds_read_b128 v[140:143], v149
	ds_read_b128 v[150:153], v149 offset:1024
	ds_read_b128 v[154:157], v149 offset:2048
	ds_read_b128 v[168:171], v149 offset:3072
	v_add_u32_e32 v149, s28, v146
	ds_read_b128 v[172:175], v149
	ds_read_b128 v[176:179], v149 offset:1024
	ds_read_b128 v[180:183], v149 offset:2048
	ds_read_b128 v[184:187], v149 offset:3072
	s_add_u32 s0, s68, 0x158000
	s_addc_u32 s1, s69, 0
	s_mov_b32 m0, s71
	ds_read_b128 v[188:191], v148 offset:32768
	ds_read_b128 v[192:195], v148 offset:33792
	ds_read_b128 v[196:199], v148 offset:34816
	ds_read_b128 v[200:203], v148 offset:35840
	ds_read_b128 v[204:207], v148 offset:36864
	ds_read_b128 v[216:219], v148 offset:37888
	ds_read_b128 v[220:223], v148 offset:38912
	ds_read_b128 v[224:227], v148 offset:39936
	global_load_lds_dwordx4 v130, s[0:1]
	s_mov_b32 m0, s72
	s_nop 0
	global_load_lds_dwordx4 v132, s[0:1]
	s_waitcnt vmcnt(8)
	s_waitcnt lgkmcnt(0)
	s_barrier
	s_nop 0
	s_waitcnt lgkmcnt(0)
	v_mfma_f32_16x16x32_bf16 v[126:129], v[140:143], v[188:191], v[126:129]
	v_mfma_f32_16x16x32_bf16 v[126:129], v[150:153], v[192:195], v[126:129]
	v_mfma_f32_16x16x32_bf16 v[122:125], v[154:157], v[188:191], v[122:125]
	v_mfma_f32_16x16x32_bf16 v[122:125], v[168:171], v[192:195], v[122:125]
	v_mfma_f32_16x16x32_bf16 v[110:113], v[140:143], v[196:199], v[110:113]
	v_mfma_f32_16x16x32_bf16 v[110:113], v[150:153], v[200:203], v[110:113]
	v_mfma_f32_16x16x32_bf16 v[106:109], v[154:157], v[196:199], v[106:109]
	v_mfma_f32_16x16x32_bf16 v[106:109], v[168:171], v[200:203], v[106:109]
	v_mfma_f32_16x16x32_bf16 v[94:97], v[140:143], v[204:207], v[94:97]
	v_mfma_f32_16x16x32_bf16 v[94:97], v[150:153], v[216:219], v[94:97]
	v_mfma_f32_16x16x32_bf16 v[90:93], v[154:157], v[204:207], v[90:93]
	v_mfma_f32_16x16x32_bf16 v[90:93], v[168:171], v[216:219], v[90:93]
	v_mfma_f32_16x16x32_bf16 v[78:81], v[140:143], v[220:223], v[78:81]
	v_mfma_f32_16x16x32_bf16 v[78:81], v[150:153], v[224:227], v[78:81]
	v_mfma_f32_16x16x32_bf16 v[74:77], v[154:157], v[220:223], v[74:77]
	v_mfma_f32_16x16x32_bf16 v[74:77], v[168:171], v[224:227], v[74:77]
	v_mfma_f32_16x16x32_bf16 v[118:121], v[172:175], v[188:191], v[118:121]
	v_mfma_f32_16x16x32_bf16 v[118:121], v[176:179], v[192:195], v[118:121]
	v_mfma_f32_16x16x32_bf16 v[114:117], v[180:183], v[188:191], v[114:117]
	v_mfma_f32_16x16x32_bf16 v[114:117], v[184:187], v[192:195], v[114:117]
	v_mfma_f32_16x16x32_bf16 v[102:105], v[172:175], v[196:199], v[102:105]
	v_mfma_f32_16x16x32_bf16 v[102:105], v[176:179], v[200:203], v[102:105]
	v_mfma_f32_16x16x32_bf16 v[98:101], v[180:183], v[196:199], v[98:101]
	v_mfma_f32_16x16x32_bf16 v[98:101], v[184:187], v[200:203], v[98:101]
	v_mfma_f32_16x16x32_bf16 v[86:89], v[172:175], v[204:207], v[86:89]
	v_mfma_f32_16x16x32_bf16 v[86:89], v[176:179], v[216:219], v[86:89]
	v_mfma_f32_16x16x32_bf16 v[82:85], v[180:183], v[204:207], v[82:85]
	v_mfma_f32_16x16x32_bf16 v[82:85], v[184:187], v[216:219], v[82:85]
	v_mfma_f32_16x16x32_bf16 v[70:73], v[172:175], v[220:223], v[70:73]
	v_mfma_f32_16x16x32_bf16 v[70:73], v[176:179], v[224:227], v[70:73]
	v_mfma_f32_16x16x32_bf16 v[66:69], v[180:183], v[220:223], v[66:69]
	v_mfma_f32_16x16x32_bf16 v[66:69], v[184:187], v[224:227], v[66:69]
	s_barrier
	s_add_i32 s0, s27, s58
	s_add_u32 s100, s14, 0x80
	s_addc_u32 s101, s15, 0
	s_mov_b32 m0, s0
	ds_read_b128 v[188:191], v148 offset:49152
	ds_read_b128 v[192:195], v148 offset:50176
	ds_read_b128 v[196:199], v148 offset:51200
	ds_read_b128 v[200:203], v148 offset:52224
	ds_read_b128 v[204:207], v148 offset:53248
	ds_read_b128 v[216:219], v148 offset:54272
	ds_read_b128 v[220:223], v148 offset:55296
	ds_read_b128 v[224:227], v148 offset:56320
	global_load_lds_dwordx4 v158, s[100:101]
	s_add_i32 m0, s0, 0x2000
	s_add_u32 s0, s14, 0x158080
	s_addc_u32 s1, s15, 0
	s_add_i32 s14, s28, s58
	global_load_lds_dwordx4 v134, s[100:101]
	s_add_u32 s100, s68, 0x80
	s_addc_u32 s101, s69, 0
	s_mov_b32 m0, s14
	s_nop 0
	global_load_lds_dwordx4 v158, s[0:1]
	s_add_i32 m0, s14, 0x2000
	s_nop 0
	global_load_lds_dwordx4 v134, s[0:1]
	s_mov_b32 m0, s73
	s_nop 0
	global_load_lds_dwordx4 v130, s[100:101]
	s_mov_b32 m0, s74
	s_nop 0
	global_load_lds_dwordx4 v132, s[100:101]
	s_waitcnt vmcnt(8)
	s_waitcnt lgkmcnt(0)
	s_barrier
	s_waitcnt lgkmcnt(0)
	v_mfma_f32_16x16x32_bf16 v[62:65], v[140:143], v[188:191], v[62:65]
	v_mfma_f32_16x16x32_bf16 v[62:65], v[150:153], v[192:195], v[62:65]
	v_mfma_f32_16x16x32_bf16 v[58:61], v[154:157], v[188:191], v[58:61]
	v_mfma_f32_16x16x32_bf16 v[58:61], v[168:171], v[192:195], v[58:61]
	v_mfma_f32_16x16x32_bf16 v[46:49], v[140:143], v[196:199], v[46:49]
	v_mfma_f32_16x16x32_bf16 v[46:49], v[150:153], v[200:203], v[46:49]
	v_mfma_f32_16x16x32_bf16 v[42:45], v[154:157], v[196:199], v[42:45]
	v_mfma_f32_16x16x32_bf16 v[42:45], v[168:171], v[200:203], v[42:45]
	v_mfma_f32_16x16x32_bf16 v[30:33], v[140:143], v[204:207], v[30:33]
	v_mfma_f32_16x16x32_bf16 v[30:33], v[150:153], v[216:219], v[30:33]
	v_mfma_f32_16x16x32_bf16 v[26:29], v[154:157], v[204:207], v[26:29]
	v_mfma_f32_16x16x32_bf16 v[26:29], v[168:171], v[216:219], v[26:29]
	v_mfma_f32_16x16x32_bf16 v[14:17], v[140:143], v[220:223], v[14:17]
	v_mfma_f32_16x16x32_bf16 v[14:17], v[150:153], v[224:227], v[14:17]
	v_mfma_f32_16x16x32_bf16 v[10:13], v[154:157], v[220:223], v[10:13]
	v_mfma_f32_16x16x32_bf16 v[10:13], v[168:171], v[224:227], v[10:13]
	v_mfma_f32_16x16x32_bf16 v[54:57], v[172:175], v[188:191], v[54:57]
	v_mfma_f32_16x16x32_bf16 v[54:57], v[176:179], v[192:195], v[54:57]
	v_mfma_f32_16x16x32_bf16 v[50:53], v[180:183], v[188:191], v[50:53]
	v_mfma_f32_16x16x32_bf16 v[50:53], v[184:187], v[192:195], v[50:53]
	v_mfma_f32_16x16x32_bf16 v[38:41], v[172:175], v[196:199], v[38:41]
	v_mfma_f32_16x16x32_bf16 v[38:41], v[176:179], v[200:203], v[38:41]
	v_mfma_f32_16x16x32_bf16 v[34:37], v[180:183], v[196:199], v[34:37]
	v_mfma_f32_16x16x32_bf16 v[34:37], v[184:187], v[200:203], v[34:37]
	v_mfma_f32_16x16x32_bf16 v[22:25], v[172:175], v[204:207], v[22:25]
	v_mfma_f32_16x16x32_bf16 v[22:25], v[176:179], v[216:219], v[22:25]
	v_mfma_f32_16x16x32_bf16 v[18:21], v[180:183], v[204:207], v[18:21]
	v_mfma_f32_16x16x32_bf16 v[18:21], v[184:187], v[216:219], v[18:21]
	v_mfma_f32_16x16x32_bf16 v[6:9], v[172:175], v[220:223], v[6:9]
	v_mfma_f32_16x16x32_bf16 v[6:9], v[176:179], v[224:227], v[6:9]
	v_mfma_f32_16x16x32_bf16 v[2:5], v[180:183], v[220:223], v[2:5]
	v_mfma_f32_16x16x32_bf16 v[2:5], v[184:187], v[224:227], v[2:5]
	s_barrier
	s_add_i32 s26, s26, 2
	s_add_u32 s24, s24, 0x100
	s_addc_u32 s25, s25, 0
	s_cmpk_gt_u32 s26, 0x53
	s_mov_b64 s[0:1], s[36:37]
	s_cbranch_scc0 .LBB0_353
	s_and_b64 vcc, exec, s[12:13]
	s_cbranch_vccz .LBB0_356
	s_barrier

.LBB0_384:
	s_add_i32 s35, s14, 2
	s_add_u32 s36, s22, 0x100
	s_addc_u32 s37, s23, 0
	s_cmp_lg_u32 s34, s14
	s_cselect_b32 s14, s36, 0
	s_cselect_b32 s15, s37, 0
	s_add_u32 s40, s12, s14
	s_addc_u32 s41, s13, s15
	s_add_i32 s42, 0, 0x10000
	s_add_u32 s14, s0, s14
	v_add_u32_e32 v133, s42, v1
	s_addc_u32 s15, s1, s15
	s_add_i32 s43, 0, 0x14000
	ds_read_b128 v[144:147], v133
	ds_read_b128 v[148:151], v133 offset:1024
	ds_read_b128 v[152:155], v133 offset:2048
	ds_read_b128 v[168:171], v133 offset:3072
	v_add_u32_e32 v133, s43, v1
	ds_read_b128 v[172:175], v133
	ds_read_b128 v[176:179], v133 offset:1024
	ds_read_b128 v[180:183], v133 offset:2048
	ds_read_b128 v[184:187], v133 offset:3072
	v_lshl_add_u64 v[156:157], v[140:141], 0, s[22:23]
	s_add_i32 m0, s17, 0xc000
	ds_read_b128 v[188:191], v131
	ds_read_b128 v[192:195], v131 offset:1024
	ds_read_b128 v[196:199], v131 offset:2048
	ds_read_b128 v[200:203], v131 offset:3072
	ds_read_b128 v[204:207], v131 offset:4096
	ds_read_b128 v[216:219], v131 offset:5120
	ds_read_b128 v[220:223], v131 offset:6144
	ds_read_b128 v[224:227], v131 offset:7168
	global_load_lds_dwordx4 v[156:157], off
	v_lshl_add_u64 v[156:157], v[142:143], 0, s[22:23]
	s_add_i32 m0, s17, 0xe000
	s_nop 0
	global_load_lds_dwordx4 v[156:157], off
	s_waitcnt vmcnt(8)
	s_waitcnt lgkmcnt(0)
	s_barrier
	s_nop 0
	s_setprio 1
	s_waitcnt lgkmcnt(0)
	v_mfma_f32_16x16x32_bf16 v[126:129], v[144:147], v[188:191], v[126:129]
	v_mfma_f32_16x16x32_bf16 v[126:129], v[148:151], v[192:195], v[126:129]
	v_mfma_f32_16x16x32_bf16 v[122:125], v[152:155], v[188:191], v[122:125]
	v_mfma_f32_16x16x32_bf16 v[122:125], v[168:171], v[192:195], v[122:125]
	v_mfma_f32_16x16x32_bf16 v[110:113], v[144:147], v[196:199], v[110:113]
	v_mfma_f32_16x16x32_bf16 v[110:113], v[148:151], v[200:203], v[110:113]
	v_mfma_f32_16x16x32_bf16 v[106:109], v[152:155], v[196:199], v[106:109]
	v_mfma_f32_16x16x32_bf16 v[106:109], v[168:171], v[200:203], v[106:109]
	v_mfma_f32_16x16x32_bf16 v[94:97], v[144:147], v[204:207], v[94:97]
	v_mfma_f32_16x16x32_bf16 v[94:97], v[148:151], v[216:219], v[94:97]
	v_mfma_f32_16x16x32_bf16 v[90:93], v[152:155], v[204:207], v[90:93]
	v_mfma_f32_16x16x32_bf16 v[90:93], v[168:171], v[216:219], v[90:93]
	v_mfma_f32_16x16x32_bf16 v[78:81], v[144:147], v[220:223], v[78:81]
	v_mfma_f32_16x16x32_bf16 v[78:81], v[148:151], v[224:227], v[78:81]
	v_mfma_f32_16x16x32_bf16 v[74:77], v[152:155], v[220:223], v[74:77]
	v_mfma_f32_16x16x32_bf16 v[74:77], v[168:171], v[224:227], v[74:77]
	s_setprio 0
	s_setprio 1
	v_mfma_f32_16x16x32_bf16 v[118:121], v[172:175], v[188:191], v[118:121]
	v_mfma_f32_16x16x32_bf16 v[118:121], v[176:179], v[192:195], v[118:121]
	v_mfma_f32_16x16x32_bf16 v[114:117], v[180:183], v[188:191], v[114:117]
	v_mfma_f32_16x16x32_bf16 v[114:117], v[184:187], v[192:195], v[114:117]
	v_mfma_f32_16x16x32_bf16 v[102:105], v[172:175], v[196:199], v[102:105]
	v_mfma_f32_16x16x32_bf16 v[102:105], v[176:179], v[200:203], v[102:105]
	v_mfma_f32_16x16x32_bf16 v[98:101], v[180:183], v[196:199], v[98:101]
	v_mfma_f32_16x16x32_bf16 v[98:101], v[184:187], v[200:203], v[98:101]
	v_mfma_f32_16x16x32_bf16 v[86:89], v[172:175], v[204:207], v[86:89]
	v_mfma_f32_16x16x32_bf16 v[86:89], v[176:179], v[216:219], v[86:89]
	v_mfma_f32_16x16x32_bf16 v[82:85], v[180:183], v[204:207], v[82:85]
	v_mfma_f32_16x16x32_bf16 v[82:85], v[184:187], v[216:219], v[82:85]
	v_mfma_f32_16x16x32_bf16 v[70:73], v[172:175], v[220:223], v[70:73]
	v_mfma_f32_16x16x32_bf16 v[70:73], v[176:179], v[224:227], v[70:73]
	v_mfma_f32_16x16x32_bf16 v[66:69], v[180:183], v[220:223], v[66:69]
	v_mfma_f32_16x16x32_bf16 v[66:69], v[184:187], v[224:227], v[66:69]
	s_setprio 0
	s_barrier
	s_add_i32 s22, s42, s25
	v_lshl_add_u64 v[156:157], s[14:15], 0, v[158:159]
	s_mov_b32 m0, s22
	ds_read_b128 v[188:191], v131 offset:16384
	ds_read_b128 v[192:195], v131 offset:17408
	ds_read_b128 v[196:199], v131 offset:18432
	ds_read_b128 v[200:203], v131 offset:19456
	ds_read_b128 v[204:207], v131 offset:20480
	ds_read_b128 v[216:219], v131 offset:21504
	ds_read_b128 v[220:223], v131 offset:22528
	ds_read_b128 v[224:227], v131 offset:23552
	global_load_lds_dwordx4 v[156:157], off
	s_add_i32 m0, s22, 0x2000
	s_add_u32 s22, s14, 0x158000
	v_lshl_add_u64 v[228:229], s[14:15], 0, v[134:135]
	s_addc_u32 s23, s15, 0
	s_add_i32 s42, s43, s25
	global_load_lds_dwordx4 v[228:229], off
	v_lshl_add_u64 v[230:231], s[22:23], 0, v[158:159]
	s_mov_b32 m0, s42
	v_lshl_add_u64 v[232:233], s[40:41], 0, v[136:137]
	global_load_lds_dwordx4 v[230:231], off
	v_lshl_add_u64 v[230:231], s[22:23], 0, v[134:135]
	s_add_i32 m0, s42, 0x2000
	s_nop 0
	global_load_lds_dwordx4 v[230:231], off
	v_lshl_add_u64 v[230:231], s[40:41], 0, v[138:139]
	s_mov_b32 m0, s17
	s_nop 0
	global_load_lds_dwordx4 v[230:231], off
	s_mov_b32 m0, s26
	s_nop 0
	global_load_lds_dwordx4 v[232:233], off
	s_waitcnt vmcnt(8)
	s_waitcnt lgkmcnt(0)
	s_barrier
	s_nop 0
	s_setprio 1
	s_waitcnt lgkmcnt(0)
	v_mfma_f32_16x16x32_bf16 v[62:65], v[144:147], v[188:191], v[62:65]
	v_mfma_f32_16x16x32_bf16 v[62:65], v[148:151], v[192:195], v[62:65]
	v_mfma_f32_16x16x32_bf16 v[58:61], v[152:155], v[188:191], v[58:61]
	v_mfma_f32_16x16x32_bf16 v[58:61], v[168:171], v[192:195], v[58:61]
	v_mfma_f32_16x16x32_bf16 v[46:49], v[144:147], v[196:199], v[46:49]
	v_mfma_f32_16x16x32_bf16 v[46:49], v[148:151], v[200:203], v[46:49]
	v_mfma_f32_16x16x32_bf16 v[42:45], v[152:155], v[196:199], v[42:45]
	v_mfma_f32_16x16x32_bf16 v[42:45], v[168:171], v[200:203], v[42:45]
	v_mfma_f32_16x16x32_bf16 v[30:33], v[144:147], v[204:207], v[30:33]
	v_mfma_f32_16x16x32_bf16 v[30:33], v[148:151], v[216:219], v[30:33]
	v_mfma_f32_16x16x32_bf16 v[26:29], v[152:155], v[204:207], v[26:29]
	v_mfma_f32_16x16x32_bf16 v[26:29], v[168:171], v[216:219], v[26:29]
	v_mfma_f32_16x16x32_bf16 v[14:17], v[144:147], v[220:223], v[14:17]
	v_mfma_f32_16x16x32_bf16 v[14:17], v[148:151], v[224:227], v[14:17]
	v_mfma_f32_16x16x32_bf16 v[10:13], v[152:155], v[220:223], v[10:13]
	v_mfma_f32_16x16x32_bf16 v[10:13], v[168:171], v[224:227], v[10:13]
	s_setprio 0
	s_setprio 1
	v_mfma_f32_16x16x32_bf16 v[54:57], v[172:175], v[188:191], v[54:57]
	v_mfma_f32_16x16x32_bf16 v[54:57], v[176:179], v[192:195], v[54:57]
	v_mfma_f32_16x16x32_bf16 v[50:53], v[180:183], v[188:191], v[50:53]
	v_mfma_f32_16x16x32_bf16 v[50:53], v[184:187], v[192:195], v[50:53]
	v_mfma_f32_16x16x32_bf16 v[38:41], v[172:175], v[196:199], v[38:41]
	v_mfma_f32_16x16x32_bf16 v[38:41], v[176:179], v[200:203], v[38:41]
	v_mfma_f32_16x16x32_bf16 v[34:37], v[180:183], v[196:199], v[34:37]
	v_mfma_f32_16x16x32_bf16 v[34:37], v[184:187], v[200:203], v[34:37]
	v_mfma_f32_16x16x32_bf16 v[22:25], v[172:175], v[204:207], v[22:25]
	v_mfma_f32_16x16x32_bf16 v[22:25], v[176:179], v[216:219], v[22:25]
	v_mfma_f32_16x16x32_bf16 v[18:21], v[180:183], v[204:207], v[18:21]
	v_mfma_f32_16x16x32_bf16 v[18:21], v[184:187], v[216:219], v[18:21]
	v_mfma_f32_16x16x32_bf16 v[6:9], v[172:175], v[220:223], v[6:9]
	v_mfma_f32_16x16x32_bf16 v[6:9], v[176:179], v[224:227], v[6:9]
	v_mfma_f32_16x16x32_bf16 v[2:5], v[180:183], v[220:223], v[2:5]
	v_mfma_f32_16x16x32_bf16 v[2:5], v[184:187], v[224:227], v[2:5]
	s_setprio 0
	s_barrier
	s_add_i32 s42, 0, 0x18000
	v_add_u32_e32 v133, s42, v1
	s_add_i32 s43, 0, 0x1c000
	ds_read_b128 v[144:147], v133
	ds_read_b128 v[148:151], v133 offset:1024
	ds_read_b128 v[152:155], v133 offset:2048
	ds_read_b128 v[168:171], v133 offset:3072
	v_add_u32_e32 v133, s43, v1
	ds_read_b128 v[172:175], v133
	ds_read_b128 v[176:179], v133 offset:1024
	ds_read_b128 v[180:183], v133 offset:2048
	ds_read_b128 v[184:187], v133 offset:3072
	s_add_u32 s22, s40, 0x158000
	s_addc_u32 s23, s41, 0
	s_mov_b32 m0, s27
	v_lshl_add_u64 v[234:235], s[22:23], 0, v[138:139]
	ds_read_b128 v[188:191], v131 offset:32768
	ds_read_b128 v[192:195], v131 offset:33792
	ds_read_b128 v[196:199], v131 offset:34816
	ds_read_b128 v[200:203], v131 offset:35840
	ds_read_b128 v[204:207], v131 offset:36864
	ds_read_b128 v[216:219], v131 offset:37888
	ds_read_b128 v[220:223], v131 offset:38912
	ds_read_b128 v[224:227], v131 offset:39936
	global_load_lds_dwordx4 v[234:235], off
	v_lshl_add_u64 v[234:235], s[22:23], 0, v[136:137]
	s_mov_b32 m0, s28
	s_nop 0
	global_load_lds_dwordx4 v[234:235], off
	s_waitcnt vmcnt(8)
	s_waitcnt lgkmcnt(0)
	s_barrier
	s_nop 0
	s_setprio 1
	s_waitcnt lgkmcnt(0)
	v_mfma_f32_16x16x32_bf16 v[126:129], v[144:147], v[188:191], v[126:129]
	v_mfma_f32_16x16x32_bf16 v[126:129], v[148:151], v[192:195], v[126:129]
	v_mfma_f32_16x16x32_bf16 v[122:125], v[152:155], v[188:191], v[122:125]
	v_mfma_f32_16x16x32_bf16 v[122:125], v[168:171], v[192:195], v[122:125]
	v_mfma_f32_16x16x32_bf16 v[110:113], v[144:147], v[196:199], v[110:113]
	v_mfma_f32_16x16x32_bf16 v[110:113], v[148:151], v[200:203], v[110:113]
	v_mfma_f32_16x16x32_bf16 v[106:109], v[152:155], v[196:199], v[106:109]
	v_mfma_f32_16x16x32_bf16 v[106:109], v[168:171], v[200:203], v[106:109]
	v_mfma_f32_16x16x32_bf16 v[94:97], v[144:147], v[204:207], v[94:97]
	v_mfma_f32_16x16x32_bf16 v[94:97], v[148:151], v[216:219], v[94:97]
	v_mfma_f32_16x16x32_bf16 v[90:93], v[152:155], v[204:207], v[90:93]
	v_mfma_f32_16x16x32_bf16 v[90:93], v[168:171], v[216:219], v[90:93]
	v_mfma_f32_16x16x32_bf16 v[78:81], v[144:147], v[220:223], v[78:81]
	v_mfma_f32_16x16x32_bf16 v[78:81], v[148:151], v[224:227], v[78:81]
	v_mfma_f32_16x16x32_bf16 v[74:77], v[152:155], v[220:223], v[74:77]
	v_mfma_f32_16x16x32_bf16 v[74:77], v[168:171], v[224:227], v[74:77]
	s_setprio 0
	s_setprio 1
	v_mfma_f32_16x16x32_bf16 v[118:121], v[172:175], v[188:191], v[118:121]
	v_mfma_f32_16x16x32_bf16 v[118:121], v[176:179], v[192:195], v[118:121]
	v_mfma_f32_16x16x32_bf16 v[114:117], v[180:183], v[188:191], v[114:117]
	v_mfma_f32_16x16x32_bf16 v[114:117], v[184:187], v[192:195], v[114:117]
	v_mfma_f32_16x16x32_bf16 v[102:105], v[172:175], v[196:199], v[102:105]
	v_mfma_f32_16x16x32_bf16 v[102:105], v[176:179], v[200:203], v[102:105]
	v_mfma_f32_16x16x32_bf16 v[98:101], v[180:183], v[196:199], v[98:101]
	v_mfma_f32_16x16x32_bf16 v[98:101], v[184:187], v[200:203], v[98:101]
	v_mfma_f32_16x16x32_bf16 v[86:89], v[172:175], v[204:207], v[86:89]
	v_mfma_f32_16x16x32_bf16 v[86:89], v[176:179], v[216:219], v[86:89]
	v_mfma_f32_16x16x32_bf16 v[82:85], v[180:183], v[204:207], v[82:85]
	v_mfma_f32_16x16x32_bf16 v[82:85], v[184:187], v[216:219], v[82:85]
	v_mfma_f32_16x16x32_bf16 v[70:73], v[172:175], v[220:223], v[70:73]
	v_mfma_f32_16x16x32_bf16 v[70:73], v[176:179], v[224:227], v[70:73]
	v_mfma_f32_16x16x32_bf16 v[66:69], v[180:183], v[220:223], v[66:69]
	v_mfma_f32_16x16x32_bf16 v[66:69], v[184:187], v[224:227], v[66:69]
	s_setprio 0
	s_barrier
	s_add_i32 s22, s42, s25
	v_lshl_add_u64 v[156:157], v[156:157], 0, s[56:57]
	s_mov_b32 m0, s22
	ds_read_b128 v[188:191], v131 offset:49152
	ds_read_b128 v[192:195], v131 offset:50176
	ds_read_b128 v[196:199], v131 offset:51200
	ds_read_b128 v[200:203], v131 offset:52224
	ds_read_b128 v[204:207], v131 offset:53248
	ds_read_b128 v[216:219], v131 offset:54272
	ds_read_b128 v[220:223], v131 offset:55296
	ds_read_b128 v[224:227], v131 offset:56320
	global_load_lds_dwordx4 v[156:157], off
	s_add_i32 m0, s22, 0x2000
	s_add_u32 s14, s14, 0x158080
	v_lshl_add_u64 v[156:157], v[228:229], 0, s[56:57]
	s_addc_u32 s15, s15, 0
	s_add_i32 s22, s43, s25
	global_load_lds_dwordx4 v[156:157], off
	v_lshl_add_u64 v[156:157], s[14:15], 0, v[158:159]
	s_mov_b32 m0, s22
	s_nop 0
	global_load_lds_dwordx4 v[156:157], off
	v_lshl_add_u64 v[156:157], s[14:15], 0, v[134:135]
	s_add_i32 m0, s22, 0x2000
	s_nop 0
	global_load_lds_dwordx4 v[156:157], off
	v_lshl_add_u64 v[156:157], v[230:231], 0, s[56:57]
	s_mov_b32 m0, s29
	s_nop 0
	global_load_lds_dwordx4 v[156:157], off
	v_lshl_add_u64 v[156:157], v[232:233], 0, s[56:57]
	s_mov_b32 m0, s30
	s_nop 0
	global_load_lds_dwordx4 v[156:157], off
	s_waitcnt vmcnt(8)
	s_waitcnt lgkmcnt(0)
	s_barrier
	s_setprio 1
	s_waitcnt lgkmcnt(0)
	v_mfma_f32_16x16x32_bf16 v[62:65], v[144:147], v[188:191], v[62:65]
	v_mfma_f32_16x16x32_bf16 v[62:65], v[148:151], v[192:195], v[62:65]
	v_mfma_f32_16x16x32_bf16 v[58:61], v[152:155], v[188:191], v[58:61]
	v_mfma_f32_16x16x32_bf16 v[58:61], v[168:171], v[192:195], v[58:61]
	v_mfma_f32_16x16x32_bf16 v[46:49], v[144:147], v[196:199], v[46:49]
	v_mfma_f32_16x16x32_bf16 v[46:49], v[148:151], v[200:203], v[46:49]
	v_mfma_f32_16x16x32_bf16 v[42:45], v[152:155], v[196:199], v[42:45]
	v_mfma_f32_16x16x32_bf16 v[42:45], v[168:171], v[200:203], v[42:45]
	v_mfma_f32_16x16x32_bf16 v[30:33], v[144:147], v[204:207], v[30:33]
	v_mfma_f32_16x16x32_bf16 v[30:33], v[148:151], v[216:219], v[30:33]
	v_mfma_f32_16x16x32_bf16 v[26:29], v[152:155], v[204:207], v[26:29]
	v_mfma_f32_16x16x32_bf16 v[26:29], v[168:171], v[216:219], v[26:29]
	v_mfma_f32_16x16x32_bf16 v[14:17], v[144:147], v[220:223], v[14:17]
	v_mfma_f32_16x16x32_bf16 v[14:17], v[148:151], v[224:227], v[14:17]
	v_mfma_f32_16x16x32_bf16 v[10:13], v[152:155], v[220:223], v[10:13]
	v_mfma_f32_16x16x32_bf16 v[10:13], v[168:171], v[224:227], v[10:13]
	s_setprio 0
	s_setprio 1
	v_mfma_f32_16x16x32_bf16 v[54:57], v[172:175], v[188:191], v[54:57]
	v_mfma_f32_16x16x32_bf16 v[54:57], v[176:179], v[192:195], v[54:57]
	v_mfma_f32_16x16x32_bf16 v[50:53], v[180:183], v[188:191], v[50:53]
	v_mfma_f32_16x16x32_bf16 v[50:53], v[184:187], v[192:195], v[50:53]
	v_mfma_f32_16x16x32_bf16 v[38:41], v[172:175], v[196:199], v[38:41]
	v_mfma_f32_16x16x32_bf16 v[38:41], v[176:179], v[200:203], v[38:41]
	v_mfma_f32_16x16x32_bf16 v[34:37], v[180:183], v[196:199], v[34:37]
	v_mfma_f32_16x16x32_bf16 v[34:37], v[184:187], v[200:203], v[34:37]
	v_mfma_f32_16x16x32_bf16 v[22:25], v[172:175], v[204:207], v[22:25]
	v_mfma_f32_16x16x32_bf16 v[22:25], v[176:179], v[216:219], v[22:25]
	v_mfma_f32_16x16x32_bf16 v[18:21], v[180:183], v[204:207], v[18:21]
	v_mfma_f32_16x16x32_bf16 v[18:21], v[184:187], v[216:219], v[18:21]
	v_mfma_f32_16x16x32_bf16 v[6:9], v[172:175], v[220:223], v[6:9]
	v_mfma_f32_16x16x32_bf16 v[6:9], v[176:179], v[224:227], v[6:9]
	v_mfma_f32_16x16x32_bf16 v[2:5], v[180:183], v[220:223], v[2:5]
	v_mfma_f32_16x16x32_bf16 v[2:5], v[184:187], v[224:227], v[2:5]
	s_setprio 0
	s_barrier
	s_cmp_ge_i32 s35, s31
	s_mov_b64 s[22:23], s[36:37]
	s_mov_b32 s14, s35
	s_cbranch_scc0 .LBB0_384
	s_cmpk_lt_u32 s10, 0x100
	s_cbranch_scc0 .LBB0_387

.Lsp_LBB0715_plp715:
	s_add_u32 s14, s66, 0xfff80080
	s_addc_u32 s15, s67, -1
	s_add_i32 s24, 0, 0x10000
	s_cmp_eq_u32 s17, 28
	s_cselect_b32 s69, s49, s15
	s_cselect_b32 s68, s48, s14
	v_add_u32_e32 v147, s24, v144
	s_cselect_b32 s15, s1, s16
	s_cselect_b32 s14, s10, s11
	s_add_i32 s26, 0, 0x14000
	ds_read_b128 v[140:143], v147
	ds_read_b128 v[148:151], v147 offset:1024
	ds_read_b128 v[152:155], v147 offset:2048
	ds_read_b128 v[168:171], v147 offset:3072
	v_add_u32_e32 v147, s26, v144
	ds_read_b128 v[172:175], v147
	ds_read_b128 v[176:179], v147 offset:1024
	ds_read_b128 v[180:183], v147 offset:2048
	ds_read_b128 v[184:187], v147 offset:3072
	v_lshl_add_u64 v[156:157], s[66:67], 0, v[136:137]
	s_add_i32 m0, s65, 0xc000
	ds_read_b128 v[188:191], v146
	ds_read_b128 v[192:195], v146 offset:1024
	ds_read_b128 v[196:199], v146 offset:2048
	ds_read_b128 v[200:203], v146 offset:3072
	ds_read_b128 v[204:207], v146 offset:4096
	ds_read_b128 v[216:219], v146 offset:5120
	ds_read_b128 v[220:223], v146 offset:6144
	ds_read_b128 v[224:227], v146 offset:7168
	global_load_lds_dwordx4 v[156:157], off
	v_lshl_add_u64 v[156:157], s[66:67], 0, v[138:139]
	s_add_i32 m0, s65, 0xe000
	s_nop 0
	global_load_lds_dwordx4 v[156:157], off
	s_waitcnt vmcnt(8)
	s_waitcnt lgkmcnt(0)
	s_barrier
	s_nop 0
	s_waitcnt lgkmcnt(0)
	v_mfma_f32_16x16x32_bf16 v[126:129], v[140:143], v[188:191], 0
	v_mfma_f32_16x16x32_bf16 v[126:129], v[148:151], v[192:195], v[126:129]
	v_mfma_f32_16x16x32_bf16 v[118:121], v[152:155], v[188:191], 0
	v_mfma_f32_16x16x32_bf16 v[118:121], v[168:171], v[192:195], v[118:121]
	v_mfma_f32_16x16x32_bf16 v[106:109], v[140:143], v[196:199], 0
	v_mfma_f32_16x16x32_bf16 v[106:109], v[148:151], v[200:203], v[106:109]
	v_mfma_f32_16x16x32_bf16 v[98:101], v[152:155], v[196:199], 0
	v_mfma_f32_16x16x32_bf16 v[98:101], v[168:171], v[200:203], v[98:101]
	v_mfma_f32_16x16x32_bf16 v[90:93], v[140:143], v[204:207], 0
	v_mfma_f32_16x16x32_bf16 v[90:93], v[148:151], v[216:219], v[90:93]
	v_mfma_f32_16x16x32_bf16 v[82:85], v[152:155], v[204:207], 0
	v_mfma_f32_16x16x32_bf16 v[82:85], v[168:171], v[216:219], v[82:85]
	v_mfma_f32_16x16x32_bf16 v[74:77], v[140:143], v[220:223], 0
	v_mfma_f32_16x16x32_bf16 v[74:77], v[148:151], v[224:227], v[74:77]
	v_mfma_f32_16x16x32_bf16 v[66:69], v[152:155], v[220:223], 0
	v_mfma_f32_16x16x32_bf16 v[66:69], v[168:171], v[224:227], v[66:69]
	v_mfma_f32_16x16x32_bf16 v[122:125], v[172:175], v[188:191], 0
	v_mfma_f32_16x16x32_bf16 v[122:125], v[176:179], v[192:195], v[122:125]
	v_mfma_f32_16x16x32_bf16 v[114:117], v[180:183], v[188:191], 0
	v_mfma_f32_16x16x32_bf16 v[114:117], v[184:187], v[192:195], v[114:117]
	v_mfma_f32_16x16x32_bf16 v[110:113], v[172:175], v[196:199], 0
	v_mfma_f32_16x16x32_bf16 v[110:113], v[176:179], v[200:203], v[110:113]
	v_mfma_f32_16x16x32_bf16 v[102:105], v[180:183], v[196:199], 0
	v_mfma_f32_16x16x32_bf16 v[102:105], v[184:187], v[200:203], v[102:105]
	v_mfma_f32_16x16x32_bf16 v[94:97], v[172:175], v[204:207], 0
	v_mfma_f32_16x16x32_bf16 v[94:97], v[176:179], v[216:219], v[94:97]
	v_mfma_f32_16x16x32_bf16 v[86:89], v[180:183], v[204:207], 0
	v_mfma_f32_16x16x32_bf16 v[86:89], v[184:187], v[216:219], v[86:89]
	v_mfma_f32_16x16x32_bf16 v[78:81], v[172:175], v[220:223], 0
	v_mfma_f32_16x16x32_bf16 v[78:81], v[176:179], v[224:227], v[78:81]
	v_mfma_f32_16x16x32_bf16 v[70:73], v[180:183], v[220:223], 0
	v_mfma_f32_16x16x32_bf16 v[70:73], v[184:187], v[224:227], v[70:73]
	s_barrier
	s_add_i32 s24, s24, s59
	v_lshl_add_u64 v[156:157], s[14:15], 0, v[158:159]
	s_mov_b32 m0, s24
	ds_read_b128 v[188:191], v146 offset:16384
	ds_read_b128 v[192:195], v146 offset:17408
	ds_read_b128 v[196:199], v146 offset:18432
	ds_read_b128 v[200:203], v146 offset:19456
	ds_read_b128 v[204:207], v146 offset:20480
	ds_read_b128 v[216:219], v146 offset:21504
	ds_read_b128 v[220:223], v146 offset:22528
	ds_read_b128 v[224:227], v146 offset:23552
	global_load_lds_dwordx4 v[156:157], off
	s_add_i32 m0, s24, 0x2000
	s_add_u32 s24, s14, 0x80000
	v_lshl_add_u64 v[228:229], s[14:15], 0, v[134:135]
	s_addc_u32 s25, s15, 0
	s_add_i32 s26, s26, s59
	global_load_lds_dwordx4 v[228:229], off
	v_lshl_add_u64 v[230:231], s[24:25], 0, v[158:159]
	s_mov_b32 m0, s26
	v_lshl_add_u64 v[232:233], s[68:69], 0, v[132:133]
	global_load_lds_dwordx4 v[230:231], off
	v_lshl_add_u64 v[230:231], s[24:25], 0, v[134:135]
	s_add_i32 m0, s26, 0x2000
	s_nop 0
	global_load_lds_dwordx4 v[230:231], off
	v_lshl_add_u64 v[230:231], s[68:69], 0, v[130:131]
	s_mov_b32 m0, s65
	s_nop 0
	global_load_lds_dwordx4 v[230:231], off
	s_mov_b32 m0, s70
	s_nop 0
	global_load_lds_dwordx4 v[232:233], off
	s_waitcnt vmcnt(8)
	s_waitcnt lgkmcnt(0)
	s_barrier
	s_nop 0
	s_waitcnt lgkmcnt(0)
	v_mfma_f32_16x16x32_bf16 v[58:61], v[140:143], v[188:191], 0
	v_mfma_f32_16x16x32_bf16 v[58:61], v[148:151], v[192:195], v[58:61]
	v_mfma_f32_16x16x32_bf16 v[50:53], v[152:155], v[188:191], 0
	v_mfma_f32_16x16x32_bf16 v[50:53], v[168:171], v[192:195], v[50:53]
	v_mfma_f32_16x16x32_bf16 v[42:45], v[140:143], v[196:199], 0
	v_mfma_f32_16x16x32_bf16 v[42:45], v[148:151], v[200:203], v[42:45]
	v_mfma_f32_16x16x32_bf16 v[34:37], v[152:155], v[196:199], 0
	v_mfma_f32_16x16x32_bf16 v[34:37], v[168:171], v[200:203], v[34:37]
	v_mfma_f32_16x16x32_bf16 v[26:29], v[140:143], v[204:207], 0
	v_mfma_f32_16x16x32_bf16 v[26:29], v[148:151], v[216:219], v[26:29]
	v_mfma_f32_16x16x32_bf16 v[18:21], v[152:155], v[204:207], 0
	v_mfma_f32_16x16x32_bf16 v[18:21], v[168:171], v[216:219], v[18:21]
	v_mfma_f32_16x16x32_bf16 v[10:13], v[140:143], v[220:223], 0
	v_mfma_f32_16x16x32_bf16 v[10:13], v[148:151], v[224:227], v[10:13]
	v_mfma_f32_16x16x32_bf16 v[2:5], v[152:155], v[220:223], 0
	v_mfma_f32_16x16x32_bf16 v[2:5], v[168:171], v[224:227], v[2:5]
	v_mfma_f32_16x16x32_bf16 v[62:65], v[172:175], v[188:191], 0
	v_mfma_f32_16x16x32_bf16 v[62:65], v[176:179], v[192:195], v[62:65]
	v_mfma_f32_16x16x32_bf16 v[54:57], v[180:183], v[188:191], 0
	v_mfma_f32_16x16x32_bf16 v[54:57], v[184:187], v[192:195], v[54:57]
	v_mfma_f32_16x16x32_bf16 v[46:49], v[172:175], v[196:199], 0
	v_mfma_f32_16x16x32_bf16 v[46:49], v[176:179], v[200:203], v[46:49]
	v_mfma_f32_16x16x32_bf16 v[38:41], v[180:183], v[196:199], 0
	v_mfma_f32_16x16x32_bf16 v[38:41], v[184:187], v[200:203], v[38:41]
	v_mfma_f32_16x16x32_bf16 v[30:33], v[172:175], v[204:207], 0
	v_mfma_f32_16x16x32_bf16 v[30:33], v[176:179], v[216:219], v[30:33]
	v_mfma_f32_16x16x32_bf16 v[22:25], v[180:183], v[204:207], 0
	v_mfma_f32_16x16x32_bf16 v[22:25], v[184:187], v[216:219], v[22:25]
	v_mfma_f32_16x16x32_bf16 v[14:17], v[172:175], v[220:223], 0
	v_mfma_f32_16x16x32_bf16 v[14:17], v[176:179], v[224:227], v[14:17]
	v_mfma_f32_16x16x32_bf16 v[6:9], v[180:183], v[220:223], 0
	v_mfma_f32_16x16x32_bf16 v[6:9], v[184:187], v[224:227], v[6:9]
	s_barrier
	s_add_i32 s26, 0, 0x18000
	v_add_u32_e32 v147, s26, v144
	s_add_i32 s27, 0, 0x1c000
	ds_read_b128 v[140:143], v147
	ds_read_b128 v[148:151], v147 offset:1024
	ds_read_b128 v[152:155], v147 offset:2048
	ds_read_b128 v[168:171], v147 offset:3072
	v_add_u32_e32 v147, s27, v144
	ds_read_b128 v[172:175], v147
	ds_read_b128 v[176:179], v147 offset:1024
	ds_read_b128 v[180:183], v147 offset:2048
	ds_read_b128 v[184:187], v147 offset:3072
	s_add_u32 s24, s68, 0x80000
	s_addc_u32 s25, s69, 0
	s_mov_b32 m0, s71
	v_lshl_add_u64 v[234:235], s[24:25], 0, v[130:131]
	ds_read_b128 v[188:191], v146 offset:32768
	ds_read_b128 v[192:195], v146 offset:33792
	ds_read_b128 v[196:199], v146 offset:34816
	ds_read_b128 v[200:203], v146 offset:35840
	ds_read_b128 v[204:207], v146 offset:36864
	ds_read_b128 v[216:219], v146 offset:37888
	ds_read_b128 v[220:223], v146 offset:38912
	ds_read_b128 v[224:227], v146 offset:39936
	global_load_lds_dwordx4 v[234:235], off
	v_lshl_add_u64 v[234:235], s[24:25], 0, v[132:133]
	s_mov_b32 m0, s72
	s_nop 0
	global_load_lds_dwordx4 v[234:235], off
	s_waitcnt vmcnt(8)
	s_waitcnt lgkmcnt(0)
	s_barrier
	s_nop 0
	s_waitcnt lgkmcnt(0)
	v_mfma_f32_16x16x32_bf16 v[126:129], v[140:143], v[188:191], v[126:129]
	v_mfma_f32_16x16x32_bf16 v[126:129], v[148:151], v[192:195], v[126:129]
	v_mfma_f32_16x16x32_bf16 v[118:121], v[152:155], v[188:191], v[118:121]
	v_mfma_f32_16x16x32_bf16 v[118:121], v[168:171], v[192:195], v[118:121]
	v_mfma_f32_16x16x32_bf16 v[106:109], v[140:143], v[196:199], v[106:109]
	v_mfma_f32_16x16x32_bf16 v[106:109], v[148:151], v[200:203], v[106:109]
	v_mfma_f32_16x16x32_bf16 v[98:101], v[152:155], v[196:199], v[98:101]
	v_mfma_f32_16x16x32_bf16 v[98:101], v[168:171], v[200:203], v[98:101]
	v_mfma_f32_16x16x32_bf16 v[90:93], v[140:143], v[204:207], v[90:93]
	v_mfma_f32_16x16x32_bf16 v[90:93], v[148:151], v[216:219], v[90:93]
	v_mfma_f32_16x16x32_bf16 v[82:85], v[152:155], v[204:207], v[82:85]
	v_mfma_f32_16x16x32_bf16 v[82:85], v[168:171], v[216:219], v[82:85]
	v_mfma_f32_16x16x32_bf16 v[74:77], v[140:143], v[220:223], v[74:77]
	v_mfma_f32_16x16x32_bf16 v[74:77], v[148:151], v[224:227], v[74:77]
	v_mfma_f32_16x16x32_bf16 v[66:69], v[152:155], v[220:223], v[66:69]
	v_mfma_f32_16x16x32_bf16 v[66:69], v[168:171], v[224:227], v[66:69]
	v_mfma_f32_16x16x32_bf16 v[122:125], v[172:175], v[188:191], v[122:125]
	v_mfma_f32_16x16x32_bf16 v[122:125], v[176:179], v[192:195], v[122:125]
	v_mfma_f32_16x16x32_bf16 v[114:117], v[180:183], v[188:191], v[114:117]
	v_mfma_f32_16x16x32_bf16 v[114:117], v[184:187], v[192:195], v[114:117]
	v_mfma_f32_16x16x32_bf16 v[110:113], v[172:175], v[196:199], v[110:113]
	v_mfma_f32_16x16x32_bf16 v[110:113], v[176:179], v[200:203], v[110:113]
	v_mfma_f32_16x16x32_bf16 v[102:105], v[180:183], v[196:199], v[102:105]
	v_mfma_f32_16x16x32_bf16 v[102:105], v[184:187], v[200:203], v[102:105]
	v_mfma_f32_16x16x32_bf16 v[94:97], v[172:175], v[204:207], v[94:97]
	v_mfma_f32_16x16x32_bf16 v[94:97], v[176:179], v[216:219], v[94:97]
	v_mfma_f32_16x16x32_bf16 v[86:89], v[180:183], v[204:207], v[86:89]
	v_mfma_f32_16x16x32_bf16 v[86:89], v[184:187], v[216:219], v[86:89]
	v_mfma_f32_16x16x32_bf16 v[78:81], v[172:175], v[220:223], v[78:81]
	v_mfma_f32_16x16x32_bf16 v[78:81], v[176:179], v[224:227], v[78:81]
	v_mfma_f32_16x16x32_bf16 v[70:73], v[180:183], v[220:223], v[70:73]
	v_mfma_f32_16x16x32_bf16 v[70:73], v[184:187], v[224:227], v[70:73]
	s_barrier
	s_add_i32 s24, s26, s59
	v_lshl_add_u64 v[156:157], v[156:157], 0, s[56:57]
	s_mov_b32 m0, s24
	ds_read_b128 v[188:191], v146 offset:49152
	ds_read_b128 v[192:195], v146 offset:50176
	ds_read_b128 v[196:199], v146 offset:51200
	ds_read_b128 v[200:203], v146 offset:52224
	ds_read_b128 v[204:207], v146 offset:53248
	ds_read_b128 v[216:219], v146 offset:54272
	ds_read_b128 v[220:223], v146 offset:55296
	ds_read_b128 v[224:227], v146 offset:56320
	global_load_lds_dwordx4 v[156:157], off
	s_add_i32 m0, s24, 0x2000
	s_add_u32 s14, s14, 0x80080
	v_lshl_add_u64 v[156:157], v[228:229], 0, s[56:57]
	s_addc_u32 s15, s15, 0
	s_add_i32 s24, s27, s59
	global_load_lds_dwordx4 v[156:157], off
	v_lshl_add_u64 v[156:157], s[14:15], 0, v[158:159]
	s_mov_b32 m0, s24
	s_nop 0
	global_load_lds_dwordx4 v[156:157], off
	v_lshl_add_u64 v[156:157], s[14:15], 0, v[134:135]
	s_add_i32 m0, s24, 0x2000
	s_nop 0
	global_load_lds_dwordx4 v[156:157], off
	v_lshl_add_u64 v[156:157], v[230:231], 0, s[56:57]
	s_mov_b32 m0, s54
	s_nop 0
	global_load_lds_dwordx4 v[156:157], off
	v_lshl_add_u64 v[156:157], v[232:233], 0, s[56:57]
	s_mov_b32 m0, s73
	s_nop 0
	global_load_lds_dwordx4 v[156:157], off
	s_waitcnt vmcnt(8)
	s_waitcnt lgkmcnt(0)
	s_barrier
	s_waitcnt lgkmcnt(0)
	v_mfma_f32_16x16x32_bf16 v[58:61], v[140:143], v[188:191], v[58:61]
	v_mfma_f32_16x16x32_bf16 v[58:61], v[148:151], v[192:195], v[58:61]
	v_mfma_f32_16x16x32_bf16 v[50:53], v[152:155], v[188:191], v[50:53]
	v_mfma_f32_16x16x32_bf16 v[50:53], v[168:171], v[192:195], v[50:53]
	v_mfma_f32_16x16x32_bf16 v[42:45], v[140:143], v[196:199], v[42:45]
	v_mfma_f32_16x16x32_bf16 v[42:45], v[148:151], v[200:203], v[42:45]
	v_mfma_f32_16x16x32_bf16 v[34:37], v[152:155], v[196:199], v[34:37]
	v_mfma_f32_16x16x32_bf16 v[34:37], v[168:171], v[200:203], v[34:37]
	v_mfma_f32_16x16x32_bf16 v[26:29], v[140:143], v[204:207], v[26:29]
	v_mfma_f32_16x16x32_bf16 v[26:29], v[148:151], v[216:219], v[26:29]
	v_mfma_f32_16x16x32_bf16 v[18:21], v[152:155], v[204:207], v[18:21]
	v_mfma_f32_16x16x32_bf16 v[18:21], v[168:171], v[216:219], v[18:21]
	v_mfma_f32_16x16x32_bf16 v[10:13], v[140:143], v[220:223], v[10:13]
	v_mfma_f32_16x16x32_bf16 v[10:13], v[148:151], v[224:227], v[10:13]
	v_mfma_f32_16x16x32_bf16 v[2:5], v[152:155], v[220:223], v[2:5]
	v_mfma_f32_16x16x32_bf16 v[2:5], v[168:171], v[224:227], v[2:5]
	v_mfma_f32_16x16x32_bf16 v[62:65], v[172:175], v[188:191], v[62:65]
	v_mfma_f32_16x16x32_bf16 v[62:65], v[176:179], v[192:195], v[62:65]
	v_mfma_f32_16x16x32_bf16 v[54:57], v[180:183], v[188:191], v[54:57]
	v_mfma_f32_16x16x32_bf16 v[54:57], v[184:187], v[192:195], v[54:57]
	v_mfma_f32_16x16x32_bf16 v[46:49], v[172:175], v[196:199], v[46:49]
	v_mfma_f32_16x16x32_bf16 v[46:49], v[176:179], v[200:203], v[46:49]
	v_mfma_f32_16x16x32_bf16 v[38:41], v[180:183], v[196:199], v[38:41]
	v_mfma_f32_16x16x32_bf16 v[38:41], v[184:187], v[200:203], v[38:41]
	v_mfma_f32_16x16x32_bf16 v[30:33], v[172:175], v[204:207], v[30:33]
	v_mfma_f32_16x16x32_bf16 v[30:33], v[176:179], v[216:219], v[30:33]
	v_mfma_f32_16x16x32_bf16 v[22:25], v[180:183], v[204:207], v[22:25]
	v_mfma_f32_16x16x32_bf16 v[22:25], v[184:187], v[216:219], v[22:25]
	v_mfma_f32_16x16x32_bf16 v[14:17], v[172:175], v[220:223], v[14:17]
	v_mfma_f32_16x16x32_bf16 v[14:17], v[176:179], v[224:227], v[14:17]
	v_mfma_f32_16x16x32_bf16 v[6:9], v[180:183], v[220:223], v[6:9]
	v_mfma_f32_16x16x32_bf16 v[6:9], v[184:187], v[224:227], v[6:9]
	s_barrier
	s_add_i32 s17, s17, 2
	s_add_u32 s66, s66, 0x100
	s_addc_u32 s67, s67, 0
	s_add_u32 s11, s11, 0x100
	s_addc_u32 s16, s16, 0
	s_cmp_gt_u32 s17, 29

.Lsp_LBB0715:
	s_add_u32 s14, s66, 0xfff80080
	s_addc_u32 s15, s67, -1
	s_add_i32 s24, 0, 0x10000
	s_cmp_eq_u32 s17, 28
	s_cselect_b32 s69, s49, s15
	s_cselect_b32 s68, s48, s14
	v_add_u32_e32 v147, s24, v144
	s_cselect_b32 s15, s1, s16
	s_cselect_b32 s14, s10, s11
	s_add_i32 s26, 0, 0x14000
	ds_read_b128 v[140:143], v147
	ds_read_b128 v[148:151], v147 offset:1024
	ds_read_b128 v[152:155], v147 offset:2048
	ds_read_b128 v[168:171], v147 offset:3072
	v_add_u32_e32 v147, s26, v144
	ds_read_b128 v[172:175], v147
	ds_read_b128 v[176:179], v147 offset:1024
	ds_read_b128 v[180:183], v147 offset:2048
	ds_read_b128 v[184:187], v147 offset:3072
	v_lshl_add_u64 v[156:157], s[66:67], 0, v[136:137]
	s_add_i32 m0, s65, 0xc000
	ds_read_b128 v[188:191], v146
	ds_read_b128 v[192:195], v146 offset:1024
	ds_read_b128 v[196:199], v146 offset:2048
	ds_read_b128 v[200:203], v146 offset:3072
	ds_read_b128 v[204:207], v146 offset:4096
	ds_read_b128 v[216:219], v146 offset:5120
	ds_read_b128 v[220:223], v146 offset:6144
	ds_read_b128 v[224:227], v146 offset:7168
	global_load_lds_dwordx4 v[156:157], off
	v_lshl_add_u64 v[156:157], s[66:67], 0, v[138:139]
	s_add_i32 m0, s65, 0xe000
	s_nop 0
	global_load_lds_dwordx4 v[156:157], off
	s_waitcnt vmcnt(8)
	s_waitcnt lgkmcnt(0)
	s_barrier
	s_nop 0
	s_waitcnt lgkmcnt(0)
	v_mfma_f32_16x16x32_bf16 v[126:129], v[140:143], v[188:191], v[126:129]
	v_mfma_f32_16x16x32_bf16 v[126:129], v[148:151], v[192:195], v[126:129]
	v_mfma_f32_16x16x32_bf16 v[118:121], v[152:155], v[188:191], v[118:121]
	v_mfma_f32_16x16x32_bf16 v[118:121], v[168:171], v[192:195], v[118:121]
	v_mfma_f32_16x16x32_bf16 v[106:109], v[140:143], v[196:199], v[106:109]
	v_mfma_f32_16x16x32_bf16 v[106:109], v[148:151], v[200:203], v[106:109]
	v_mfma_f32_16x16x32_bf16 v[98:101], v[152:155], v[196:199], v[98:101]
	v_mfma_f32_16x16x32_bf16 v[98:101], v[168:171], v[200:203], v[98:101]
	v_mfma_f32_16x16x32_bf16 v[90:93], v[140:143], v[204:207], v[90:93]
	v_mfma_f32_16x16x32_bf16 v[90:93], v[148:151], v[216:219], v[90:93]
	v_mfma_f32_16x16x32_bf16 v[82:85], v[152:155], v[204:207], v[82:85]
	v_mfma_f32_16x16x32_bf16 v[82:85], v[168:171], v[216:219], v[82:85]
	v_mfma_f32_16x16x32_bf16 v[74:77], v[140:143], v[220:223], v[74:77]
	v_mfma_f32_16x16x32_bf16 v[74:77], v[148:151], v[224:227], v[74:77]
	v_mfma_f32_16x16x32_bf16 v[66:69], v[152:155], v[220:223], v[66:69]
	v_mfma_f32_16x16x32_bf16 v[66:69], v[168:171], v[224:227], v[66:69]
	v_mfma_f32_16x16x32_bf16 v[122:125], v[172:175], v[188:191], v[122:125]
	v_mfma_f32_16x16x32_bf16 v[122:125], v[176:179], v[192:195], v[122:125]
	v_mfma_f32_16x16x32_bf16 v[114:117], v[180:183], v[188:191], v[114:117]
	v_mfma_f32_16x16x32_bf16 v[114:117], v[184:187], v[192:195], v[114:117]
	v_mfma_f32_16x16x32_bf16 v[110:113], v[172:175], v[196:199], v[110:113]
	v_mfma_f32_16x16x32_bf16 v[110:113], v[176:179], v[200:203], v[110:113]
	v_mfma_f32_16x16x32_bf16 v[102:105], v[180:183], v[196:199], v[102:105]
	v_mfma_f32_16x16x32_bf16 v[102:105], v[184:187], v[200:203], v[102:105]
	v_mfma_f32_16x16x32_bf16 v[94:97], v[172:175], v[204:207], v[94:97]
	v_mfma_f32_16x16x32_bf16 v[94:97], v[176:179], v[216:219], v[94:97]
	v_mfma_f32_16x16x32_bf16 v[86:89], v[180:183], v[204:207], v[86:89]
	v_mfma_f32_16x16x32_bf16 v[86:89], v[184:187], v[216:219], v[86:89]
	v_mfma_f32_16x16x32_bf16 v[78:81], v[172:175], v[220:223], v[78:81]
	v_mfma_f32_16x16x32_bf16 v[78:81], v[176:179], v[224:227], v[78:81]
	v_mfma_f32_16x16x32_bf16 v[70:73], v[180:183], v[220:223], v[70:73]
	v_mfma_f32_16x16x32_bf16 v[70:73], v[184:187], v[224:227], v[70:73]
	s_barrier
	s_add_i32 s24, s24, s59
	v_lshl_add_u64 v[156:157], s[14:15], 0, v[158:159]
	s_mov_b32 m0, s24
	ds_read_b128 v[188:191], v146 offset:16384
	ds_read_b128 v[192:195], v146 offset:17408
	ds_read_b128 v[196:199], v146 offset:18432
	ds_read_b128 v[200:203], v146 offset:19456
	ds_read_b128 v[204:207], v146 offset:20480
	ds_read_b128 v[216:219], v146 offset:21504
	ds_read_b128 v[220:223], v146 offset:22528
	ds_read_b128 v[224:227], v146 offset:23552
	global_load_lds_dwordx4 v[156:157], off
	s_add_i32 m0, s24, 0x2000
	s_add_u32 s24, s14, 0x80000
	v_lshl_add_u64 v[228:229], s[14:15], 0, v[134:135]
	s_addc_u32 s25, s15, 0
	s_add_i32 s26, s26, s59
	global_load_lds_dwordx4 v[228:229], off
	v_lshl_add_u64 v[230:231], s[24:25], 0, v[158:159]
	s_mov_b32 m0, s26
	v_lshl_add_u64 v[232:233], s[68:69], 0, v[132:133]
	global_load_lds_dwordx4 v[230:231], off
	v_lshl_add_u64 v[230:231], s[24:25], 0, v[134:135]
	s_add_i32 m0, s26, 0x2000
	s_nop 0
	global_load_lds_dwordx4 v[230:231], off
	v_lshl_add_u64 v[230:231], s[68:69], 0, v[130:131]
	s_mov_b32 m0, s65
	s_nop 0
	global_load_lds_dwordx4 v[230:231], off
	s_mov_b32 m0, s70
	s_nop 0
	global_load_lds_dwordx4 v[232:233], off
	s_waitcnt vmcnt(8)
	s_waitcnt lgkmcnt(0)
	s_barrier
	s_nop 0
	s_waitcnt lgkmcnt(0)
	v_mfma_f32_16x16x32_bf16 v[58:61], v[140:143], v[188:191], v[58:61]
	v_mfma_f32_16x16x32_bf16 v[58:61], v[148:151], v[192:195], v[58:61]
	v_mfma_f32_16x16x32_bf16 v[50:53], v[152:155], v[188:191], v[50:53]
	v_mfma_f32_16x16x32_bf16 v[50:53], v[168:171], v[192:195], v[50:53]
	v_mfma_f32_16x16x32_bf16 v[42:45], v[140:143], v[196:199], v[42:45]
	v_mfma_f32_16x16x32_bf16 v[42:45], v[148:151], v[200:203], v[42:45]
	v_mfma_f32_16x16x32_bf16 v[34:37], v[152:155], v[196:199], v[34:37]
	v_mfma_f32_16x16x32_bf16 v[34:37], v[168:171], v[200:203], v[34:37]
	v_mfma_f32_16x16x32_bf16 v[26:29], v[140:143], v[204:207], v[26:29]
	v_mfma_f32_16x16x32_bf16 v[26:29], v[148:151], v[216:219], v[26:29]
	v_mfma_f32_16x16x32_bf16 v[18:21], v[152:155], v[204:207], v[18:21]
	v_mfma_f32_16x16x32_bf16 v[18:21], v[168:171], v[216:219], v[18:21]
	v_mfma_f32_16x16x32_bf16 v[10:13], v[140:143], v[220:223], v[10:13]
	v_mfma_f32_16x16x32_bf16 v[10:13], v[148:151], v[224:227], v[10:13]
	v_mfma_f32_16x16x32_bf16 v[2:5], v[152:155], v[220:223], v[2:5]
	v_mfma_f32_16x16x32_bf16 v[2:5], v[168:171], v[224:227], v[2:5]
	v_mfma_f32_16x16x32_bf16 v[62:65], v[172:175], v[188:191], v[62:65]
	v_mfma_f32_16x16x32_bf16 v[62:65], v[176:179], v[192:195], v[62:65]
	v_mfma_f32_16x16x32_bf16 v[54:57], v[180:183], v[188:191], v[54:57]
	v_mfma_f32_16x16x32_bf16 v[54:57], v[184:187], v[192:195], v[54:57]
	v_mfma_f32_16x16x32_bf16 v[46:49], v[172:175], v[196:199], v[46:49]
	v_mfma_f32_16x16x32_bf16 v[46:49], v[176:179], v[200:203], v[46:49]
	v_mfma_f32_16x16x32_bf16 v[38:41], v[180:183], v[196:199], v[38:41]
	v_mfma_f32_16x16x32_bf16 v[38:41], v[184:187], v[200:203], v[38:41]
	v_mfma_f32_16x16x32_bf16 v[30:33], v[172:175], v[204:207], v[30:33]
	v_mfma_f32_16x16x32_bf16 v[30:33], v[176:179], v[216:219], v[30:33]
	v_mfma_f32_16x16x32_bf16 v[22:25], v[180:183], v[204:207], v[22:25]
	v_mfma_f32_16x16x32_bf16 v[22:25], v[184:187], v[216:219], v[22:25]
	v_mfma_f32_16x16x32_bf16 v[14:17], v[172:175], v[220:223], v[14:17]
	v_mfma_f32_16x16x32_bf16 v[14:17], v[176:179], v[224:227], v[14:17]
	v_mfma_f32_16x16x32_bf16 v[6:9], v[180:183], v[220:223], v[6:9]
	v_mfma_f32_16x16x32_bf16 v[6:9], v[184:187], v[224:227], v[6:9]
	s_barrier
	s_add_i32 s26, 0, 0x18000
	v_add_u32_e32 v147, s26, v144
	s_add_i32 s27, 0, 0x1c000
	ds_read_b128 v[140:143], v147
	ds_read_b128 v[148:151], v147 offset:1024
	ds_read_b128 v[152:155], v147 offset:2048
	ds_read_b128 v[168:171], v147 offset:3072
	v_add_u32_e32 v147, s27, v144
	ds_read_b128 v[172:175], v147
	ds_read_b128 v[176:179], v147 offset:1024
	ds_read_b128 v[180:183], v147 offset:2048
	ds_read_b128 v[184:187], v147 offset:3072
	s_add_u32 s24, s68, 0x80000
	s_addc_u32 s25, s69, 0
	s_mov_b32 m0, s71
	v_lshl_add_u64 v[234:235], s[24:25], 0, v[130:131]
	ds_read_b128 v[188:191], v146 offset:32768
	ds_read_b128 v[192:195], v146 offset:33792
	ds_read_b128 v[196:199], v146 offset:34816
	ds_read_b128 v[200:203], v146 offset:35840
	ds_read_b128 v[204:207], v146 offset:36864
	ds_read_b128 v[216:219], v146 offset:37888
	ds_read_b128 v[220:223], v146 offset:38912
	ds_read_b128 v[224:227], v146 offset:39936
	global_load_lds_dwordx4 v[234:235], off
	v_lshl_add_u64 v[234:235], s[24:25], 0, v[132:133]
	s_mov_b32 m0, s72
	s_nop 0
	global_load_lds_dwordx4 v[234:235], off
	s_waitcnt vmcnt(8)
	s_waitcnt lgkmcnt(0)
	s_barrier
	s_nop 0
	s_waitcnt lgkmcnt(0)
	v_mfma_f32_16x16x32_bf16 v[126:129], v[140:143], v[188:191], v[126:129]
	v_mfma_f32_16x16x32_bf16 v[126:129], v[148:151], v[192:195], v[126:129]
	v_mfma_f32_16x16x32_bf16 v[118:121], v[152:155], v[188:191], v[118:121]
	v_mfma_f32_16x16x32_bf16 v[118:121], v[168:171], v[192:195], v[118:121]
	v_mfma_f32_16x16x32_bf16 v[106:109], v[140:143], v[196:199], v[106:109]
	v_mfma_f32_16x16x32_bf16 v[106:109], v[148:151], v[200:203], v[106:109]
	v_mfma_f32_16x16x32_bf16 v[98:101], v[152:155], v[196:199], v[98:101]
	v_mfma_f32_16x16x32_bf16 v[98:101], v[168:171], v[200:203], v[98:101]
	v_mfma_f32_16x16x32_bf16 v[90:93], v[140:143], v[204:207], v[90:93]
	v_mfma_f32_16x16x32_bf16 v[90:93], v[148:151], v[216:219], v[90:93]
	v_mfma_f32_16x16x32_bf16 v[82:85], v[152:155], v[204:207], v[82:85]
	v_mfma_f32_16x16x32_bf16 v[82:85], v[168:171], v[216:219], v[82:85]
	v_mfma_f32_16x16x32_bf16 v[74:77], v[140:143], v[220:223], v[74:77]
	v_mfma_f32_16x16x32_bf16 v[74:77], v[148:151], v[224:227], v[74:77]
	v_mfma_f32_16x16x32_bf16 v[66:69], v[152:155], v[220:223], v[66:69]
	v_mfma_f32_16x16x32_bf16 v[66:69], v[168:171], v[224:227], v[66:69]
	v_mfma_f32_16x16x32_bf16 v[122:125], v[172:175], v[188:191], v[122:125]
	v_mfma_f32_16x16x32_bf16 v[122:125], v[176:179], v[192:195], v[122:125]
	v_mfma_f32_16x16x32_bf16 v[114:117], v[180:183], v[188:191], v[114:117]
	v_mfma_f32_16x16x32_bf16 v[114:117], v[184:187], v[192:195], v[114:117]
	v_mfma_f32_16x16x32_bf16 v[110:113], v[172:175], v[196:199], v[110:113]
	v_mfma_f32_16x16x32_bf16 v[110:113], v[176:179], v[200:203], v[110:113]
	v_mfma_f32_16x16x32_bf16 v[102:105], v[180:183], v[196:199], v[102:105]
	v_mfma_f32_16x16x32_bf16 v[102:105], v[184:187], v[200:203], v[102:105]
	v_mfma_f32_16x16x32_bf16 v[94:97], v[172:175], v[204:207], v[94:97]
	v_mfma_f32_16x16x32_bf16 v[94:97], v[176:179], v[216:219], v[94:97]
	v_mfma_f32_16x16x32_bf16 v[86:89], v[180:183], v[204:207], v[86:89]
	v_mfma_f32_16x16x32_bf16 v[86:89], v[184:187], v[216:219], v[86:89]
	v_mfma_f32_16x16x32_bf16 v[78:81], v[172:175], v[220:223], v[78:81]
	v_mfma_f32_16x16x32_bf16 v[78:81], v[176:179], v[224:227], v[78:81]
	v_mfma_f32_16x16x32_bf16 v[70:73], v[180:183], v[220:223], v[70:73]
	v_mfma_f32_16x16x32_bf16 v[70:73], v[184:187], v[224:227], v[70:73]
	s_barrier
	s_add_i32 s24, s26, s59
	v_lshl_add_u64 v[156:157], v[156:157], 0, s[56:57]
	s_mov_b32 m0, s24
	ds_read_b128 v[188:191], v146 offset:49152
	ds_read_b128 v[192:195], v146 offset:50176
	ds_read_b128 v[196:199], v146 offset:51200
	ds_read_b128 v[200:203], v146 offset:52224
	ds_read_b128 v[204:207], v146 offset:53248
	ds_read_b128 v[216:219], v146 offset:54272
	ds_read_b128 v[220:223], v146 offset:55296
	ds_read_b128 v[224:227], v146 offset:56320
	global_load_lds_dwordx4 v[156:157], off
	s_add_i32 m0, s24, 0x2000
	s_add_u32 s14, s14, 0x80080
	v_lshl_add_u64 v[156:157], v[228:229], 0, s[56:57]
	s_addc_u32 s15, s15, 0
	s_add_i32 s24, s27, s59
	global_load_lds_dwordx4 v[156:157], off
	v_lshl_add_u64 v[156:157], s[14:15], 0, v[158:159]
	s_mov_b32 m0, s24
	s_nop 0
	global_load_lds_dwordx4 v[156:157], off
	v_lshl_add_u64 v[156:157], s[14:15], 0, v[134:135]
	s_add_i32 m0, s24, 0x2000
	s_nop 0
	global_load_lds_dwordx4 v[156:157], off
	v_lshl_add_u64 v[156:157], v[230:231], 0, s[56:57]
	s_mov_b32 m0, s54
	s_nop 0
	global_load_lds_dwordx4 v[156:157], off
	v_lshl_add_u64 v[156:157], v[232:233], 0, s[56:57]
	s_mov_b32 m0, s73
	s_nop 0
	global_load_lds_dwordx4 v[156:157], off
	s_waitcnt vmcnt(8)
	s_waitcnt lgkmcnt(0)
	s_barrier
	s_waitcnt lgkmcnt(0)
	v_mfma_f32_16x16x32_bf16 v[58:61], v[140:143], v[188:191], v[58:61]
	v_mfma_f32_16x16x32_bf16 v[58:61], v[148:151], v[192:195], v[58:61]
	v_mfma_f32_16x16x32_bf16 v[50:53], v[152:155], v[188:191], v[50:53]
	v_mfma_f32_16x16x32_bf16 v[50:53], v[168:171], v[192:195], v[50:53]
	v_mfma_f32_16x16x32_bf16 v[42:45], v[140:143], v[196:199], v[42:45]
	v_mfma_f32_16x16x32_bf16 v[42:45], v[148:151], v[200:203], v[42:45]
	v_mfma_f32_16x16x32_bf16 v[34:37], v[152:155], v[196:199], v[34:37]
	v_mfma_f32_16x16x32_bf16 v[34:37], v[168:171], v[200:203], v[34:37]
	v_mfma_f32_16x16x32_bf16 v[26:29], v[140:143], v[204:207], v[26:29]
	v_mfma_f32_16x16x32_bf16 v[26:29], v[148:151], v[216:219], v[26:29]
	v_mfma_f32_16x16x32_bf16 v[18:21], v[152:155], v[204:207], v[18:21]
	v_mfma_f32_16x16x32_bf16 v[18:21], v[168:171], v[216:219], v[18:21]
	v_mfma_f32_16x16x32_bf16 v[10:13], v[140:143], v[220:223], v[10:13]
	v_mfma_f32_16x16x32_bf16 v[10:13], v[148:151], v[224:227], v[10:13]
	v_mfma_f32_16x16x32_bf16 v[2:5], v[152:155], v[220:223], v[2:5]
	v_mfma_f32_16x16x32_bf16 v[2:5], v[168:171], v[224:227], v[2:5]
	v_mfma_f32_16x16x32_bf16 v[62:65], v[172:175], v[188:191], v[62:65]
	v_mfma_f32_16x16x32_bf16 v[62:65], v[176:179], v[192:195], v[62:65]
	v_mfma_f32_16x16x32_bf16 v[54:57], v[180:183], v[188:191], v[54:57]
	v_mfma_f32_16x16x32_bf16 v[54:57], v[184:187], v[192:195], v[54:57]
	v_mfma_f32_16x16x32_bf16 v[46:49], v[172:175], v[196:199], v[46:49]
	v_mfma_f32_16x16x32_bf16 v[46:49], v[176:179], v[200:203], v[46:49]
	v_mfma_f32_16x16x32_bf16 v[38:41], v[180:183], v[196:199], v[38:41]
	v_mfma_f32_16x16x32_bf16 v[38:41], v[184:187], v[200:203], v[38:41]
	v_mfma_f32_16x16x32_bf16 v[30:33], v[172:175], v[204:207], v[30:33]
	v_mfma_f32_16x16x32_bf16 v[30:33], v[176:179], v[216:219], v[30:33]
	v_mfma_f32_16x16x32_bf16 v[22:25], v[180:183], v[204:207], v[22:25]
	v_mfma_f32_16x16x32_bf16 v[22:25], v[184:187], v[216:219], v[22:25]
	v_mfma_f32_16x16x32_bf16 v[14:17], v[172:175], v[220:223], v[14:17]
	v_mfma_f32_16x16x32_bf16 v[14:17], v[176:179], v[224:227], v[14:17]
	v_mfma_f32_16x16x32_bf16 v[6:9], v[180:183], v[220:223], v[6:9]
	v_mfma_f32_16x16x32_bf16 v[6:9], v[184:187], v[224:227], v[6:9]
	s_barrier
	s_add_i32 s17, s17, 2
	s_add_u32 s66, s66, 0x100
	s_addc_u32 s67, s67, 0
	s_add_u32 s11, s11, 0x100
	s_addc_u32 s16, s16, 0
	s_cmp_gt_u32 s17, 29
	s_cbranch_scc0 .LBB0_715
	s_and_b64 vcc, exec, s[22:23]
	s_cbranch_vccz .LBB0_718
	s_barrier

.Lsp_LBB0801_plp801:
	s_add_u32 s14, s50, 0xfff80080
	s_addc_u32 s15, s51, -1
	s_add_i32 s30, 0, 0x10000
	s_cmp_eq_u32 s29, 28
	s_cselect_b32 s65, s43, s15
	s_cselect_b32 s64, s42, s14
	v_add_u32_e32 v150, s30, v152
	s_cselect_b32 s15, s1, s23
	s_cselect_b32 s14, s16, s17
	s_add_i32 s34, 0, 0x14000
	ds_read_b128 v[142:145], v150
	ds_read_b128 v[146:149], v150 offset:1024
	ds_read_b128 v[168:171], v150 offset:2048
	ds_read_b128 v[172:175], v150 offset:3072
	v_add_u32_e32 v150, s34, v152
	ds_read_b128 v[176:179], v150
	ds_read_b128 v[180:183], v150 offset:1024
	ds_read_b128 v[184:187], v150 offset:2048
	ds_read_b128 v[188:191], v150 offset:3072
	v_lshl_add_u64 v[150:151], s[50:51], 0, v[138:139]
	s_add_i32 m0, s58, 0xc000
	ds_read_b128 v[192:195], v155
	ds_read_b128 v[196:199], v155 offset:1024
	ds_read_b128 v[200:203], v155 offset:2048
	ds_read_b128 v[204:207], v155 offset:3072
	ds_read_b128 v[216:219], v155 offset:4096
	ds_read_b128 v[220:223], v155 offset:5120
	ds_read_b128 v[224:227], v155 offset:6144
	ds_read_b128 v[228:231], v155 offset:7168
	global_load_lds_dwordx4 v[150:151], off
	v_lshl_add_u64 v[150:151], s[50:51], 0, v[140:141]
	s_add_i32 m0, s58, 0xe000
	s_nop 0
	global_load_lds_dwordx4 v[150:151], off
	s_waitcnt vmcnt(8)
	s_waitcnt lgkmcnt(0)
	s_barrier
	s_waitcnt lgkmcnt(0)
	v_mfma_f32_16x16x32_bf16 v[126:129], v[142:145], v[192:195], 0
	v_mfma_f32_16x16x32_bf16 v[126:129], v[146:149], v[196:199], v[126:129]
	v_mfma_f32_16x16x32_bf16 v[122:125], v[168:171], v[192:195], 0
	v_mfma_f32_16x16x32_bf16 v[122:125], v[172:175], v[196:199], v[122:125]
	v_mfma_f32_16x16x32_bf16 v[110:113], v[142:145], v[200:203], 0
	v_mfma_f32_16x16x32_bf16 v[110:113], v[146:149], v[204:207], v[110:113]
	v_mfma_f32_16x16x32_bf16 v[106:109], v[168:171], v[200:203], 0
	v_mfma_f32_16x16x32_bf16 v[106:109], v[172:175], v[204:207], v[106:109]
	v_mfma_f32_16x16x32_bf16 v[94:97], v[142:145], v[216:219], 0
	v_mfma_f32_16x16x32_bf16 v[94:97], v[146:149], v[220:223], v[94:97]
	v_mfma_f32_16x16x32_bf16 v[90:93], v[168:171], v[216:219], 0
	v_mfma_f32_16x16x32_bf16 v[90:93], v[172:175], v[220:223], v[90:93]
	v_mfma_f32_16x16x32_bf16 v[78:81], v[142:145], v[224:227], 0
	v_mfma_f32_16x16x32_bf16 v[78:81], v[146:149], v[228:231], v[78:81]
	v_mfma_f32_16x16x32_bf16 v[74:77], v[168:171], v[224:227], 0
	v_mfma_f32_16x16x32_bf16 v[74:77], v[172:175], v[228:231], v[74:77]
	v_mfma_f32_16x16x32_bf16 v[118:121], v[176:179], v[192:195], 0
	v_mfma_f32_16x16x32_bf16 v[118:121], v[180:183], v[196:199], v[118:121]
	v_mfma_f32_16x16x32_bf16 v[114:117], v[184:187], v[192:195], 0
	v_mfma_f32_16x16x32_bf16 v[114:117], v[188:191], v[196:199], v[114:117]
	v_mfma_f32_16x16x32_bf16 v[102:105], v[176:179], v[200:203], 0
	v_mfma_f32_16x16x32_bf16 v[102:105], v[180:183], v[204:207], v[102:105]
	v_mfma_f32_16x16x32_bf16 v[98:101], v[184:187], v[200:203], 0
	v_mfma_f32_16x16x32_bf16 v[98:101], v[188:191], v[204:207], v[98:101]
	v_mfma_f32_16x16x32_bf16 v[86:89], v[176:179], v[216:219], 0
	v_mfma_f32_16x16x32_bf16 v[86:89], v[180:183], v[220:223], v[86:89]
	v_mfma_f32_16x16x32_bf16 v[82:85], v[184:187], v[216:219], 0
	v_mfma_f32_16x16x32_bf16 v[82:85], v[188:191], v[220:223], v[82:85]
	v_mfma_f32_16x16x32_bf16 v[70:73], v[176:179], v[224:227], 0
	v_mfma_f32_16x16x32_bf16 v[70:73], v[180:183], v[228:231], v[70:73]
	v_mfma_f32_16x16x32_bf16 v[66:69], v[184:187], v[224:227], 0
	v_mfma_f32_16x16x32_bf16 v[66:69], v[188:191], v[228:231], v[66:69]
	s_barrier
	s_add_i32 s30, s30, s11
	v_lshl_add_u64 v[150:151], s[14:15], 0, v[158:159]
	s_mov_b32 m0, s30
	ds_read_b128 v[192:195], v155 offset:16384
	ds_read_b128 v[196:199], v155 offset:17408
	ds_read_b128 v[200:203], v155 offset:18432
	ds_read_b128 v[204:207], v155 offset:19456
	ds_read_b128 v[216:219], v155 offset:20480
	ds_read_b128 v[220:223], v155 offset:21504
	ds_read_b128 v[224:227], v155 offset:22528
	ds_read_b128 v[228:231], v155 offset:23552
	global_load_lds_dwordx4 v[150:151], off
	s_add_i32 m0, s30, 0x2000
	s_add_u32 s30, s14, 0x80000
	v_lshl_add_u64 v[156:157], s[14:15], 0, v[134:135]
	s_addc_u32 s31, s15, 0
	s_add_i32 s34, s34, s11
	global_load_lds_dwordx4 v[156:157], off
	v_lshl_add_u64 v[232:233], s[30:31], 0, v[158:159]
	s_mov_b32 m0, s34
	v_lshl_add_u64 v[234:235], s[64:65], 0, v[132:133]
	global_load_lds_dwordx4 v[232:233], off
	v_lshl_add_u64 v[232:233], s[30:31], 0, v[134:135]
	s_add_i32 m0, s34, 0x2000
	s_nop 0
	global_load_lds_dwordx4 v[232:233], off
	v_lshl_add_u64 v[232:233], s[64:65], 0, v[130:131]
	s_mov_b32 m0, s58
	s_nop 0
	global_load_lds_dwordx4 v[232:233], off
	s_mov_b32 m0, s24
	s_nop 0
	global_load_lds_dwordx4 v[234:235], off
	s_waitcnt vmcnt(8)
	s_waitcnt lgkmcnt(0)
	s_barrier
	s_nop 0
	s_waitcnt lgkmcnt(0)
	v_mfma_f32_16x16x32_bf16 v[62:65], v[142:145], v[192:195], 0
	v_mfma_f32_16x16x32_bf16 v[62:65], v[146:149], v[196:199], v[62:65]
	v_mfma_f32_16x16x32_bf16 v[58:61], v[168:171], v[192:195], 0
	v_mfma_f32_16x16x32_bf16 v[58:61], v[172:175], v[196:199], v[58:61]
	v_mfma_f32_16x16x32_bf16 v[46:49], v[142:145], v[200:203], 0
	v_mfma_f32_16x16x32_bf16 v[46:49], v[146:149], v[204:207], v[46:49]
	v_mfma_f32_16x16x32_bf16 v[42:45], v[168:171], v[200:203], 0
	v_mfma_f32_16x16x32_bf16 v[42:45], v[172:175], v[204:207], v[42:45]
	v_mfma_f32_16x16x32_bf16 v[30:33], v[142:145], v[216:219], 0
	v_mfma_f32_16x16x32_bf16 v[30:33], v[146:149], v[220:223], v[30:33]
	v_mfma_f32_16x16x32_bf16 v[26:29], v[168:171], v[216:219], 0
	v_mfma_f32_16x16x32_bf16 v[26:29], v[172:175], v[220:223], v[26:29]
	v_mfma_f32_16x16x32_bf16 v[14:17], v[142:145], v[224:227], 0
	v_mfma_f32_16x16x32_bf16 v[14:17], v[146:149], v[228:231], v[14:17]
	v_mfma_f32_16x16x32_bf16 v[10:13], v[168:171], v[224:227], 0
	v_mfma_f32_16x16x32_bf16 v[10:13], v[172:175], v[228:231], v[10:13]
	v_mfma_f32_16x16x32_bf16 v[54:57], v[176:179], v[192:195], 0
	v_mfma_f32_16x16x32_bf16 v[54:57], v[180:183], v[196:199], v[54:57]
	v_mfma_f32_16x16x32_bf16 v[50:53], v[184:187], v[192:195], 0
	v_mfma_f32_16x16x32_bf16 v[50:53], v[188:191], v[196:199], v[50:53]
	v_mfma_f32_16x16x32_bf16 v[38:41], v[176:179], v[200:203], 0
	v_mfma_f32_16x16x32_bf16 v[38:41], v[180:183], v[204:207], v[38:41]
	v_mfma_f32_16x16x32_bf16 v[34:37], v[184:187], v[200:203], 0
	v_mfma_f32_16x16x32_bf16 v[34:37], v[188:191], v[204:207], v[34:37]
	v_mfma_f32_16x16x32_bf16 v[22:25], v[176:179], v[216:219], 0
	v_mfma_f32_16x16x32_bf16 v[22:25], v[180:183], v[220:223], v[22:25]
	v_mfma_f32_16x16x32_bf16 v[18:21], v[184:187], v[216:219], 0
	v_mfma_f32_16x16x32_bf16 v[18:21], v[188:191], v[220:223], v[18:21]
	v_mfma_f32_16x16x32_bf16 v[6:9], v[176:179], v[224:227], 0
	v_mfma_f32_16x16x32_bf16 v[6:9], v[180:183], v[228:231], v[6:9]
	v_mfma_f32_16x16x32_bf16 v[2:5], v[184:187], v[224:227], 0
	v_mfma_f32_16x16x32_bf16 v[2:5], v[188:191], v[228:231], v[2:5]
	s_barrier
	s_add_i32 s34, 0, 0x18000
	v_add_u32_e32 v161, s34, v152
	s_add_i32 s35, 0, 0x1c000
	ds_read_b128 v[142:145], v161
	ds_read_b128 v[146:149], v161 offset:1024
	ds_read_b128 v[168:171], v161 offset:2048
	ds_read_b128 v[172:175], v161 offset:3072
	v_add_u32_e32 v161, s35, v152
	ds_read_b128 v[176:179], v161
	ds_read_b128 v[180:183], v161 offset:1024
	ds_read_b128 v[184:187], v161 offset:2048
	ds_read_b128 v[188:191], v161 offset:3072
	s_add_u32 s30, s64, 0x80000
	s_addc_u32 s31, s65, 0
	s_mov_b32 m0, s25
	v_lshl_add_u64 v[236:237], s[30:31], 0, v[130:131]
	ds_read_b128 v[192:195], v155 offset:32768
	ds_read_b128 v[196:199], v155 offset:33792
	ds_read_b128 v[200:203], v155 offset:34816
	ds_read_b128 v[204:207], v155 offset:35840
	ds_read_b128 v[216:219], v155 offset:36864
	ds_read_b128 v[220:223], v155 offset:37888
	ds_read_b128 v[224:227], v155 offset:38912
	ds_read_b128 v[228:231], v155 offset:39936
	global_load_lds_dwordx4 v[236:237], off
	v_lshl_add_u64 v[236:237], s[30:31], 0, v[132:133]
	s_mov_b32 m0, s59
	s_nop 0
	global_load_lds_dwordx4 v[236:237], off
	s_waitcnt vmcnt(8)
	s_waitcnt lgkmcnt(0)
	s_barrier
	s_nop 0
	s_waitcnt lgkmcnt(0)
	v_mfma_f32_16x16x32_bf16 v[126:129], v[142:145], v[192:195], v[126:129]
	v_mfma_f32_16x16x32_bf16 v[126:129], v[146:149], v[196:199], v[126:129]
	v_mfma_f32_16x16x32_bf16 v[122:125], v[168:171], v[192:195], v[122:125]
	v_mfma_f32_16x16x32_bf16 v[122:125], v[172:175], v[196:199], v[122:125]
	v_mfma_f32_16x16x32_bf16 v[110:113], v[142:145], v[200:203], v[110:113]
	v_mfma_f32_16x16x32_bf16 v[110:113], v[146:149], v[204:207], v[110:113]
	v_mfma_f32_16x16x32_bf16 v[106:109], v[168:171], v[200:203], v[106:109]
	v_mfma_f32_16x16x32_bf16 v[106:109], v[172:175], v[204:207], v[106:109]
	v_mfma_f32_16x16x32_bf16 v[94:97], v[142:145], v[216:219], v[94:97]
	v_mfma_f32_16x16x32_bf16 v[94:97], v[146:149], v[220:223], v[94:97]
	v_mfma_f32_16x16x32_bf16 v[90:93], v[168:171], v[216:219], v[90:93]
	v_mfma_f32_16x16x32_bf16 v[90:93], v[172:175], v[220:223], v[90:93]
	v_mfma_f32_16x16x32_bf16 v[78:81], v[142:145], v[224:227], v[78:81]
	v_mfma_f32_16x16x32_bf16 v[78:81], v[146:149], v[228:231], v[78:81]
	v_mfma_f32_16x16x32_bf16 v[74:77], v[168:171], v[224:227], v[74:77]
	v_mfma_f32_16x16x32_bf16 v[74:77], v[172:175], v[228:231], v[74:77]
	v_mfma_f32_16x16x32_bf16 v[118:121], v[176:179], v[192:195], v[118:121]
	v_mfma_f32_16x16x32_bf16 v[118:121], v[180:183], v[196:199], v[118:121]
	v_mfma_f32_16x16x32_bf16 v[114:117], v[184:187], v[192:195], v[114:117]
	v_mfma_f32_16x16x32_bf16 v[114:117], v[188:191], v[196:199], v[114:117]
	v_mfma_f32_16x16x32_bf16 v[102:105], v[176:179], v[200:203], v[102:105]
	v_mfma_f32_16x16x32_bf16 v[102:105], v[180:183], v[204:207], v[102:105]
	v_mfma_f32_16x16x32_bf16 v[98:101], v[184:187], v[200:203], v[98:101]
	v_mfma_f32_16x16x32_bf16 v[98:101], v[188:191], v[204:207], v[98:101]
	v_mfma_f32_16x16x32_bf16 v[86:89], v[176:179], v[216:219], v[86:89]
	v_mfma_f32_16x16x32_bf16 v[86:89], v[180:183], v[220:223], v[86:89]
	v_mfma_f32_16x16x32_bf16 v[82:85], v[184:187], v[216:219], v[82:85]
	v_mfma_f32_16x16x32_bf16 v[82:85], v[188:191], v[220:223], v[82:85]
	v_mfma_f32_16x16x32_bf16 v[70:73], v[176:179], v[224:227], v[70:73]
	v_mfma_f32_16x16x32_bf16 v[70:73], v[180:183], v[228:231], v[70:73]
	v_mfma_f32_16x16x32_bf16 v[66:69], v[184:187], v[224:227], v[66:69]
	v_mfma_f32_16x16x32_bf16 v[66:69], v[188:191], v[228:231], v[66:69]
	s_barrier
	s_add_i32 s30, s34, s11
	v_lshl_add_u64 v[150:151], v[150:151], 0, s[56:57]
	s_mov_b32 m0, s30
	ds_read_b128 v[192:195], v155 offset:49152
	ds_read_b128 v[196:199], v155 offset:50176
	ds_read_b128 v[200:203], v155 offset:51200
	ds_read_b128 v[204:207], v155 offset:52224
	ds_read_b128 v[216:219], v155 offset:53248
	ds_read_b128 v[220:223], v155 offset:54272
	ds_read_b128 v[224:227], v155 offset:55296
	ds_read_b128 v[228:231], v155 offset:56320
	global_load_lds_dwordx4 v[150:151], off
	s_add_i32 m0, s30, 0x2000
	s_add_u32 s14, s14, 0x80080
	v_lshl_add_u64 v[150:151], v[156:157], 0, s[56:57]
	s_addc_u32 s15, s15, 0
	s_add_i32 s30, s35, s11
	global_load_lds_dwordx4 v[150:151], off
	v_lshl_add_u64 v[150:151], s[14:15], 0, v[158:159]
	s_mov_b32 m0, s30
	s_nop 0
	global_load_lds_dwordx4 v[150:151], off
	v_lshl_add_u64 v[150:151], s[14:15], 0, v[134:135]
	s_add_i32 m0, s30, 0x2000
	s_nop 0
	global_load_lds_dwordx4 v[150:151], off
	v_lshl_add_u64 v[150:151], v[232:233], 0, s[56:57]
	s_mov_b32 m0, s26
	s_nop 0
	global_load_lds_dwordx4 v[150:151], off
	v_lshl_add_u64 v[150:151], v[234:235], 0, s[56:57]
	s_mov_b32 m0, s27
	s_nop 0
	global_load_lds_dwordx4 v[150:151], off
	s_waitcnt vmcnt(8)
	s_waitcnt lgkmcnt(0)
	s_barrier
	s_waitcnt lgkmcnt(0)
	v_mfma_f32_16x16x32_bf16 v[62:65], v[142:145], v[192:195], v[62:65]
	v_mfma_f32_16x16x32_bf16 v[62:65], v[146:149], v[196:199], v[62:65]
	v_mfma_f32_16x16x32_bf16 v[58:61], v[168:171], v[192:195], v[58:61]
	v_mfma_f32_16x16x32_bf16 v[58:61], v[172:175], v[196:199], v[58:61]
	v_mfma_f32_16x16x32_bf16 v[46:49], v[142:145], v[200:203], v[46:49]
	v_mfma_f32_16x16x32_bf16 v[46:49], v[146:149], v[204:207], v[46:49]
	v_mfma_f32_16x16x32_bf16 v[42:45], v[168:171], v[200:203], v[42:45]
	v_mfma_f32_16x16x32_bf16 v[42:45], v[172:175], v[204:207], v[42:45]
	v_mfma_f32_16x16x32_bf16 v[30:33], v[142:145], v[216:219], v[30:33]
	v_mfma_f32_16x16x32_bf16 v[30:33], v[146:149], v[220:223], v[30:33]
	v_mfma_f32_16x16x32_bf16 v[26:29], v[168:171], v[216:219], v[26:29]
	v_mfma_f32_16x16x32_bf16 v[26:29], v[172:175], v[220:223], v[26:29]
	v_mfma_f32_16x16x32_bf16 v[14:17], v[142:145], v[224:227], v[14:17]
	v_mfma_f32_16x16x32_bf16 v[14:17], v[146:149], v[228:231], v[14:17]
	v_mfma_f32_16x16x32_bf16 v[10:13], v[168:171], v[224:227], v[10:13]
	v_mfma_f32_16x16x32_bf16 v[10:13], v[172:175], v[228:231], v[10:13]
	v_mfma_f32_16x16x32_bf16 v[54:57], v[176:179], v[192:195], v[54:57]
	v_mfma_f32_16x16x32_bf16 v[54:57], v[180:183], v[196:199], v[54:57]
	v_mfma_f32_16x16x32_bf16 v[50:53], v[184:187], v[192:195], v[50:53]
	v_mfma_f32_16x16x32_bf16 v[50:53], v[188:191], v[196:199], v[50:53]
	v_mfma_f32_16x16x32_bf16 v[38:41], v[176:179], v[200:203], v[38:41]
	v_mfma_f32_16x16x32_bf16 v[38:41], v[180:183], v[204:207], v[38:41]
	v_mfma_f32_16x16x32_bf16 v[34:37], v[184:187], v[200:203], v[34:37]
	v_mfma_f32_16x16x32_bf16 v[34:37], v[188:191], v[204:207], v[34:37]
	v_mfma_f32_16x16x32_bf16 v[22:25], v[176:179], v[216:219], v[22:25]
	v_mfma_f32_16x16x32_bf16 v[22:25], v[180:183], v[220:223], v[22:25]
	v_mfma_f32_16x16x32_bf16 v[18:21], v[184:187], v[216:219], v[18:21]
	v_mfma_f32_16x16x32_bf16 v[18:21], v[188:191], v[220:223], v[18:21]
	v_mfma_f32_16x16x32_bf16 v[6:9], v[176:179], v[224:227], v[6:9]
	v_mfma_f32_16x16x32_bf16 v[6:9], v[180:183], v[228:231], v[6:9]
	v_mfma_f32_16x16x32_bf16 v[2:5], v[184:187], v[224:227], v[2:5]
	v_mfma_f32_16x16x32_bf16 v[2:5], v[188:191], v[228:231], v[2:5]
	s_barrier
	s_add_i32 s29, s29, 2
	s_add_u32 s50, s50, 0x100
	s_addc_u32 s51, s51, 0
	s_add_u32 s17, s17, 0x100
	s_addc_u32 s23, s23, 0
	s_cmp_gt_u32 s29, 29

.Lsp_LBB0801:
	s_add_u32 s14, s50, 0xfff80080
	s_addc_u32 s15, s51, -1
	s_add_i32 s30, 0, 0x10000
	s_cmp_eq_u32 s29, 28
	s_cselect_b32 s65, s43, s15
	s_cselect_b32 s64, s42, s14
	v_add_u32_e32 v150, s30, v152
	s_cselect_b32 s15, s1, s23
	s_cselect_b32 s14, s16, s17
	s_add_i32 s34, 0, 0x14000
	ds_read_b128 v[142:145], v150
	ds_read_b128 v[146:149], v150 offset:1024
	ds_read_b128 v[168:171], v150 offset:2048
	ds_read_b128 v[172:175], v150 offset:3072
	v_add_u32_e32 v150, s34, v152
	ds_read_b128 v[176:179], v150
	ds_read_b128 v[180:183], v150 offset:1024
	ds_read_b128 v[184:187], v150 offset:2048
	ds_read_b128 v[188:191], v150 offset:3072
	v_lshl_add_u64 v[150:151], s[50:51], 0, v[138:139]
	s_add_i32 m0, s58, 0xc000
	ds_read_b128 v[192:195], v155
	ds_read_b128 v[196:199], v155 offset:1024
	ds_read_b128 v[200:203], v155 offset:2048
	ds_read_b128 v[204:207], v155 offset:3072
	ds_read_b128 v[216:219], v155 offset:4096
	ds_read_b128 v[220:223], v155 offset:5120
	ds_read_b128 v[224:227], v155 offset:6144
	ds_read_b128 v[228:231], v155 offset:7168
	global_load_lds_dwordx4 v[150:151], off
	v_lshl_add_u64 v[150:151], s[50:51], 0, v[140:141]
	s_add_i32 m0, s58, 0xe000
	s_nop 0
	global_load_lds_dwordx4 v[150:151], off
	s_waitcnt vmcnt(8)
	s_waitcnt lgkmcnt(0)
	s_barrier
	s_nop 0
	s_waitcnt lgkmcnt(0)
	v_mfma_f32_16x16x32_bf16 v[126:129], v[142:145], v[192:195], v[126:129]
	v_mfma_f32_16x16x32_bf16 v[126:129], v[146:149], v[196:199], v[126:129]
	v_mfma_f32_16x16x32_bf16 v[122:125], v[168:171], v[192:195], v[122:125]
	v_mfma_f32_16x16x32_bf16 v[122:125], v[172:175], v[196:199], v[122:125]
	v_mfma_f32_16x16x32_bf16 v[110:113], v[142:145], v[200:203], v[110:113]
	v_mfma_f32_16x16x32_bf16 v[110:113], v[146:149], v[204:207], v[110:113]
	v_mfma_f32_16x16x32_bf16 v[106:109], v[168:171], v[200:203], v[106:109]
	v_mfma_f32_16x16x32_bf16 v[106:109], v[172:175], v[204:207], v[106:109]
	v_mfma_f32_16x16x32_bf16 v[94:97], v[142:145], v[216:219], v[94:97]
	v_mfma_f32_16x16x32_bf16 v[94:97], v[146:149], v[220:223], v[94:97]
	v_mfma_f32_16x16x32_bf16 v[90:93], v[168:171], v[216:219], v[90:93]
	v_mfma_f32_16x16x32_bf16 v[90:93], v[172:175], v[220:223], v[90:93]
	v_mfma_f32_16x16x32_bf16 v[78:81], v[142:145], v[224:227], v[78:81]
	v_mfma_f32_16x16x32_bf16 v[78:81], v[146:149], v[228:231], v[78:81]
	v_mfma_f32_16x16x32_bf16 v[74:77], v[168:171], v[224:227], v[74:77]
	v_mfma_f32_16x16x32_bf16 v[74:77], v[172:175], v[228:231], v[74:77]
	v_mfma_f32_16x16x32_bf16 v[118:121], v[176:179], v[192:195], v[118:121]
	v_mfma_f32_16x16x32_bf16 v[118:121], v[180:183], v[196:199], v[118:121]
	v_mfma_f32_16x16x32_bf16 v[114:117], v[184:187], v[192:195], v[114:117]
	v_mfma_f32_16x16x32_bf16 v[114:117], v[188:191], v[196:199], v[114:117]
	v_mfma_f32_16x16x32_bf16 v[102:105], v[176:179], v[200:203], v[102:105]
	v_mfma_f32_16x16x32_bf16 v[102:105], v[180:183], v[204:207], v[102:105]
	v_mfma_f32_16x16x32_bf16 v[98:101], v[184:187], v[200:203], v[98:101]
	v_mfma_f32_16x16x32_bf16 v[98:101], v[188:191], v[204:207], v[98:101]
	v_mfma_f32_16x16x32_bf16 v[86:89], v[176:179], v[216:219], v[86:89]
	v_mfma_f32_16x16x32_bf16 v[86:89], v[180:183], v[220:223], v[86:89]
	v_mfma_f32_16x16x32_bf16 v[82:85], v[184:187], v[216:219], v[82:85]
	v_mfma_f32_16x16x32_bf16 v[82:85], v[188:191], v[220:223], v[82:85]
	v_mfma_f32_16x16x32_bf16 v[70:73], v[176:179], v[224:227], v[70:73]
	v_mfma_f32_16x16x32_bf16 v[70:73], v[180:183], v[228:231], v[70:73]
	v_mfma_f32_16x16x32_bf16 v[66:69], v[184:187], v[224:227], v[66:69]
	v_mfma_f32_16x16x32_bf16 v[66:69], v[188:191], v[228:231], v[66:69]
	s_barrier
	s_add_i32 s30, s30, s11
	v_lshl_add_u64 v[150:151], s[14:15], 0, v[158:159]
	s_mov_b32 m0, s30
	ds_read_b128 v[192:195], v155 offset:16384
	ds_read_b128 v[196:199], v155 offset:17408
	ds_read_b128 v[200:203], v155 offset:18432
	ds_read_b128 v[204:207], v155 offset:19456
	ds_read_b128 v[216:219], v155 offset:20480
	ds_read_b128 v[220:223], v155 offset:21504
	ds_read_b128 v[224:227], v155 offset:22528
	ds_read_b128 v[228:231], v155 offset:23552
	global_load_lds_dwordx4 v[150:151], off
	s_add_i32 m0, s30, 0x2000
	s_add_u32 s30, s14, 0x80000
	v_lshl_add_u64 v[156:157], s[14:15], 0, v[134:135]
	s_addc_u32 s31, s15, 0
	s_add_i32 s34, s34, s11
	global_load_lds_dwordx4 v[156:157], off
	v_lshl_add_u64 v[232:233], s[30:31], 0, v[158:159]
	s_mov_b32 m0, s34
	v_lshl_add_u64 v[234:235], s[64:65], 0, v[132:133]
	global_load_lds_dwordx4 v[232:233], off
	v_lshl_add_u64 v[232:233], s[30:31], 0, v[134:135]
	s_add_i32 m0, s34, 0x2000
	s_nop 0
	global_load_lds_dwordx4 v[232:233], off
	v_lshl_add_u64 v[232:233], s[64:65], 0, v[130:131]
	s_mov_b32 m0, s58
	s_nop 0
	global_load_lds_dwordx4 v[232:233], off
	s_mov_b32 m0, s24
	s_nop 0
	global_load_lds_dwordx4 v[234:235], off
	s_waitcnt vmcnt(8)
	s_waitcnt lgkmcnt(0)
	s_barrier
	s_nop 0
	s_waitcnt lgkmcnt(0)
	v_mfma_f32_16x16x32_bf16 v[62:65], v[142:145], v[192:195], v[62:65]
	v_mfma_f32_16x16x32_bf16 v[62:65], v[146:149], v[196:199], v[62:65]
	v_mfma_f32_16x16x32_bf16 v[58:61], v[168:171], v[192:195], v[58:61]
	v_mfma_f32_16x16x32_bf16 v[58:61], v[172:175], v[196:199], v[58:61]
	v_mfma_f32_16x16x32_bf16 v[46:49], v[142:145], v[200:203], v[46:49]
	v_mfma_f32_16x16x32_bf16 v[46:49], v[146:149], v[204:207], v[46:49]
	v_mfma_f32_16x16x32_bf16 v[42:45], v[168:171], v[200:203], v[42:45]
	v_mfma_f32_16x16x32_bf16 v[42:45], v[172:175], v[204:207], v[42:45]
	v_mfma_f32_16x16x32_bf16 v[30:33], v[142:145], v[216:219], v[30:33]
	v_mfma_f32_16x16x32_bf16 v[30:33], v[146:149], v[220:223], v[30:33]
	v_mfma_f32_16x16x32_bf16 v[26:29], v[168:171], v[216:219], v[26:29]
	v_mfma_f32_16x16x32_bf16 v[26:29], v[172:175], v[220:223], v[26:29]
	v_mfma_f32_16x16x32_bf16 v[14:17], v[142:145], v[224:227], v[14:17]
	v_mfma_f32_16x16x32_bf16 v[14:17], v[146:149], v[228:231], v[14:17]
	v_mfma_f32_16x16x32_bf16 v[10:13], v[168:171], v[224:227], v[10:13]
	v_mfma_f32_16x16x32_bf16 v[10:13], v[172:175], v[228:231], v[10:13]
	v_mfma_f32_16x16x32_bf16 v[54:57], v[176:179], v[192:195], v[54:57]
	v_mfma_f32_16x16x32_bf16 v[54:57], v[180:183], v[196:199], v[54:57]
	v_mfma_f32_16x16x32_bf16 v[50:53], v[184:187], v[192:195], v[50:53]
	v_mfma_f32_16x16x32_bf16 v[50:53], v[188:191], v[196:199], v[50:53]
	v_mfma_f32_16x16x32_bf16 v[38:41], v[176:179], v[200:203], v[38:41]
	v_mfma_f32_16x16x32_bf16 v[38:41], v[180:183], v[204:207], v[38:41]
	v_mfma_f32_16x16x32_bf16 v[34:37], v[184:187], v[200:203], v[34:37]
	v_mfma_f32_16x16x32_bf16 v[34:37], v[188:191], v[204:207], v[34:37]
	v_mfma_f32_16x16x32_bf16 v[22:25], v[176:179], v[216:219], v[22:25]
	v_mfma_f32_16x16x32_bf16 v[22:25], v[180:183], v[220:223], v[22:25]
	v_mfma_f32_16x16x32_bf16 v[18:21], v[184:187], v[216:219], v[18:21]
	v_mfma_f32_16x16x32_bf16 v[18:21], v[188:191], v[220:223], v[18:21]
	v_mfma_f32_16x16x32_bf16 v[6:9], v[176:179], v[224:227], v[6:9]
	v_mfma_f32_16x16x32_bf16 v[6:9], v[180:183], v[228:231], v[6:9]
	v_mfma_f32_16x16x32_bf16 v[2:5], v[184:187], v[224:227], v[2:5]
	v_mfma_f32_16x16x32_bf16 v[2:5], v[188:191], v[228:231], v[2:5]
	s_barrier
	s_add_i32 s34, 0, 0x18000
	v_add_u32_e32 v161, s34, v152
	s_add_i32 s35, 0, 0x1c000
	ds_read_b128 v[142:145], v161
	ds_read_b128 v[146:149], v161 offset:1024
	ds_read_b128 v[168:171], v161 offset:2048
	ds_read_b128 v[172:175], v161 offset:3072
	v_add_u32_e32 v161, s35, v152
	ds_read_b128 v[176:179], v161
	ds_read_b128 v[180:183], v161 offset:1024
	ds_read_b128 v[184:187], v161 offset:2048
	ds_read_b128 v[188:191], v161 offset:3072
	s_add_u32 s30, s64, 0x80000
	s_addc_u32 s31, s65, 0
	s_mov_b32 m0, s25
	v_lshl_add_u64 v[236:237], s[30:31], 0, v[130:131]
	ds_read_b128 v[192:195], v155 offset:32768
	ds_read_b128 v[196:199], v155 offset:33792
	ds_read_b128 v[200:203], v155 offset:34816
	ds_read_b128 v[204:207], v155 offset:35840
	ds_read_b128 v[216:219], v155 offset:36864
	ds_read_b128 v[220:223], v155 offset:37888
	ds_read_b128 v[224:227], v155 offset:38912
	ds_read_b128 v[228:231], v155 offset:39936
	global_load_lds_dwordx4 v[236:237], off
	v_lshl_add_u64 v[236:237], s[30:31], 0, v[132:133]
	s_mov_b32 m0, s59
	s_nop 0
	global_load_lds_dwordx4 v[236:237], off
	s_waitcnt vmcnt(8)
	s_waitcnt lgkmcnt(0)
	s_barrier
	s_nop 0
	s_waitcnt lgkmcnt(0)
	v_mfma_f32_16x16x32_bf16 v[126:129], v[142:145], v[192:195], v[126:129]
	v_mfma_f32_16x16x32_bf16 v[126:129], v[146:149], v[196:199], v[126:129]
	v_mfma_f32_16x16x32_bf16 v[122:125], v[168:171], v[192:195], v[122:125]
	v_mfma_f32_16x16x32_bf16 v[122:125], v[172:175], v[196:199], v[122:125]
	v_mfma_f32_16x16x32_bf16 v[110:113], v[142:145], v[200:203], v[110:113]
	v_mfma_f32_16x16x32_bf16 v[110:113], v[146:149], v[204:207], v[110:113]
	v_mfma_f32_16x16x32_bf16 v[106:109], v[168:171], v[200:203], v[106:109]
	v_mfma_f32_16x16x32_bf16 v[106:109], v[172:175], v[204:207], v[106:109]
	v_mfma_f32_16x16x32_bf16 v[94:97], v[142:145], v[216:219], v[94:97]
	v_mfma_f32_16x16x32_bf16 v[94:97], v[146:149], v[220:223], v[94:97]
	v_mfma_f32_16x16x32_bf16 v[90:93], v[168:171], v[216:219], v[90:93]
	v_mfma_f32_16x16x32_bf16 v[90:93], v[172:175], v[220:223], v[90:93]
	v_mfma_f32_16x16x32_bf16 v[78:81], v[142:145], v[224:227], v[78:81]
	v_mfma_f32_16x16x32_bf16 v[78:81], v[146:149], v[228:231], v[78:81]
	v_mfma_f32_16x16x32_bf16 v[74:77], v[168:171], v[224:227], v[74:77]
	v_mfma_f32_16x16x32_bf16 v[74:77], v[172:175], v[228:231], v[74:77]
	v_mfma_f32_16x16x32_bf16 v[118:121], v[176:179], v[192:195], v[118:121]
	v_mfma_f32_16x16x32_bf16 v[118:121], v[180:183], v[196:199], v[118:121]
	v_mfma_f32_16x16x32_bf16 v[114:117], v[184:187], v[192:195], v[114:117]
	v_mfma_f32_16x16x32_bf16 v[114:117], v[188:191], v[196:199], v[114:117]
	v_mfma_f32_16x16x32_bf16 v[102:105], v[176:179], v[200:203], v[102:105]
	v_mfma_f32_16x16x32_bf16 v[102:105], v[180:183], v[204:207], v[102:105]
	v_mfma_f32_16x16x32_bf16 v[98:101], v[184:187], v[200:203], v[98:101]
	v_mfma_f32_16x16x32_bf16 v[98:101], v[188:191], v[204:207], v[98:101]
	v_mfma_f32_16x16x32_bf16 v[86:89], v[176:179], v[216:219], v[86:89]
	v_mfma_f32_16x16x32_bf16 v[86:89], v[180:183], v[220:223], v[86:89]
	v_mfma_f32_16x16x32_bf16 v[82:85], v[184:187], v[216:219], v[82:85]
	v_mfma_f32_16x16x32_bf16 v[82:85], v[188:191], v[220:223], v[82:85]
	v_mfma_f32_16x16x32_bf16 v[70:73], v[176:179], v[224:227], v[70:73]
	v_mfma_f32_16x16x32_bf16 v[70:73], v[180:183], v[228:231], v[70:73]
	v_mfma_f32_16x16x32_bf16 v[66:69], v[184:187], v[224:227], v[66:69]
	v_mfma_f32_16x16x32_bf16 v[66:69], v[188:191], v[228:231], v[66:69]
	s_barrier
	s_add_i32 s30, s34, s11
	v_lshl_add_u64 v[150:151], v[150:151], 0, s[56:57]
	s_mov_b32 m0, s30
	ds_read_b128 v[192:195], v155 offset:49152
	ds_read_b128 v[196:199], v155 offset:50176
	ds_read_b128 v[200:203], v155 offset:51200
	ds_read_b128 v[204:207], v155 offset:52224
	ds_read_b128 v[216:219], v155 offset:53248
	ds_read_b128 v[220:223], v155 offset:54272
	ds_read_b128 v[224:227], v155 offset:55296
	ds_read_b128 v[228:231], v155 offset:56320
	global_load_lds_dwordx4 v[150:151], off
	s_add_i32 m0, s30, 0x2000
	s_add_u32 s14, s14, 0x80080
	v_lshl_add_u64 v[150:151], v[156:157], 0, s[56:57]
	s_addc_u32 s15, s15, 0
	s_add_i32 s30, s35, s11
	global_load_lds_dwordx4 v[150:151], off
	v_lshl_add_u64 v[150:151], s[14:15], 0, v[158:159]
	s_mov_b32 m0, s30
	s_nop 0
	global_load_lds_dwordx4 v[150:151], off
	v_lshl_add_u64 v[150:151], s[14:15], 0, v[134:135]
	s_add_i32 m0, s30, 0x2000
	s_nop 0
	global_load_lds_dwordx4 v[150:151], off
	v_lshl_add_u64 v[150:151], v[232:233], 0, s[56:57]
	s_mov_b32 m0, s26
	s_nop 0
	global_load_lds_dwordx4 v[150:151], off
	v_lshl_add_u64 v[150:151], v[234:235], 0, s[56:57]
	s_mov_b32 m0, s27
	s_nop 0
	global_load_lds_dwordx4 v[150:151], off
	s_waitcnt vmcnt(8)
	s_waitcnt lgkmcnt(0)
	s_barrier
	s_waitcnt lgkmcnt(0)
	v_mfma_f32_16x16x32_bf16 v[62:65], v[142:145], v[192:195], v[62:65]
	v_mfma_f32_16x16x32_bf16 v[62:65], v[146:149], v[196:199], v[62:65]
	v_mfma_f32_16x16x32_bf16 v[58:61], v[168:171], v[192:195], v[58:61]
	v_mfma_f32_16x16x32_bf16 v[58:61], v[172:175], v[196:199], v[58:61]
	v_mfma_f32_16x16x32_bf16 v[46:49], v[142:145], v[200:203], v[46:49]
	v_mfma_f32_16x16x32_bf16 v[46:49], v[146:149], v[204:207], v[46:49]
	v_mfma_f32_16x16x32_bf16 v[42:45], v[168:171], v[200:203], v[42:45]
	v_mfma_f32_16x16x32_bf16 v[42:45], v[172:175], v[204:207], v[42:45]
	v_mfma_f32_16x16x32_bf16 v[30:33], v[142:145], v[216:219], v[30:33]
	v_mfma_f32_16x16x32_bf16 v[30:33], v[146:149], v[220:223], v[30:33]
	v_mfma_f32_16x16x32_bf16 v[26:29], v[168:171], v[216:219], v[26:29]
	v_mfma_f32_16x16x32_bf16 v[26:29], v[172:175], v[220:223], v[26:29]
	v_mfma_f32_16x16x32_bf16 v[14:17], v[142:145], v[224:227], v[14:17]
	v_mfma_f32_16x16x32_bf16 v[14:17], v[146:149], v[228:231], v[14:17]
	v_mfma_f32_16x16x32_bf16 v[10:13], v[168:171], v[224:227], v[10:13]
	v_mfma_f32_16x16x32_bf16 v[10:13], v[172:175], v[228:231], v[10:13]
	v_mfma_f32_16x16x32_bf16 v[54:57], v[176:179], v[192:195], v[54:57]
	v_mfma_f32_16x16x32_bf16 v[54:57], v[180:183], v[196:199], v[54:57]
	v_mfma_f32_16x16x32_bf16 v[50:53], v[184:187], v[192:195], v[50:53]
	v_mfma_f32_16x16x32_bf16 v[50:53], v[188:191], v[196:199], v[50:53]
	v_mfma_f32_16x16x32_bf16 v[38:41], v[176:179], v[200:203], v[38:41]
	v_mfma_f32_16x16x32_bf16 v[38:41], v[180:183], v[204:207], v[38:41]
	v_mfma_f32_16x16x32_bf16 v[34:37], v[184:187], v[200:203], v[34:37]
	v_mfma_f32_16x16x32_bf16 v[34:37], v[188:191], v[204:207], v[34:37]
	v_mfma_f32_16x16x32_bf16 v[22:25], v[176:179], v[216:219], v[22:25]
	v_mfma_f32_16x16x32_bf16 v[22:25], v[180:183], v[220:223], v[22:25]
	v_mfma_f32_16x16x32_bf16 v[18:21], v[184:187], v[216:219], v[18:21]
	v_mfma_f32_16x16x32_bf16 v[18:21], v[188:191], v[220:223], v[18:21]
	v_mfma_f32_16x16x32_bf16 v[6:9], v[176:179], v[224:227], v[6:9]
	v_mfma_f32_16x16x32_bf16 v[6:9], v[180:183], v[228:231], v[6:9]
	v_mfma_f32_16x16x32_bf16 v[2:5], v[184:187], v[224:227], v[2:5]
	v_mfma_f32_16x16x32_bf16 v[2:5], v[188:191], v[228:231], v[2:5]
	s_barrier
	s_add_i32 s29, s29, 2
	s_add_u32 s50, s50, 0x100
	s_addc_u32 s51, s51, 0
	s_add_u32 s17, s17, 0x100
	s_addc_u32 s23, s23, 0
	s_cmp_gt_u32 s29, 29
	s_cbranch_scc0 .LBB0_801
	s_and_b64 vcc, exec, s[20:21]
	s_cbranch_vccz .LBB0_804
	s_barrier

.LBB0_1186:
	s_add_u32 s16, s38, s11
	s_addc_u32 s17, s39, 0
	s_add_u32 s21, s16, 0x100
	s_addc_u32 s24, s17, 0
	s_and_b64 s[14:15], s[64:65], exec
	s_cselect_b32 s69, s49, s24
	s_cselect_b32 s68, s48, s21
	s_add_u32 s11, s0, s11
	s_addc_u32 s14, s1, 0
	s_add_u32 s11, s11, 0x100
	s_addc_u32 s21, s14, 0
	s_add_i32 s28, 0, 0x10000
	s_and_b64 s[14:15], s[64:65], exec
	s_cselect_b32 s15, s9, s21
	s_cselect_b32 s14, s10, s11
	s_add_i32 s29, 0, 0x14000
	s_add_u32 s72, s16, 0x40080
	s_addc_u32 s73, s17, 0
	s_add_i32 s27, s28, s58
	s_add_i32 m0, s13, 0xc000
	s_add_i32 s30, s13, 0xe000
	s_add_i32 s24, s27, 0x2000
	s_add_u32 s70, s14, 0x10000
	v_add_u32_e32 v150, s28, v161
	v_add_u32_e32 v172, s29, v161
	s_addc_u32 s71, s15, 0
	s_add_i32 s26, s29, s58
	ds_read_b128 v[130:133], v150
	ds_read_b128 v[134:137], v150 offset:1024
	ds_read_b128 v[138:141], v150 offset:2048
	ds_read_b128 v[150:153], v150 offset:3072
	ds_read_b128 v[154:157], v172
	ds_read_b128 v[168:171], v172 offset:1024
	ds_read_b128 v[178:181], v172 offset:2048
	ds_read_b128 v[182:185], v172 offset:3072
	s_add_i32 s25, s26, 0x2000
	s_add_i32 s21, 0, 0x18000
	s_add_i32 s17, 0, 0x1c000
	s_add_u32 s66, s68, 0x40000
	s_addc_u32 s67, s69, 0
	s_add_i32 s16, s21, s58
	s_add_i32 s11, s16, 0x2000
	s_add_u32 s64, s14, 0x10080
	s_addc_u32 s65, s15, 0
	s_add_i32 s29, s17, s58
	s_add_i32 s28, s29, 0x2000
	v_lshl_add_u64 v[172:173], s[72:73], 0, v[142:143]
	ds_read_b128 v[186:189], v176
	ds_read_b128 v[190:193], v176 offset:1024
	ds_read_b128 v[194:197], v176 offset:2048
	ds_read_b128 v[198:201], v176 offset:3072
	ds_read_b128 v[202:205], v176 offset:4096
	ds_read_b128 v[216:219], v176 offset:5120
	ds_read_b128 v[220:223], v176 offset:6144
	ds_read_b128 v[224:227], v176 offset:7168
	global_load_lds_dwordx4 v[172:173], off
	v_lshl_add_u64 v[172:173], s[72:73], 0, v[144:145]
	s_mov_b32 m0, s30
	s_nop 0
	global_load_lds_dwordx4 v[172:173], off
	s_waitcnt vmcnt(8)
	s_waitcnt lgkmcnt(0)
	s_barrier
	s_nop 0
	s_setprio 1
	s_waitcnt lgkmcnt(0)
	v_mfma_f32_16x16x32_bf16 v[126:129], v[130:133], v[186:189], v[126:129]
	v_mfma_f32_16x16x32_bf16 v[126:129], v[134:137], v[190:193], v[126:129]
	v_mfma_f32_16x16x32_bf16 v[62:65], v[138:141], v[186:189], v[62:65]
	v_mfma_f32_16x16x32_bf16 v[62:65], v[150:153], v[190:193], v[62:65]
	v_mfma_f32_16x16x32_bf16 v[118:121], v[130:133], v[194:197], v[118:121]
	v_mfma_f32_16x16x32_bf16 v[118:121], v[134:137], v[198:201], v[118:121]
	v_mfma_f32_16x16x32_bf16 v[54:57], v[138:141], v[194:197], v[54:57]
	v_mfma_f32_16x16x32_bf16 v[54:57], v[150:153], v[198:201], v[54:57]
	v_mfma_f32_16x16x32_bf16 v[110:113], v[130:133], v[202:205], v[110:113]
	v_mfma_f32_16x16x32_bf16 v[110:113], v[134:137], v[216:219], v[110:113]
	v_mfma_f32_16x16x32_bf16 v[46:49], v[138:141], v[202:205], v[46:49]
	v_mfma_f32_16x16x32_bf16 v[46:49], v[150:153], v[216:219], v[46:49]
	v_mfma_f32_16x16x32_bf16 v[102:105], v[130:133], v[220:223], v[102:105]
	v_mfma_f32_16x16x32_bf16 v[102:105], v[134:137], v[224:227], v[102:105]
	v_mfma_f32_16x16x32_bf16 v[38:41], v[138:141], v[220:223], v[38:41]
	v_mfma_f32_16x16x32_bf16 v[38:41], v[150:153], v[224:227], v[38:41]
	s_setprio 0
	s_setprio 1
	v_mfma_f32_16x16x32_bf16 v[122:125], v[154:157], v[186:189], v[122:125]
	v_mfma_f32_16x16x32_bf16 v[122:125], v[168:171], v[190:193], v[122:125]
	v_mfma_f32_16x16x32_bf16 v[58:61], v[178:181], v[186:189], v[58:61]
	v_mfma_f32_16x16x32_bf16 v[58:61], v[182:185], v[190:193], v[58:61]
	v_mfma_f32_16x16x32_bf16 v[114:117], v[154:157], v[194:197], v[114:117]
	v_mfma_f32_16x16x32_bf16 v[114:117], v[168:171], v[198:201], v[114:117]
	v_mfma_f32_16x16x32_bf16 v[50:53], v[178:181], v[194:197], v[50:53]
	v_mfma_f32_16x16x32_bf16 v[50:53], v[182:185], v[198:201], v[50:53]
	v_mfma_f32_16x16x32_bf16 v[106:109], v[154:157], v[202:205], v[106:109]
	v_mfma_f32_16x16x32_bf16 v[106:109], v[168:171], v[216:219], v[106:109]
	v_mfma_f32_16x16x32_bf16 v[42:45], v[178:181], v[202:205], v[42:45]
	v_mfma_f32_16x16x32_bf16 v[42:45], v[182:185], v[216:219], v[42:45]
	v_mfma_f32_16x16x32_bf16 v[98:101], v[154:157], v[220:223], v[98:101]
	v_mfma_f32_16x16x32_bf16 v[98:101], v[168:171], v[224:227], v[98:101]
	v_mfma_f32_16x16x32_bf16 v[34:37], v[178:181], v[220:223], v[34:37]
	v_mfma_f32_16x16x32_bf16 v[34:37], v[182:185], v[224:227], v[34:37]
	s_setprio 0
	s_barrier
	s_mov_b32 m0, s27
	v_lshl_add_u64 v[172:173], s[14:15], 0, v[158:159]
	ds_read_b128 v[186:189], v176 offset:16384
	ds_read_b128 v[190:193], v176 offset:17408
	ds_read_b128 v[194:197], v176 offset:18432
	ds_read_b128 v[198:201], v176 offset:19456
	ds_read_b128 v[202:205], v176 offset:20480
	ds_read_b128 v[216:219], v176 offset:21504
	ds_read_b128 v[220:223], v176 offset:22528
	ds_read_b128 v[224:227], v176 offset:23552
	global_load_lds_dwordx4 v[172:173], off
	v_lshl_add_u64 v[206:207], s[14:15], 0, v[146:147]
	s_mov_b32 m0, s24
	v_lshl_add_u64 v[228:229], s[70:71], 0, v[158:159]
	global_load_lds_dwordx4 v[206:207], off
	s_mov_b32 m0, s26
	v_lshl_add_u64 v[230:231], s[68:69], 0, v[144:145]
	global_load_lds_dwordx4 v[228:229], off
	v_lshl_add_u64 v[228:229], s[70:71], 0, v[146:147]
	s_mov_b32 m0, s25
	s_nop 0
	global_load_lds_dwordx4 v[228:229], off
	v_lshl_add_u64 v[228:229], s[68:69], 0, v[142:143]
	s_mov_b32 m0, s13
	s_nop 0
	global_load_lds_dwordx4 v[228:229], off
	s_mov_b32 m0, s23
	s_nop 0
	global_load_lds_dwordx4 v[230:231], off
	s_waitcnt vmcnt(8)
	s_waitcnt lgkmcnt(0)
	s_barrier
	s_setprio 1
	s_waitcnt lgkmcnt(0)
	v_mfma_f32_16x16x32_bf16 v[94:97], v[130:133], v[186:189], v[94:97]
	v_mfma_f32_16x16x32_bf16 v[94:97], v[134:137], v[190:193], v[94:97]
	v_mfma_f32_16x16x32_bf16 v[30:33], v[138:141], v[186:189], v[30:33]
	v_mfma_f32_16x16x32_bf16 v[30:33], v[150:153], v[190:193], v[30:33]
	v_mfma_f32_16x16x32_bf16 v[86:89], v[130:133], v[194:197], v[86:89]
	v_mfma_f32_16x16x32_bf16 v[86:89], v[134:137], v[198:201], v[86:89]
	v_mfma_f32_16x16x32_bf16 v[22:25], v[138:141], v[194:197], v[22:25]
	v_mfma_f32_16x16x32_bf16 v[22:25], v[150:153], v[198:201], v[22:25]
	v_mfma_f32_16x16x32_bf16 v[78:81], v[130:133], v[202:205], v[78:81]
	v_mfma_f32_16x16x32_bf16 v[78:81], v[134:137], v[216:219], v[78:81]
	v_mfma_f32_16x16x32_bf16 v[14:17], v[138:141], v[202:205], v[14:17]
	v_mfma_f32_16x16x32_bf16 v[14:17], v[150:153], v[216:219], v[14:17]
	v_mfma_f32_16x16x32_bf16 v[70:73], v[130:133], v[220:223], v[70:73]
	v_mfma_f32_16x16x32_bf16 v[70:73], v[134:137], v[224:227], v[70:73]
	v_mfma_f32_16x16x32_bf16 v[6:9], v[138:141], v[220:223], v[6:9]
	v_mfma_f32_16x16x32_bf16 v[6:9], v[150:153], v[224:227], v[6:9]
	s_setprio 0
	s_setprio 1
	v_mfma_f32_16x16x32_bf16 v[90:93], v[154:157], v[186:189], v[90:93]
	v_mfma_f32_16x16x32_bf16 v[90:93], v[168:171], v[190:193], v[90:93]
	v_mfma_f32_16x16x32_bf16 v[26:29], v[178:181], v[186:189], v[26:29]
	v_mfma_f32_16x16x32_bf16 v[26:29], v[182:185], v[190:193], v[26:29]
	v_mfma_f32_16x16x32_bf16 v[82:85], v[154:157], v[194:197], v[82:85]
	v_mfma_f32_16x16x32_bf16 v[82:85], v[168:171], v[198:201], v[82:85]
	v_mfma_f32_16x16x32_bf16 v[18:21], v[178:181], v[194:197], v[18:21]
	v_mfma_f32_16x16x32_bf16 v[18:21], v[182:185], v[198:201], v[18:21]
	v_mfma_f32_16x16x32_bf16 v[74:77], v[154:157], v[202:205], v[74:77]
	v_mfma_f32_16x16x32_bf16 v[74:77], v[168:171], v[216:219], v[74:77]
	v_mfma_f32_16x16x32_bf16 v[10:13], v[178:181], v[202:205], v[10:13]
	v_mfma_f32_16x16x32_bf16 v[10:13], v[182:185], v[216:219], v[10:13]
	v_mfma_f32_16x16x32_bf16 v[66:69], v[154:157], v[220:223], v[66:69]
	v_mfma_f32_16x16x32_bf16 v[66:69], v[168:171], v[224:227], v[66:69]
	v_mfma_f32_16x16x32_bf16 v[2:5], v[178:181], v[220:223], v[2:5]
	v_mfma_f32_16x16x32_bf16 v[2:5], v[182:185], v[224:227], v[2:5]
	s_setprio 0
	s_barrier
	v_add_u32_e32 v150, s21, v161
	v_add_u32_e32 v177, s17, v161
	ds_read_b128 v[130:133], v150
	ds_read_b128 v[134:137], v150 offset:1024
	ds_read_b128 v[138:141], v150 offset:2048
	ds_read_b128 v[150:153], v150 offset:3072
	ds_read_b128 v[154:157], v177
	ds_read_b128 v[168:171], v177 offset:1024
	ds_read_b128 v[178:181], v177 offset:2048
	ds_read_b128 v[182:185], v177 offset:3072
	s_mov_b32 m0, s59
	v_lshl_add_u64 v[232:233], s[66:67], 0, v[142:143]
	ds_read_b128 v[186:189], v176 offset:32768
	ds_read_b128 v[190:193], v176 offset:33792
	ds_read_b128 v[194:197], v176 offset:34816
	ds_read_b128 v[198:201], v176 offset:35840
	ds_read_b128 v[202:205], v176 offset:36864
	ds_read_b128 v[216:219], v176 offset:37888
	ds_read_b128 v[220:223], v176 offset:38912
	ds_read_b128 v[224:227], v176 offset:39936
	global_load_lds_dwordx4 v[232:233], off
	v_lshl_add_u64 v[232:233], s[66:67], 0, v[144:145]
	s_mov_b32 m0, s31
	s_nop 0
	global_load_lds_dwordx4 v[232:233], off
	s_waitcnt vmcnt(8)
	s_waitcnt lgkmcnt(0)
	s_barrier
	s_setprio 1
	s_waitcnt lgkmcnt(0)
	v_mfma_f32_16x16x32_bf16 v[126:129], v[130:133], v[186:189], v[126:129]
	v_mfma_f32_16x16x32_bf16 v[126:129], v[134:137], v[190:193], v[126:129]
	v_mfma_f32_16x16x32_bf16 v[62:65], v[138:141], v[186:189], v[62:65]
	v_mfma_f32_16x16x32_bf16 v[62:65], v[150:153], v[190:193], v[62:65]
	v_mfma_f32_16x16x32_bf16 v[118:121], v[130:133], v[194:197], v[118:121]
	v_mfma_f32_16x16x32_bf16 v[118:121], v[134:137], v[198:201], v[118:121]
	v_mfma_f32_16x16x32_bf16 v[54:57], v[138:141], v[194:197], v[54:57]
	v_mfma_f32_16x16x32_bf16 v[54:57], v[150:153], v[198:201], v[54:57]
	v_mfma_f32_16x16x32_bf16 v[110:113], v[130:133], v[202:205], v[110:113]
	v_mfma_f32_16x16x32_bf16 v[110:113], v[134:137], v[216:219], v[110:113]
	v_mfma_f32_16x16x32_bf16 v[46:49], v[138:141], v[202:205], v[46:49]
	v_mfma_f32_16x16x32_bf16 v[46:49], v[150:153], v[216:219], v[46:49]
	v_mfma_f32_16x16x32_bf16 v[102:105], v[130:133], v[220:223], v[102:105]
	v_mfma_f32_16x16x32_bf16 v[102:105], v[134:137], v[224:227], v[102:105]
	v_mfma_f32_16x16x32_bf16 v[38:41], v[138:141], v[220:223], v[38:41]
	v_mfma_f32_16x16x32_bf16 v[38:41], v[150:153], v[224:227], v[38:41]
	s_setprio 0
	s_setprio 1
	v_mfma_f32_16x16x32_bf16 v[122:125], v[154:157], v[186:189], v[122:125]
	v_mfma_f32_16x16x32_bf16 v[122:125], v[168:171], v[190:193], v[122:125]
	v_mfma_f32_16x16x32_bf16 v[58:61], v[178:181], v[186:189], v[58:61]
	v_mfma_f32_16x16x32_bf16 v[58:61], v[182:185], v[190:193], v[58:61]
	v_mfma_f32_16x16x32_bf16 v[114:117], v[154:157], v[194:197], v[114:117]
	v_mfma_f32_16x16x32_bf16 v[114:117], v[168:171], v[198:201], v[114:117]
	v_mfma_f32_16x16x32_bf16 v[50:53], v[178:181], v[194:197], v[50:53]
	v_mfma_f32_16x16x32_bf16 v[50:53], v[182:185], v[198:201], v[50:53]
	v_mfma_f32_16x16x32_bf16 v[106:109], v[154:157], v[202:205], v[106:109]
	v_mfma_f32_16x16x32_bf16 v[106:109], v[168:171], v[216:219], v[106:109]
	v_mfma_f32_16x16x32_bf16 v[42:45], v[178:181], v[202:205], v[42:45]
	v_mfma_f32_16x16x32_bf16 v[42:45], v[182:185], v[216:219], v[42:45]
	v_mfma_f32_16x16x32_bf16 v[98:101], v[154:157], v[220:223], v[98:101]
	v_mfma_f32_16x16x32_bf16 v[98:101], v[168:171], v[224:227], v[98:101]
	v_mfma_f32_16x16x32_bf16 v[34:37], v[178:181], v[220:223], v[34:37]
	v_mfma_f32_16x16x32_bf16 v[34:37], v[182:185], v[224:227], v[34:37]
	s_setprio 0
	s_barrier
	s_mov_b32 m0, s16
	v_lshl_add_u64 v[172:173], v[172:173], 0, s[56:57]
	ds_read_b128 v[186:189], v176 offset:49152
	ds_read_b128 v[190:193], v176 offset:50176
	ds_read_b128 v[194:197], v176 offset:51200
	ds_read_b128 v[198:201], v176 offset:52224
	ds_read_b128 v[202:205], v176 offset:53248
	ds_read_b128 v[216:219], v176 offset:54272
	ds_read_b128 v[220:223], v176 offset:55296
	ds_read_b128 v[224:227], v176 offset:56320
	global_load_lds_dwordx4 v[172:173], off
	v_lshl_add_u64 v[172:173], v[206:207], 0, s[56:57]
	s_mov_b32 m0, s11
	s_nop 0
	global_load_lds_dwordx4 v[172:173], off
	v_lshl_add_u64 v[172:173], s[64:65], 0, v[158:159]
	s_mov_b32 m0, s29
	s_nop 0
	global_load_lds_dwordx4 v[172:173], off
	v_lshl_add_u64 v[172:173], s[64:65], 0, v[146:147]
	s_mov_b32 m0, s28
	s_nop 0
	global_load_lds_dwordx4 v[172:173], off
	v_lshl_add_u64 v[172:173], v[228:229], 0, s[56:57]
	s_mov_b32 m0, s75
	s_nop 0
	global_load_lds_dwordx4 v[172:173], off
	v_lshl_add_u64 v[172:173], v[230:231], 0, s[56:57]
	s_mov_b32 m0, s92
	s_nop 0
	global_load_lds_dwordx4 v[172:173], off
	s_waitcnt vmcnt(8)
	s_waitcnt lgkmcnt(0)
	s_barrier
	s_setprio 1
	s_waitcnt lgkmcnt(0)
	v_mfma_f32_16x16x32_bf16 v[94:97], v[130:133], v[186:189], v[94:97]
	v_mfma_f32_16x16x32_bf16 v[94:97], v[134:137], v[190:193], v[94:97]
	v_mfma_f32_16x16x32_bf16 v[30:33], v[138:141], v[186:189], v[30:33]
	v_mfma_f32_16x16x32_bf16 v[30:33], v[150:153], v[190:193], v[30:33]
	v_mfma_f32_16x16x32_bf16 v[86:89], v[130:133], v[194:197], v[86:89]
	v_mfma_f32_16x16x32_bf16 v[86:89], v[134:137], v[198:201], v[86:89]
	v_mfma_f32_16x16x32_bf16 v[22:25], v[138:141], v[194:197], v[22:25]
	v_mfma_f32_16x16x32_bf16 v[22:25], v[150:153], v[198:201], v[22:25]
	v_mfma_f32_16x16x32_bf16 v[78:81], v[130:133], v[202:205], v[78:81]
	v_mfma_f32_16x16x32_bf16 v[78:81], v[134:137], v[216:219], v[78:81]
	v_mfma_f32_16x16x32_bf16 v[14:17], v[138:141], v[202:205], v[14:17]
	v_mfma_f32_16x16x32_bf16 v[14:17], v[150:153], v[216:219], v[14:17]
	v_mfma_f32_16x16x32_bf16 v[70:73], v[130:133], v[220:223], v[70:73]
	v_mfma_f32_16x16x32_bf16 v[70:73], v[134:137], v[224:227], v[70:73]
	v_mfma_f32_16x16x32_bf16 v[6:9], v[138:141], v[220:223], v[6:9]
	v_mfma_f32_16x16x32_bf16 v[6:9], v[150:153], v[224:227], v[6:9]
	s_setprio 0
	s_setprio 1
	v_mfma_f32_16x16x32_bf16 v[90:93], v[154:157], v[186:189], v[90:93]
	v_mfma_f32_16x16x32_bf16 v[90:93], v[168:171], v[190:193], v[90:93]
	v_mfma_f32_16x16x32_bf16 v[26:29], v[178:181], v[186:189], v[26:29]
	v_mfma_f32_16x16x32_bf16 v[26:29], v[182:185], v[190:193], v[26:29]
	v_mfma_f32_16x16x32_bf16 v[82:85], v[154:157], v[194:197], v[82:85]
	v_mfma_f32_16x16x32_bf16 v[82:85], v[168:171], v[198:201], v[82:85]
	v_mfma_f32_16x16x32_bf16 v[18:21], v[178:181], v[194:197], v[18:21]
	v_mfma_f32_16x16x32_bf16 v[18:21], v[182:185], v[198:201], v[18:21]
	v_mfma_f32_16x16x32_bf16 v[74:77], v[154:157], v[202:205], v[74:77]
	v_mfma_f32_16x16x32_bf16 v[74:77], v[168:171], v[216:219], v[74:77]
	v_mfma_f32_16x16x32_bf16 v[10:13], v[178:181], v[202:205], v[10:13]
	v_mfma_f32_16x16x32_bf16 v[10:13], v[182:185], v[216:219], v[10:13]
	v_mfma_f32_16x16x32_bf16 v[66:69], v[154:157], v[220:223], v[66:69]
	v_mfma_f32_16x16x32_bf16 v[66:69], v[168:171], v[224:227], v[66:69]
	v_mfma_f32_16x16x32_bf16 v[2:5], v[178:181], v[220:223], v[2:5]
	v_mfma_f32_16x16x32_bf16 v[2:5], v[182:185], v[224:227], v[2:5]
	s_setprio 0
	s_barrier
	s_movk_i32 s11, 0x100
	s_andn2_b64 vcc, exec, s[40:41]
	s_mov_b64 s[64:65], -1
	s_mov_b64 s[40:41], 0
	s_cbranch_vccz .LBB0_1186
	v_readlane_b32 s0, v241, 17
	v_readlane_b32 s1, v241, 18
	s_and_b64 vcc, exec, s[0:1]
	s_cbranch_vccz .LBB0_1189
	s_barrier

.Lsp_LBB01607_plp1607:
	s_add_u32 s14, s64, 0xfff80080
	s_addc_u32 s15, s65, -1
	s_add_i32 s26, 0, 0x10000
	s_cmp_eq_u32 s25, 28
	s_cselect_b32 s67, s23, s15
	s_cselect_b32 s66, s22, s14
	v_add_u32_e32 v147, s26, v144
	s_cselect_b32 s15, s1, s24
	s_cselect_b32 s14, s10, s11
	s_add_i32 s28, 0, 0x14000
	ds_read_b128 v[140:143], v147
	ds_read_b128 v[148:151], v147 offset:1024
	ds_read_b128 v[152:155], v147 offset:2048
	ds_read_b128 v[168:171], v147 offset:3072
	v_add_u32_e32 v147, s28, v144
	ds_read_b128 v[172:175], v147
	ds_read_b128 v[176:179], v147 offset:1024
	ds_read_b128 v[180:183], v147 offset:2048
	ds_read_b128 v[184:187], v147 offset:3072
	v_lshl_add_u64 v[156:157], s[64:65], 0, v[136:137]
	s_add_i32 m0, s13, 0xc000
	ds_read_b128 v[188:191], v146
	ds_read_b128 v[192:195], v146 offset:1024
	ds_read_b128 v[196:199], v146 offset:2048
	ds_read_b128 v[200:203], v146 offset:3072
	ds_read_b128 v[204:207], v146 offset:4096
	ds_read_b128 v[216:219], v146 offset:5120
	ds_read_b128 v[220:223], v146 offset:6144
	ds_read_b128 v[224:227], v146 offset:7168
	global_load_lds_dwordx4 v[156:157], off
	v_lshl_add_u64 v[156:157], s[64:65], 0, v[138:139]
	s_add_i32 m0, s13, 0xe000
	s_nop 0
	global_load_lds_dwordx4 v[156:157], off
	s_waitcnt vmcnt(8)
	s_waitcnt lgkmcnt(0)
	s_barrier
	s_waitcnt lgkmcnt(0)
	v_mfma_f32_16x16x32_bf16 v[126:129], v[140:143], v[188:191], 0
	v_mfma_f32_16x16x32_bf16 v[126:129], v[148:151], v[192:195], v[126:129]
	v_mfma_f32_16x16x32_bf16 v[122:125], v[152:155], v[188:191], 0
	v_mfma_f32_16x16x32_bf16 v[122:125], v[168:171], v[192:195], v[122:125]
	v_mfma_f32_16x16x32_bf16 v[110:113], v[140:143], v[196:199], 0
	v_mfma_f32_16x16x32_bf16 v[110:113], v[148:151], v[200:203], v[110:113]
	v_mfma_f32_16x16x32_bf16 v[106:109], v[152:155], v[196:199], 0
	v_mfma_f32_16x16x32_bf16 v[106:109], v[168:171], v[200:203], v[106:109]
	v_mfma_f32_16x16x32_bf16 v[94:97], v[140:143], v[204:207], 0
	v_mfma_f32_16x16x32_bf16 v[94:97], v[148:151], v[216:219], v[94:97]
	v_mfma_f32_16x16x32_bf16 v[90:93], v[152:155], v[204:207], 0
	v_mfma_f32_16x16x32_bf16 v[90:93], v[168:171], v[216:219], v[90:93]
	v_mfma_f32_16x16x32_bf16 v[78:81], v[140:143], v[220:223], 0
	v_mfma_f32_16x16x32_bf16 v[78:81], v[148:151], v[224:227], v[78:81]
	v_mfma_f32_16x16x32_bf16 v[74:77], v[152:155], v[220:223], 0
	v_mfma_f32_16x16x32_bf16 v[74:77], v[168:171], v[224:227], v[74:77]
	v_mfma_f32_16x16x32_bf16 v[118:121], v[172:175], v[188:191], 0
	v_mfma_f32_16x16x32_bf16 v[118:121], v[176:179], v[192:195], v[118:121]
	v_mfma_f32_16x16x32_bf16 v[114:117], v[180:183], v[188:191], 0
	v_mfma_f32_16x16x32_bf16 v[114:117], v[184:187], v[192:195], v[114:117]
	v_mfma_f32_16x16x32_bf16 v[102:105], v[172:175], v[196:199], 0
	v_mfma_f32_16x16x32_bf16 v[102:105], v[176:179], v[200:203], v[102:105]
	v_mfma_f32_16x16x32_bf16 v[98:101], v[180:183], v[196:199], 0
	v_mfma_f32_16x16x32_bf16 v[98:101], v[184:187], v[200:203], v[98:101]
	v_mfma_f32_16x16x32_bf16 v[86:89], v[172:175], v[204:207], 0
	v_mfma_f32_16x16x32_bf16 v[86:89], v[176:179], v[216:219], v[86:89]
	v_mfma_f32_16x16x32_bf16 v[82:85], v[180:183], v[204:207], 0
	v_mfma_f32_16x16x32_bf16 v[82:85], v[184:187], v[216:219], v[82:85]
	v_mfma_f32_16x16x32_bf16 v[70:73], v[172:175], v[220:223], 0
	v_mfma_f32_16x16x32_bf16 v[70:73], v[176:179], v[224:227], v[70:73]
	v_mfma_f32_16x16x32_bf16 v[66:69], v[180:183], v[220:223], 0
	v_mfma_f32_16x16x32_bf16 v[66:69], v[184:187], v[224:227], v[66:69]
	s_barrier
	s_add_i32 s26, s26, s17
	v_lshl_add_u64 v[156:157], s[14:15], 0, v[158:159]
	s_mov_b32 m0, s26
	ds_read_b128 v[188:191], v146 offset:16384
	ds_read_b128 v[192:195], v146 offset:17408
	ds_read_b128 v[196:199], v146 offset:18432
	ds_read_b128 v[200:203], v146 offset:19456
	ds_read_b128 v[204:207], v146 offset:20480
	ds_read_b128 v[216:219], v146 offset:21504
	ds_read_b128 v[220:223], v146 offset:22528
	ds_read_b128 v[224:227], v146 offset:23552
	global_load_lds_dwordx4 v[156:157], off
	s_add_i32 m0, s26, 0x2000
	s_add_u32 s26, s14, 0x80000
	v_lshl_add_u64 v[228:229], s[14:15], 0, v[134:135]
	s_addc_u32 s27, s15, 0
	s_add_i32 s28, s28, s17
	global_load_lds_dwordx4 v[228:229], off
	v_lshl_add_u64 v[230:231], s[26:27], 0, v[158:159]
	s_mov_b32 m0, s28
	v_lshl_add_u64 v[232:233], s[66:67], 0, v[132:133]
	global_load_lds_dwordx4 v[230:231], off
	v_lshl_add_u64 v[230:231], s[26:27], 0, v[134:135]
	s_add_i32 m0, s28, 0x2000
	s_nop 0
	global_load_lds_dwordx4 v[230:231], off
	v_lshl_add_u64 v[230:231], s[66:67], 0, v[130:131]
	s_mov_b32 m0, s13
	s_nop 0
	global_load_lds_dwordx4 v[230:231], off
	s_mov_b32 m0, s53
	s_nop 0
	global_load_lds_dwordx4 v[232:233], off
	s_waitcnt vmcnt(8)
	s_waitcnt lgkmcnt(0)
	s_barrier
	s_nop 0
	s_waitcnt lgkmcnt(0)
	v_mfma_f32_16x16x32_bf16 v[62:65], v[140:143], v[188:191], 0
	v_mfma_f32_16x16x32_bf16 v[62:65], v[148:151], v[192:195], v[62:65]
	v_mfma_f32_16x16x32_bf16 v[58:61], v[152:155], v[188:191], 0
	v_mfma_f32_16x16x32_bf16 v[58:61], v[168:171], v[192:195], v[58:61]
	v_mfma_f32_16x16x32_bf16 v[46:49], v[140:143], v[196:199], 0
	v_mfma_f32_16x16x32_bf16 v[46:49], v[148:151], v[200:203], v[46:49]
	v_mfma_f32_16x16x32_bf16 v[42:45], v[152:155], v[196:199], 0
	v_mfma_f32_16x16x32_bf16 v[42:45], v[168:171], v[200:203], v[42:45]
	v_mfma_f32_16x16x32_bf16 v[30:33], v[140:143], v[204:207], 0
	v_mfma_f32_16x16x32_bf16 v[30:33], v[148:151], v[216:219], v[30:33]
	v_mfma_f32_16x16x32_bf16 v[26:29], v[152:155], v[204:207], 0
	v_mfma_f32_16x16x32_bf16 v[26:29], v[168:171], v[216:219], v[26:29]
	v_mfma_f32_16x16x32_bf16 v[14:17], v[140:143], v[220:223], 0
	v_mfma_f32_16x16x32_bf16 v[14:17], v[148:151], v[224:227], v[14:17]
	v_mfma_f32_16x16x32_bf16 v[10:13], v[152:155], v[220:223], 0
	v_mfma_f32_16x16x32_bf16 v[10:13], v[168:171], v[224:227], v[10:13]
	v_mfma_f32_16x16x32_bf16 v[54:57], v[172:175], v[188:191], 0
	v_mfma_f32_16x16x32_bf16 v[54:57], v[176:179], v[192:195], v[54:57]
	v_mfma_f32_16x16x32_bf16 v[50:53], v[180:183], v[188:191], 0
	v_mfma_f32_16x16x32_bf16 v[50:53], v[184:187], v[192:195], v[50:53]
	v_mfma_f32_16x16x32_bf16 v[38:41], v[172:175], v[196:199], 0
	v_mfma_f32_16x16x32_bf16 v[38:41], v[176:179], v[200:203], v[38:41]
	v_mfma_f32_16x16x32_bf16 v[34:37], v[180:183], v[196:199], 0
	v_mfma_f32_16x16x32_bf16 v[34:37], v[184:187], v[200:203], v[34:37]
	v_mfma_f32_16x16x32_bf16 v[22:25], v[172:175], v[204:207], 0
	v_mfma_f32_16x16x32_bf16 v[22:25], v[176:179], v[216:219], v[22:25]
	v_mfma_f32_16x16x32_bf16 v[18:21], v[180:183], v[204:207], 0
	v_mfma_f32_16x16x32_bf16 v[18:21], v[184:187], v[216:219], v[18:21]
	v_mfma_f32_16x16x32_bf16 v[6:9], v[172:175], v[220:223], 0
	v_mfma_f32_16x16x32_bf16 v[6:9], v[176:179], v[224:227], v[6:9]
	v_mfma_f32_16x16x32_bf16 v[2:5], v[180:183], v[220:223], 0
	v_mfma_f32_16x16x32_bf16 v[2:5], v[184:187], v[224:227], v[2:5]
	s_barrier
	s_add_i32 s28, 0, 0x18000
	v_add_u32_e32 v147, s28, v144
	s_add_i32 s29, 0, 0x1c000
	ds_read_b128 v[140:143], v147
	ds_read_b128 v[148:151], v147 offset:1024
	ds_read_b128 v[152:155], v147 offset:2048
	ds_read_b128 v[168:171], v147 offset:3072
	v_add_u32_e32 v147, s29, v144
	ds_read_b128 v[172:175], v147
	ds_read_b128 v[176:179], v147 offset:1024
	ds_read_b128 v[180:183], v147 offset:2048
	ds_read_b128 v[184:187], v147 offset:3072
	s_add_u32 s26, s66, 0x80000
	s_addc_u32 s27, s67, 0
	s_mov_b32 m0, s58
	v_lshl_add_u64 v[234:235], s[26:27], 0, v[130:131]
	ds_read_b128 v[188:191], v146 offset:32768
	ds_read_b128 v[192:195], v146 offset:33792
	ds_read_b128 v[196:199], v146 offset:34816
	ds_read_b128 v[200:203], v146 offset:35840
	ds_read_b128 v[204:207], v146 offset:36864
	ds_read_b128 v[216:219], v146 offset:37888
	ds_read_b128 v[220:223], v146 offset:38912
	ds_read_b128 v[224:227], v146 offset:39936
	global_load_lds_dwordx4 v[234:235], off
	v_lshl_add_u64 v[234:235], s[26:27], 0, v[132:133]
	s_mov_b32 m0, s59
	s_nop 0
	global_load_lds_dwordx4 v[234:235], off
	s_waitcnt vmcnt(8)
	s_waitcnt lgkmcnt(0)
	s_barrier
	s_nop 0
	s_waitcnt lgkmcnt(0)
	v_mfma_f32_16x16x32_bf16 v[126:129], v[140:143], v[188:191], v[126:129]
	v_mfma_f32_16x16x32_bf16 v[126:129], v[148:151], v[192:195], v[126:129]
	v_mfma_f32_16x16x32_bf16 v[122:125], v[152:155], v[188:191], v[122:125]
	v_mfma_f32_16x16x32_bf16 v[122:125], v[168:171], v[192:195], v[122:125]
	v_mfma_f32_16x16x32_bf16 v[110:113], v[140:143], v[196:199], v[110:113]
	v_mfma_f32_16x16x32_bf16 v[110:113], v[148:151], v[200:203], v[110:113]
	v_mfma_f32_16x16x32_bf16 v[106:109], v[152:155], v[196:199], v[106:109]
	v_mfma_f32_16x16x32_bf16 v[106:109], v[168:171], v[200:203], v[106:109]
	v_mfma_f32_16x16x32_bf16 v[94:97], v[140:143], v[204:207], v[94:97]
	v_mfma_f32_16x16x32_bf16 v[94:97], v[148:151], v[216:219], v[94:97]
	v_mfma_f32_16x16x32_bf16 v[90:93], v[152:155], v[204:207], v[90:93]
	v_mfma_f32_16x16x32_bf16 v[90:93], v[168:171], v[216:219], v[90:93]
	v_mfma_f32_16x16x32_bf16 v[78:81], v[140:143], v[220:223], v[78:81]
	v_mfma_f32_16x16x32_bf16 v[78:81], v[148:151], v[224:227], v[78:81]
	v_mfma_f32_16x16x32_bf16 v[74:77], v[152:155], v[220:223], v[74:77]
	v_mfma_f32_16x16x32_bf16 v[74:77], v[168:171], v[224:227], v[74:77]
	v_mfma_f32_16x16x32_bf16 v[118:121], v[172:175], v[188:191], v[118:121]
	v_mfma_f32_16x16x32_bf16 v[118:121], v[176:179], v[192:195], v[118:121]
	v_mfma_f32_16x16x32_bf16 v[114:117], v[180:183], v[188:191], v[114:117]
	v_mfma_f32_16x16x32_bf16 v[114:117], v[184:187], v[192:195], v[114:117]
	v_mfma_f32_16x16x32_bf16 v[102:105], v[172:175], v[196:199], v[102:105]
	v_mfma_f32_16x16x32_bf16 v[102:105], v[176:179], v[200:203], v[102:105]
	v_mfma_f32_16x16x32_bf16 v[98:101], v[180:183], v[196:199], v[98:101]
	v_mfma_f32_16x16x32_bf16 v[98:101], v[184:187], v[200:203], v[98:101]
	v_mfma_f32_16x16x32_bf16 v[86:89], v[172:175], v[204:207], v[86:89]
	v_mfma_f32_16x16x32_bf16 v[86:89], v[176:179], v[216:219], v[86:89]
	v_mfma_f32_16x16x32_bf16 v[82:85], v[180:183], v[204:207], v[82:85]
	v_mfma_f32_16x16x32_bf16 v[82:85], v[184:187], v[216:219], v[82:85]
	v_mfma_f32_16x16x32_bf16 v[70:73], v[172:175], v[220:223], v[70:73]
	v_mfma_f32_16x16x32_bf16 v[70:73], v[176:179], v[224:227], v[70:73]
	v_mfma_f32_16x16x32_bf16 v[66:69], v[180:183], v[220:223], v[66:69]
	v_mfma_f32_16x16x32_bf16 v[66:69], v[184:187], v[224:227], v[66:69]
	s_barrier
	s_add_i32 s26, s28, s17
	v_lshl_add_u64 v[156:157], v[156:157], 0, s[56:57]
	s_mov_b32 m0, s26
	ds_read_b128 v[188:191], v146 offset:49152
	ds_read_b128 v[192:195], v146 offset:50176
	ds_read_b128 v[196:199], v146 offset:51200
	ds_read_b128 v[200:203], v146 offset:52224
	ds_read_b128 v[204:207], v146 offset:53248
	ds_read_b128 v[216:219], v146 offset:54272
	ds_read_b128 v[220:223], v146 offset:55296
	ds_read_b128 v[224:227], v146 offset:56320
	global_load_lds_dwordx4 v[156:157], off
	s_add_i32 m0, s26, 0x2000
	s_add_u32 s14, s14, 0x80080
	v_lshl_add_u64 v[156:157], v[228:229], 0, s[56:57]
	s_addc_u32 s15, s15, 0
	s_add_i32 s26, s29, s17
	global_load_lds_dwordx4 v[156:157], off
	v_lshl_add_u64 v[156:157], s[14:15], 0, v[158:159]
	s_mov_b32 m0, s26
	s_nop 0
	global_load_lds_dwordx4 v[156:157], off
	v_lshl_add_u64 v[156:157], s[14:15], 0, v[134:135]
	s_add_i32 m0, s26, 0x2000
	s_nop 0
	global_load_lds_dwordx4 v[156:157], off
	v_lshl_add_u64 v[156:157], v[230:231], 0, s[56:57]
	s_mov_b32 m0, s54
	s_nop 0
	global_load_lds_dwordx4 v[156:157], off
	v_lshl_add_u64 v[156:157], v[232:233], 0, s[56:57]
	s_mov_b32 m0, s68
	s_nop 0
	global_load_lds_dwordx4 v[156:157], off
	s_waitcnt vmcnt(8)
	s_waitcnt lgkmcnt(0)
	s_barrier
	s_waitcnt lgkmcnt(0)
	v_mfma_f32_16x16x32_bf16 v[62:65], v[140:143], v[188:191], v[62:65]
	v_mfma_f32_16x16x32_bf16 v[62:65], v[148:151], v[192:195], v[62:65]
	v_mfma_f32_16x16x32_bf16 v[58:61], v[152:155], v[188:191], v[58:61]
	v_mfma_f32_16x16x32_bf16 v[58:61], v[168:171], v[192:195], v[58:61]
	v_mfma_f32_16x16x32_bf16 v[46:49], v[140:143], v[196:199], v[46:49]
	v_mfma_f32_16x16x32_bf16 v[46:49], v[148:151], v[200:203], v[46:49]
	v_mfma_f32_16x16x32_bf16 v[42:45], v[152:155], v[196:199], v[42:45]
	v_mfma_f32_16x16x32_bf16 v[42:45], v[168:171], v[200:203], v[42:45]
	v_mfma_f32_16x16x32_bf16 v[30:33], v[140:143], v[204:207], v[30:33]
	v_mfma_f32_16x16x32_bf16 v[30:33], v[148:151], v[216:219], v[30:33]
	v_mfma_f32_16x16x32_bf16 v[26:29], v[152:155], v[204:207], v[26:29]
	v_mfma_f32_16x16x32_bf16 v[26:29], v[168:171], v[216:219], v[26:29]
	v_mfma_f32_16x16x32_bf16 v[14:17], v[140:143], v[220:223], v[14:17]
	v_mfma_f32_16x16x32_bf16 v[14:17], v[148:151], v[224:227], v[14:17]
	v_mfma_f32_16x16x32_bf16 v[10:13], v[152:155], v[220:223], v[10:13]
	v_mfma_f32_16x16x32_bf16 v[10:13], v[168:171], v[224:227], v[10:13]
	v_mfma_f32_16x16x32_bf16 v[54:57], v[172:175], v[188:191], v[54:57]
	v_mfma_f32_16x16x32_bf16 v[54:57], v[176:179], v[192:195], v[54:57]
	v_mfma_f32_16x16x32_bf16 v[50:53], v[180:183], v[188:191], v[50:53]
	v_mfma_f32_16x16x32_bf16 v[50:53], v[184:187], v[192:195], v[50:53]
	v_mfma_f32_16x16x32_bf16 v[38:41], v[172:175], v[196:199], v[38:41]
	v_mfma_f32_16x16x32_bf16 v[38:41], v[176:179], v[200:203], v[38:41]
	v_mfma_f32_16x16x32_bf16 v[34:37], v[180:183], v[196:199], v[34:37]
	v_mfma_f32_16x16x32_bf16 v[34:37], v[184:187], v[200:203], v[34:37]
	v_mfma_f32_16x16x32_bf16 v[22:25], v[172:175], v[204:207], v[22:25]
	v_mfma_f32_16x16x32_bf16 v[22:25], v[176:179], v[216:219], v[22:25]
	v_mfma_f32_16x16x32_bf16 v[18:21], v[180:183], v[204:207], v[18:21]
	v_mfma_f32_16x16x32_bf16 v[18:21], v[184:187], v[216:219], v[18:21]
	v_mfma_f32_16x16x32_bf16 v[6:9], v[172:175], v[220:223], v[6:9]
	v_mfma_f32_16x16x32_bf16 v[6:9], v[176:179], v[224:227], v[6:9]
	v_mfma_f32_16x16x32_bf16 v[2:5], v[180:183], v[220:223], v[2:5]
	v_mfma_f32_16x16x32_bf16 v[2:5], v[184:187], v[224:227], v[2:5]
	s_barrier
	s_add_i32 s25, s25, 2
	s_add_u32 s64, s64, 0x100
	s_addc_u32 s65, s65, 0
	s_add_u32 s11, s11, 0x100
	s_addc_u32 s24, s24, 0
	s_cmp_gt_u32 s25, 29

.Lsp_LBB01607:
	s_add_u32 s14, s64, 0xfff80080
	s_addc_u32 s15, s65, -1
	s_add_i32 s26, 0, 0x10000
	s_cmp_eq_u32 s25, 28
	s_cselect_b32 s67, s23, s15
	s_cselect_b32 s66, s22, s14
	v_add_u32_e32 v147, s26, v144
	s_cselect_b32 s15, s1, s24
	s_cselect_b32 s14, s10, s11
	s_add_i32 s28, 0, 0x14000
	ds_read_b128 v[140:143], v147
	ds_read_b128 v[148:151], v147 offset:1024
	ds_read_b128 v[152:155], v147 offset:2048
	ds_read_b128 v[168:171], v147 offset:3072
	v_add_u32_e32 v147, s28, v144
	ds_read_b128 v[172:175], v147
	ds_read_b128 v[176:179], v147 offset:1024
	ds_read_b128 v[180:183], v147 offset:2048
	ds_read_b128 v[184:187], v147 offset:3072
	v_lshl_add_u64 v[156:157], s[64:65], 0, v[136:137]
	s_add_i32 m0, s13, 0xc000
	ds_read_b128 v[188:191], v146
	ds_read_b128 v[192:195], v146 offset:1024
	ds_read_b128 v[196:199], v146 offset:2048
	ds_read_b128 v[200:203], v146 offset:3072
	ds_read_b128 v[204:207], v146 offset:4096
	ds_read_b128 v[216:219], v146 offset:5120
	ds_read_b128 v[220:223], v146 offset:6144
	ds_read_b128 v[224:227], v146 offset:7168
	global_load_lds_dwordx4 v[156:157], off
	v_lshl_add_u64 v[156:157], s[64:65], 0, v[138:139]
	s_add_i32 m0, s13, 0xe000
	s_nop 0
	global_load_lds_dwordx4 v[156:157], off
	s_waitcnt vmcnt(8)
	s_waitcnt lgkmcnt(0)
	s_barrier
	s_nop 0
	s_waitcnt lgkmcnt(0)
	v_mfma_f32_16x16x32_bf16 v[126:129], v[140:143], v[188:191], v[126:129]
	v_mfma_f32_16x16x32_bf16 v[126:129], v[148:151], v[192:195], v[126:129]
	v_mfma_f32_16x16x32_bf16 v[122:125], v[152:155], v[188:191], v[122:125]
	v_mfma_f32_16x16x32_bf16 v[122:125], v[168:171], v[192:195], v[122:125]
	v_mfma_f32_16x16x32_bf16 v[110:113], v[140:143], v[196:199], v[110:113]
	v_mfma_f32_16x16x32_bf16 v[110:113], v[148:151], v[200:203], v[110:113]
	v_mfma_f32_16x16x32_bf16 v[106:109], v[152:155], v[196:199], v[106:109]
	v_mfma_f32_16x16x32_bf16 v[106:109], v[168:171], v[200:203], v[106:109]
	v_mfma_f32_16x16x32_bf16 v[94:97], v[140:143], v[204:207], v[94:97]
	v_mfma_f32_16x16x32_bf16 v[94:97], v[148:151], v[216:219], v[94:97]
	v_mfma_f32_16x16x32_bf16 v[90:93], v[152:155], v[204:207], v[90:93]
	v_mfma_f32_16x16x32_bf16 v[90:93], v[168:171], v[216:219], v[90:93]
	v_mfma_f32_16x16x32_bf16 v[78:81], v[140:143], v[220:223], v[78:81]
	v_mfma_f32_16x16x32_bf16 v[78:81], v[148:151], v[224:227], v[78:81]
	v_mfma_f32_16x16x32_bf16 v[74:77], v[152:155], v[220:223], v[74:77]
	v_mfma_f32_16x16x32_bf16 v[74:77], v[168:171], v[224:227], v[74:77]
	v_mfma_f32_16x16x32_bf16 v[118:121], v[172:175], v[188:191], v[118:121]
	v_mfma_f32_16x16x32_bf16 v[118:121], v[176:179], v[192:195], v[118:121]
	v_mfma_f32_16x16x32_bf16 v[114:117], v[180:183], v[188:191], v[114:117]
	v_mfma_f32_16x16x32_bf16 v[114:117], v[184:187], v[192:195], v[114:117]
	v_mfma_f32_16x16x32_bf16 v[102:105], v[172:175], v[196:199], v[102:105]
	v_mfma_f32_16x16x32_bf16 v[102:105], v[176:179], v[200:203], v[102:105]
	v_mfma_f32_16x16x32_bf16 v[98:101], v[180:183], v[196:199], v[98:101]
	v_mfma_f32_16x16x32_bf16 v[98:101], v[184:187], v[200:203], v[98:101]
	v_mfma_f32_16x16x32_bf16 v[86:89], v[172:175], v[204:207], v[86:89]
	v_mfma_f32_16x16x32_bf16 v[86:89], v[176:179], v[216:219], v[86:89]
	v_mfma_f32_16x16x32_bf16 v[82:85], v[180:183], v[204:207], v[82:85]
	v_mfma_f32_16x16x32_bf16 v[82:85], v[184:187], v[216:219], v[82:85]
	v_mfma_f32_16x16x32_bf16 v[70:73], v[172:175], v[220:223], v[70:73]
	v_mfma_f32_16x16x32_bf16 v[70:73], v[176:179], v[224:227], v[70:73]
	v_mfma_f32_16x16x32_bf16 v[66:69], v[180:183], v[220:223], v[66:69]
	v_mfma_f32_16x16x32_bf16 v[66:69], v[184:187], v[224:227], v[66:69]
	s_barrier
	s_add_i32 s26, s26, s17
	v_lshl_add_u64 v[156:157], s[14:15], 0, v[158:159]
	s_mov_b32 m0, s26
	ds_read_b128 v[188:191], v146 offset:16384
	ds_read_b128 v[192:195], v146 offset:17408
	ds_read_b128 v[196:199], v146 offset:18432
	ds_read_b128 v[200:203], v146 offset:19456
	ds_read_b128 v[204:207], v146 offset:20480
	ds_read_b128 v[216:219], v146 offset:21504
	ds_read_b128 v[220:223], v146 offset:22528
	ds_read_b128 v[224:227], v146 offset:23552
	global_load_lds_dwordx4 v[156:157], off
	s_add_i32 m0, s26, 0x2000
	s_add_u32 s26, s14, 0x80000
	v_lshl_add_u64 v[228:229], s[14:15], 0, v[134:135]
	s_addc_u32 s27, s15, 0
	s_add_i32 s28, s28, s17
	global_load_lds_dwordx4 v[228:229], off
	v_lshl_add_u64 v[230:231], s[26:27], 0, v[158:159]
	s_mov_b32 m0, s28
	v_lshl_add_u64 v[232:233], s[66:67], 0, v[132:133]
	global_load_lds_dwordx4 v[230:231], off
	v_lshl_add_u64 v[230:231], s[26:27], 0, v[134:135]
	s_add_i32 m0, s28, 0x2000
	s_nop 0
	global_load_lds_dwordx4 v[230:231], off
	v_lshl_add_u64 v[230:231], s[66:67], 0, v[130:131]
	s_mov_b32 m0, s13
	s_nop 0
	global_load_lds_dwordx4 v[230:231], off
	s_mov_b32 m0, s53
	s_nop 0
	global_load_lds_dwordx4 v[232:233], off
	s_waitcnt vmcnt(8)
	s_waitcnt lgkmcnt(0)
	s_barrier
	s_nop 0
	s_waitcnt lgkmcnt(0)
	v_mfma_f32_16x16x32_bf16 v[62:65], v[140:143], v[188:191], v[62:65]
	v_mfma_f32_16x16x32_bf16 v[62:65], v[148:151], v[192:195], v[62:65]
	v_mfma_f32_16x16x32_bf16 v[58:61], v[152:155], v[188:191], v[58:61]
	v_mfma_f32_16x16x32_bf16 v[58:61], v[168:171], v[192:195], v[58:61]
	v_mfma_f32_16x16x32_bf16 v[46:49], v[140:143], v[196:199], v[46:49]
	v_mfma_f32_16x16x32_bf16 v[46:49], v[148:151], v[200:203], v[46:49]
	v_mfma_f32_16x16x32_bf16 v[42:45], v[152:155], v[196:199], v[42:45]
	v_mfma_f32_16x16x32_bf16 v[42:45], v[168:171], v[200:203], v[42:45]
	v_mfma_f32_16x16x32_bf16 v[30:33], v[140:143], v[204:207], v[30:33]
	v_mfma_f32_16x16x32_bf16 v[30:33], v[148:151], v[216:219], v[30:33]
	v_mfma_f32_16x16x32_bf16 v[26:29], v[152:155], v[204:207], v[26:29]
	v_mfma_f32_16x16x32_bf16 v[26:29], v[168:171], v[216:219], v[26:29]
	v_mfma_f32_16x16x32_bf16 v[14:17], v[140:143], v[220:223], v[14:17]
	v_mfma_f32_16x16x32_bf16 v[14:17], v[148:151], v[224:227], v[14:17]
	v_mfma_f32_16x16x32_bf16 v[10:13], v[152:155], v[220:223], v[10:13]
	v_mfma_f32_16x16x32_bf16 v[10:13], v[168:171], v[224:227], v[10:13]
	v_mfma_f32_16x16x32_bf16 v[54:57], v[172:175], v[188:191], v[54:57]
	v_mfma_f32_16x16x32_bf16 v[54:57], v[176:179], v[192:195], v[54:57]
	v_mfma_f32_16x16x32_bf16 v[50:53], v[180:183], v[188:191], v[50:53]
	v_mfma_f32_16x16x32_bf16 v[50:53], v[184:187], v[192:195], v[50:53]
	v_mfma_f32_16x16x32_bf16 v[38:41], v[172:175], v[196:199], v[38:41]
	v_mfma_f32_16x16x32_bf16 v[38:41], v[176:179], v[200:203], v[38:41]
	v_mfma_f32_16x16x32_bf16 v[34:37], v[180:183], v[196:199], v[34:37]
	v_mfma_f32_16x16x32_bf16 v[34:37], v[184:187], v[200:203], v[34:37]
	v_mfma_f32_16x16x32_bf16 v[22:25], v[172:175], v[204:207], v[22:25]
	v_mfma_f32_16x16x32_bf16 v[22:25], v[176:179], v[216:219], v[22:25]
	v_mfma_f32_16x16x32_bf16 v[18:21], v[180:183], v[204:207], v[18:21]
	v_mfma_f32_16x16x32_bf16 v[18:21], v[184:187], v[216:219], v[18:21]
	v_mfma_f32_16x16x32_bf16 v[6:9], v[172:175], v[220:223], v[6:9]
	v_mfma_f32_16x16x32_bf16 v[6:9], v[176:179], v[224:227], v[6:9]
	v_mfma_f32_16x16x32_bf16 v[2:5], v[180:183], v[220:223], v[2:5]
	v_mfma_f32_16x16x32_bf16 v[2:5], v[184:187], v[224:227], v[2:5]
	s_barrier
	s_add_i32 s28, 0, 0x18000
	v_add_u32_e32 v147, s28, v144
	s_add_i32 s29, 0, 0x1c000
	ds_read_b128 v[140:143], v147
	ds_read_b128 v[148:151], v147 offset:1024
	ds_read_b128 v[152:155], v147 offset:2048
	ds_read_b128 v[168:171], v147 offset:3072
	v_add_u32_e32 v147, s29, v144
	ds_read_b128 v[172:175], v147
	ds_read_b128 v[176:179], v147 offset:1024
	ds_read_b128 v[180:183], v147 offset:2048
	ds_read_b128 v[184:187], v147 offset:3072
	s_add_u32 s26, s66, 0x80000
	s_addc_u32 s27, s67, 0
	s_mov_b32 m0, s58
	v_lshl_add_u64 v[234:235], s[26:27], 0, v[130:131]
	ds_read_b128 v[188:191], v146 offset:32768
	ds_read_b128 v[192:195], v146 offset:33792
	ds_read_b128 v[196:199], v146 offset:34816
	ds_read_b128 v[200:203], v146 offset:35840
	ds_read_b128 v[204:207], v146 offset:36864
	ds_read_b128 v[216:219], v146 offset:37888
	ds_read_b128 v[220:223], v146 offset:38912
	ds_read_b128 v[224:227], v146 offset:39936
	global_load_lds_dwordx4 v[234:235], off
	v_lshl_add_u64 v[234:235], s[26:27], 0, v[132:133]
	s_mov_b32 m0, s59
	s_nop 0
	global_load_lds_dwordx4 v[234:235], off
	s_waitcnt vmcnt(8)
	s_waitcnt lgkmcnt(0)
	s_barrier
	s_nop 0
	s_waitcnt lgkmcnt(0)
	v_mfma_f32_16x16x32_bf16 v[126:129], v[140:143], v[188:191], v[126:129]
	v_mfma_f32_16x16x32_bf16 v[126:129], v[148:151], v[192:195], v[126:129]
	v_mfma_f32_16x16x32_bf16 v[122:125], v[152:155], v[188:191], v[122:125]
	v_mfma_f32_16x16x32_bf16 v[122:125], v[168:171], v[192:195], v[122:125]
	v_mfma_f32_16x16x32_bf16 v[110:113], v[140:143], v[196:199], v[110:113]
	v_mfma_f32_16x16x32_bf16 v[110:113], v[148:151], v[200:203], v[110:113]
	v_mfma_f32_16x16x32_bf16 v[106:109], v[152:155], v[196:199], v[106:109]
	v_mfma_f32_16x16x32_bf16 v[106:109], v[168:171], v[200:203], v[106:109]
	v_mfma_f32_16x16x32_bf16 v[94:97], v[140:143], v[204:207], v[94:97]
	v_mfma_f32_16x16x32_bf16 v[94:97], v[148:151], v[216:219], v[94:97]
	v_mfma_f32_16x16x32_bf16 v[90:93], v[152:155], v[204:207], v[90:93]
	v_mfma_f32_16x16x32_bf16 v[90:93], v[168:171], v[216:219], v[90:93]
	v_mfma_f32_16x16x32_bf16 v[78:81], v[140:143], v[220:223], v[78:81]
	v_mfma_f32_16x16x32_bf16 v[78:81], v[148:151], v[224:227], v[78:81]
	v_mfma_f32_16x16x32_bf16 v[74:77], v[152:155], v[220:223], v[74:77]
	v_mfma_f32_16x16x32_bf16 v[74:77], v[168:171], v[224:227], v[74:77]
	v_mfma_f32_16x16x32_bf16 v[118:121], v[172:175], v[188:191], v[118:121]
	v_mfma_f32_16x16x32_bf16 v[118:121], v[176:179], v[192:195], v[118:121]
	v_mfma_f32_16x16x32_bf16 v[114:117], v[180:183], v[188:191], v[114:117]
	v_mfma_f32_16x16x32_bf16 v[114:117], v[184:187], v[192:195], v[114:117]
	v_mfma_f32_16x16x32_bf16 v[102:105], v[172:175], v[196:199], v[102:105]
	v_mfma_f32_16x16x32_bf16 v[102:105], v[176:179], v[200:203], v[102:105]
	v_mfma_f32_16x16x32_bf16 v[98:101], v[180:183], v[196:199], v[98:101]
	v_mfma_f32_16x16x32_bf16 v[98:101], v[184:187], v[200:203], v[98:101]
	v_mfma_f32_16x16x32_bf16 v[86:89], v[172:175], v[204:207], v[86:89]
	v_mfma_f32_16x16x32_bf16 v[86:89], v[176:179], v[216:219], v[86:89]
	v_mfma_f32_16x16x32_bf16 v[82:85], v[180:183], v[204:207], v[82:85]
	v_mfma_f32_16x16x32_bf16 v[82:85], v[184:187], v[216:219], v[82:85]
	v_mfma_f32_16x16x32_bf16 v[70:73], v[172:175], v[220:223], v[70:73]
	v_mfma_f32_16x16x32_bf16 v[70:73], v[176:179], v[224:227], v[70:73]
	v_mfma_f32_16x16x32_bf16 v[66:69], v[180:183], v[220:223], v[66:69]
	v_mfma_f32_16x16x32_bf16 v[66:69], v[184:187], v[224:227], v[66:69]
	s_barrier
	s_add_i32 s26, s28, s17
	v_lshl_add_u64 v[156:157], v[156:157], 0, s[56:57]
	s_mov_b32 m0, s26
	ds_read_b128 v[188:191], v146 offset:49152
	ds_read_b128 v[192:195], v146 offset:50176
	ds_read_b128 v[196:199], v146 offset:51200
	ds_read_b128 v[200:203], v146 offset:52224
	ds_read_b128 v[204:207], v146 offset:53248
	ds_read_b128 v[216:219], v146 offset:54272
	ds_read_b128 v[220:223], v146 offset:55296
	ds_read_b128 v[224:227], v146 offset:56320
	global_load_lds_dwordx4 v[156:157], off
	s_add_i32 m0, s26, 0x2000
	s_add_u32 s14, s14, 0x80080
	v_lshl_add_u64 v[156:157], v[228:229], 0, s[56:57]
	s_addc_u32 s15, s15, 0
	s_add_i32 s26, s29, s17
	global_load_lds_dwordx4 v[156:157], off
	v_lshl_add_u64 v[156:157], s[14:15], 0, v[158:159]
	s_mov_b32 m0, s26
	s_nop 0
	global_load_lds_dwordx4 v[156:157], off
	v_lshl_add_u64 v[156:157], s[14:15], 0, v[134:135]
	s_add_i32 m0, s26, 0x2000
	s_nop 0
	global_load_lds_dwordx4 v[156:157], off
	v_lshl_add_u64 v[156:157], v[230:231], 0, s[56:57]
	s_mov_b32 m0, s54
	s_nop 0
	global_load_lds_dwordx4 v[156:157], off
	v_lshl_add_u64 v[156:157], v[232:233], 0, s[56:57]
	s_mov_b32 m0, s68
	s_nop 0
	global_load_lds_dwordx4 v[156:157], off
	s_waitcnt vmcnt(8)
	s_waitcnt lgkmcnt(0)
	s_barrier
	s_waitcnt lgkmcnt(0)
	v_mfma_f32_16x16x32_bf16 v[62:65], v[140:143], v[188:191], v[62:65]
	v_mfma_f32_16x16x32_bf16 v[62:65], v[148:151], v[192:195], v[62:65]
	v_mfma_f32_16x16x32_bf16 v[58:61], v[152:155], v[188:191], v[58:61]
	v_mfma_f32_16x16x32_bf16 v[58:61], v[168:171], v[192:195], v[58:61]
	v_mfma_f32_16x16x32_bf16 v[46:49], v[140:143], v[196:199], v[46:49]
	v_mfma_f32_16x16x32_bf16 v[46:49], v[148:151], v[200:203], v[46:49]
	v_mfma_f32_16x16x32_bf16 v[42:45], v[152:155], v[196:199], v[42:45]
	v_mfma_f32_16x16x32_bf16 v[42:45], v[168:171], v[200:203], v[42:45]
	v_mfma_f32_16x16x32_bf16 v[30:33], v[140:143], v[204:207], v[30:33]
	v_mfma_f32_16x16x32_bf16 v[30:33], v[148:151], v[216:219], v[30:33]
	v_mfma_f32_16x16x32_bf16 v[26:29], v[152:155], v[204:207], v[26:29]
	v_mfma_f32_16x16x32_bf16 v[26:29], v[168:171], v[216:219], v[26:29]
	v_mfma_f32_16x16x32_bf16 v[14:17], v[140:143], v[220:223], v[14:17]
	v_mfma_f32_16x16x32_bf16 v[14:17], v[148:151], v[224:227], v[14:17]
	v_mfma_f32_16x16x32_bf16 v[10:13], v[152:155], v[220:223], v[10:13]
	v_mfma_f32_16x16x32_bf16 v[10:13], v[168:171], v[224:227], v[10:13]
	v_mfma_f32_16x16x32_bf16 v[54:57], v[172:175], v[188:191], v[54:57]
	v_mfma_f32_16x16x32_bf16 v[54:57], v[176:179], v[192:195], v[54:57]
	v_mfma_f32_16x16x32_bf16 v[50:53], v[180:183], v[188:191], v[50:53]
	v_mfma_f32_16x16x32_bf16 v[50:53], v[184:187], v[192:195], v[50:53]
	v_mfma_f32_16x16x32_bf16 v[38:41], v[172:175], v[196:199], v[38:41]
	v_mfma_f32_16x16x32_bf16 v[38:41], v[176:179], v[200:203], v[38:41]
	v_mfma_f32_16x16x32_bf16 v[34:37], v[180:183], v[196:199], v[34:37]
	v_mfma_f32_16x16x32_bf16 v[34:37], v[184:187], v[200:203], v[34:37]
	v_mfma_f32_16x16x32_bf16 v[22:25], v[172:175], v[204:207], v[22:25]
	v_mfma_f32_16x16x32_bf16 v[22:25], v[176:179], v[216:219], v[22:25]
	v_mfma_f32_16x16x32_bf16 v[18:21], v[180:183], v[204:207], v[18:21]
	v_mfma_f32_16x16x32_bf16 v[18:21], v[184:187], v[216:219], v[18:21]
	v_mfma_f32_16x16x32_bf16 v[6:9], v[172:175], v[220:223], v[6:9]
	v_mfma_f32_16x16x32_bf16 v[6:9], v[176:179], v[224:227], v[6:9]
	v_mfma_f32_16x16x32_bf16 v[2:5], v[180:183], v[220:223], v[2:5]
	v_mfma_f32_16x16x32_bf16 v[2:5], v[184:187], v[224:227], v[2:5]
	s_barrier
	s_add_i32 s25, s25, 2
	s_add_u32 s64, s64, 0x100
	s_addc_u32 s65, s65, 0
	s_add_u32 s11, s11, 0x100
	s_addc_u32 s24, s24, 0
	s_cmp_gt_u32 s25, 29
	s_cbranch_scc0 .LBB0_1607
	s_and_b64 vcc, exec, s[42:43]
	s_cbranch_vccz .LBB0_1610
	s_barrier
